# cross-lane reductions via v_permlane16/32_swap instead of ds_bpermute round trips (attention softmax max/sum, residual-epilogue row sums): 48 sites
# speedup vs baseline: 1.0055x; 1.0055x over previous
.LBB0_145:
	s_cmp_eq_u32 s2, 0
	v_and_b32_e32 v67, 64, v174
	s_cselect_b64 s[22:23], -1, 0
	v_xor_b32_e32 v66, 16, v174
	v_add_u32_e32 v67, 64, v67
	s_and_b64 vcc, s[0:1], s[22:23]
	v_cmp_lt_i32_e64 s[0:1], v66, v67
	v_lshl_add_u64 v[100:101], s[24:25], 1, v[96:97]
	s_mov_b32 s2, 0xff800000
	v_cndmask_b32_e64 v66, v174, v66, s[0:1]
	v_lshlrev_b32_e32 v105, 2, v66
	v_xor_b32_e32 v66, 32, v174
	v_cmp_lt_i32_e64 s[0:1], v66, v67
	s_waitcnt vmcnt(0)
	v_mul_f32_e32 v99, 0x3fb8aa3b, v135
	v_cndmask_b32_e64 v66, v174, v66, s[0:1]
	v_lshlrev_b32_e32 v103, 2, v66
	ds_read_b128 v[66:69], v127
	ds_read_b128 v[70:73], v127 offset:64
	s_waitcnt lgkmcnt(1)
	v_mfma_f32_16x16x32_bf16 v[66:69], v[66:69], v[62:65], 0
	s_xor_b64 s[0:1], vcc, -1
	s_and_b64 s[24:25], s[0:1], s[76:77]
	s_and_b64 s[26:27], s[0:1], s[78:79]
	s_waitcnt lgkmcnt(0)
	v_mfma_f32_16x16x32_bf16 v[136:139], v[70:73], v[58:61], v[66:69]
	s_nop 2
	ds_read_b128 v[66:69], v127 offset:576
	ds_read_b128 v[70:73], v127 offset:640
	s_and_b64 s[28:29], s[0:1], s[80:81]
	s_and_b64 s[30:31], s[0:1], s[82:83]
	s_waitcnt lgkmcnt(1)
	v_mfma_f32_16x16x32_bf16 v[66:69], v[66:69], v[62:65], 0
	v_cndmask_b32_e64 v107, v175, v139, s[30:31]
	s_and_b64 s[34:35], s[0:1], s[84:85]
	s_and_b64 s[36:37], s[0:1], s[86:87]
	s_waitcnt lgkmcnt(0)
	v_mfma_f32_16x16x32_bf16 v[142:145], v[70:73], v[58:61], v[66:69]
	s_nop 2
	ds_read_b128 v[66:69], v127 offset:4608
	ds_read_b128 v[70:73], v127 offset:4672
	s_and_b64 s[38:39], s[0:1], s[88:89]
	s_and_b64 s[0:1], s[0:1], s[90:91]
	s_waitcnt lgkmcnt(1)
	v_mfma_f32_16x16x32_bf16 v[66:69], v[66:69], v[62:65], 0
	v_cndmask_b32_e64 v109, v175, v142, s[34:35]
	v_cndmask_b32_e64 v111, v175, v143, s[36:37]
	v_cndmask_b32_e64 v113, v175, v144, s[38:39]
	s_waitcnt lgkmcnt(0)
	v_mfma_f32_16x16x32_bf16 v[66:69], v[70:73], v[58:61], v[66:69]
	ds_read_b128 v[70:73], v127 offset:5184
	ds_read_b128 v[74:77], v127 offset:5248
	s_waitcnt lgkmcnt(1)
	v_mfma_f32_16x16x32_bf16 v[70:73], v[70:73], v[62:65], 0
	s_nop 3
	v_cndmask_b32_e32 v66, v66, v175, vcc
	v_cndmask_b32_e32 v67, v67, v175, vcc
	v_cndmask_b32_e32 v68, v68, v175, vcc
	s_waitcnt lgkmcnt(0)
	v_mfma_f32_16x16x32_bf16 v[70:73], v[74:77], v[58:61], v[70:73]
	ds_read_b128 v[74:77], v127 offset:9216
	ds_read_b128 v[78:81], v127 offset:9280
	v_cndmask_b32_e32 v69, v69, v175, vcc
	s_waitcnt lgkmcnt(1)
	v_mfma_f32_16x16x32_bf16 v[74:77], v[74:77], v[62:65], 0
	s_nop 2
	v_cndmask_b32_e32 v70, v70, v175, vcc
	v_cndmask_b32_e32 v71, v71, v175, vcc
	v_cndmask_b32_e32 v72, v72, v175, vcc
	s_waitcnt lgkmcnt(0)
	v_mfma_f32_16x16x32_bf16 v[74:77], v[78:81], v[58:61], v[74:77]
	ds_read_b128 v[78:81], v127 offset:9792
	ds_read_b128 v[82:85], v127 offset:9856
	v_cndmask_b32_e32 v73, v73, v175, vcc
	s_waitcnt lgkmcnt(1)
	v_mfma_f32_16x16x32_bf16 v[78:81], v[78:81], v[62:65], 0
	s_nop 2
	v_cndmask_b32_e32 v74, v74, v175, vcc
	v_cndmask_b32_e32 v75, v75, v175, vcc
	v_cndmask_b32_e32 v76, v76, v175, vcc
	s_waitcnt lgkmcnt(0)
	v_mfma_f32_16x16x32_bf16 v[78:81], v[82:85], v[58:61], v[78:81]
	ds_read_b128 v[82:85], v127 offset:13824
	ds_read_b128 v[86:89], v127 offset:13888
	v_cndmask_b32_e32 v77, v77, v175, vcc
	s_waitcnt lgkmcnt(1)
	v_mfma_f32_16x16x32_bf16 v[82:85], v[82:85], v[62:65], 0
	s_nop 2
	v_cndmask_b32_e32 v78, v78, v175, vcc
	v_cndmask_b32_e32 v79, v79, v175, vcc
	v_cndmask_b32_e32 v80, v80, v175, vcc
	s_waitcnt lgkmcnt(0)
	v_mfma_f32_16x16x32_bf16 v[82:85], v[86:89], v[58:61], v[82:85]
	ds_read_b128 v[86:89], v127 offset:14400
	ds_read_b128 v[90:93], v127 offset:14464
	v_cndmask_b32_e32 v81, v81, v175, vcc
	s_waitcnt lgkmcnt(1)
	v_mfma_f32_16x16x32_bf16 v[86:89], v[86:89], v[62:65], 0
	s_nop 2
	v_cndmask_b32_e32 v82, v82, v175, vcc
	v_cndmask_b32_e32 v83, v83, v175, vcc
	v_cndmask_b32_e32 v84, v84, v175, vcc
	s_waitcnt lgkmcnt(0)
	v_mfma_f32_16x16x32_bf16 v[86:89], v[90:93], v[58:61], v[86:89]
	ds_read_b128 v[90:93], v127 offset:18432
	ds_read_b128 v[146:149], v127 offset:18496
	v_cndmask_b32_e32 v85, v85, v175, vcc
	s_waitcnt lgkmcnt(1)
	v_mfma_f32_16x16x32_bf16 v[90:93], v[90:93], v[62:65], 0
	s_nop 2
	v_cndmask_b32_e32 v86, v86, v175, vcc
	v_cndmask_b32_e32 v87, v87, v175, vcc
	v_cndmask_b32_e32 v88, v88, v175, vcc
	s_waitcnt lgkmcnt(0)
	v_mfma_f32_16x16x32_bf16 v[90:93], v[146:149], v[58:61], v[90:93]
	ds_read_b128 v[146:149], v127 offset:19008
	ds_read_b128 v[150:153], v127 offset:19072
	v_cndmask_b32_e32 v89, v89, v175, vcc
	s_waitcnt lgkmcnt(1)
	v_mfma_f32_16x16x32_bf16 v[62:65], v[146:149], v[62:65], 0
	s_nop 2
	v_cndmask_b32_e64 v90, v175, v90, s[4:5]
	v_cndmask_b32_e64 v91, v175, v91, s[6:7]
	v_cndmask_b32_e64 v92, v175, v92, s[8:9]
	s_waitcnt lgkmcnt(0)
	v_mfma_f32_16x16x32_bf16 v[58:61], v[150:153], v[58:61], v[62:65]
	v_cndmask_b32_e64 v93, v175, v93, s[10:11]
	s_nop 1
	v_cndmask_b32_e64 v62, v175, v136, s[24:25]
	v_cndmask_b32_e64 v63, v175, v137, s[26:27]
	v_max3_f32 v64, v62, s2, v63
	v_cndmask_b32_e64 v65, v175, v138, s[28:29]
	v_max3_f32 v64, v64, v65, v107
	v_max3_f32 v64, v64, v109, v111
	v_cndmask_b32_e64 v136, v175, v145, s[0:1]
	v_max3_f32 v64, v64, v113, v136
	v_max3_f32 v64, v64, v66, v67
	v_max3_f32 v64, v64, v68, v69
	v_max3_f32 v64, v64, v70, v71
	v_max3_f32 v64, v64, v72, v73
	v_max3_f32 v64, v64, v74, v75
	v_max3_f32 v64, v64, v76, v77
	v_max3_f32 v64, v64, v78, v79
	v_max3_f32 v64, v64, v80, v81
	v_max3_f32 v64, v64, v82, v83
	v_max3_f32 v64, v64, v84, v85
	v_max3_f32 v64, v64, v86, v87
	v_max3_f32 v64, v64, v88, v89
	v_max3_f32 v64, v64, v90, v91
	v_max3_f32 v64, v64, v92, v93
	v_cndmask_b32_e64 v58, v175, v58, s[12:13]
	v_cndmask_b32_e64 v59, v175, v59, s[14:15]
	v_max3_f32 v64, v64, v58, v59
	v_cndmask_b32_e64 v60, v175, v60, s[16:17]
	v_cndmask_b32_e64 v61, v175, v61, s[18:19]
	v_max3_f32 v64, v64, v60, v61
	v_mov_b32_e32 v137, v64
	s_nop 1
	v_permlane16_swap_b32_e32 v64, v137
	s_mov_b32 s2, 0x3fb8aa3b
	s_waitcnt lgkmcnt(0)
	v_max_f32_e32 v137, v137, v137
	v_max_f32_e32 v64, v64, v137
	v_mov_b32_e32 v137, v64
	s_nop 1
	v_permlane32_swap_b32_e32 v64, v137
	s_waitcnt lgkmcnt(0)
	v_max3_f32 v64, v64, v137, v99
	v_sub_f32_e32 v62, v62, v64
	v_exp_f32_e32 v62, v62
	v_sub_f32_e32 v63, v63, v64
	v_exp_f32_e32 v63, v63
	v_sub_f32_e32 v65, v65, v64
	v_exp_f32_e32 v65, v65
	v_sub_f32_e32 v107, v107, v64
	v_exp_f32_e32 v107, v107
	v_sub_f32_e32 v109, v109, v64
	v_add_f32_e32 v137, 0, v62
	v_exp_f32_e32 v109, v109
	v_sub_f32_e32 v111, v111, v64
	v_add_f32_e32 v137, v63, v137
	v_exp_f32_e32 v111, v111
	v_sub_f32_e32 v113, v113, v64
	v_add_f32_e32 v137, v65, v137
	v_exp_f32_e32 v113, v113
	v_sub_f32_e32 v136, v136, v64
	v_add_f32_e32 v137, v107, v137
	v_exp_f32_e32 v136, v136
	v_sub_f32_e32 v66, v66, v64
	v_add_f32_e32 v137, v109, v137
	v_exp_f32_e32 v66, v66
	v_sub_f32_e32 v67, v67, v64
	v_add_f32_e32 v137, v111, v137
	v_exp_f32_e32 v67, v67
	v_sub_f32_e32 v68, v68, v64
	v_add_f32_e32 v137, v113, v137
	v_exp_f32_e32 v68, v68
	v_sub_f32_e32 v69, v69, v64
	v_add_f32_e32 v137, v136, v137
	v_exp_f32_e32 v69, v69
	v_sub_f32_e32 v70, v70, v64
	v_add_f32_e32 v137, v66, v137
	v_exp_f32_e32 v138, v70
	v_add_f32_e32 v137, v67, v137
	v_add_f32_e32 v137, v68, v137
	v_add_f32_e32 v137, v69, v137
	v_sub_f32_e32 v71, v71, v64
	v_add_f32_e32 v70, v138, v137
	v_exp_f32_e32 v137, v71
	v_sub_f32_e32 v71, v72, v64
	v_exp_f32_e32 v139, v71
	v_sub_f32_e32 v71, v73, v64
	v_exp_f32_e32 v73, v71
	v_sub_f32_e32 v71, v74, v64
	v_exp_f32_e32 v74, v71
	v_sub_f32_e32 v71, v75, v64
	v_add_f32_e32 v70, v137, v70
	v_exp_f32_e32 v75, v71
	v_sub_f32_e32 v71, v76, v64
	v_add_f32_e32 v70, v139, v70
	v_exp_f32_e32 v76, v71
	v_sub_f32_e32 v71, v77, v64
	v_add_f32_e32 v70, v73, v70
	v_exp_f32_e32 v77, v71
	v_sub_f32_e32 v71, v78, v64
	v_add_f32_e32 v70, v74, v70
	v_exp_f32_e32 v78, v71
	v_sub_f32_e32 v71, v79, v64
	v_add_f32_e32 v70, v75, v70
	v_exp_f32_e32 v79, v71
	v_sub_f32_e32 v71, v80, v64
	v_add_f32_e32 v70, v76, v70
	v_exp_f32_e32 v80, v71
	v_sub_f32_e32 v71, v81, v64
	v_add_f32_e32 v70, v77, v70
	v_exp_f32_e32 v81, v71
	v_sub_f32_e32 v71, v82, v64
	v_add_f32_e32 v70, v78, v70
	v_exp_f32_e32 v82, v71
	v_sub_f32_e32 v71, v83, v64
	v_add_f32_e32 v70, v79, v70
	v_exp_f32_e32 v83, v71
	v_sub_f32_e32 v71, v84, v64
	v_add_f32_e32 v70, v80, v70
	v_exp_f32_e32 v84, v71
	v_sub_f32_e32 v71, v85, v64
	v_add_f32_e32 v70, v81, v70
	v_exp_f32_e32 v85, v71
	v_sub_f32_e32 v71, v86, v64
	v_add_f32_e32 v70, v82, v70
	v_exp_f32_e32 v86, v71
	v_sub_f32_e32 v71, v87, v64
	v_add_f32_e32 v70, v83, v70
	v_exp_f32_e32 v87, v71
	v_sub_f32_e32 v71, v88, v64
	v_add_f32_e32 v70, v84, v70
	v_exp_f32_e32 v88, v71
	v_sub_f32_e32 v71, v89, v64
	v_add_f32_e32 v70, v85, v70
	v_exp_f32_e32 v89, v71
	v_sub_f32_e32 v71, v90, v64
	v_add_f32_e32 v70, v86, v70
	v_exp_f32_e32 v90, v71
	v_sub_f32_e32 v71, v91, v64
	v_add_f32_e32 v70, v87, v70
	v_exp_f32_e32 v91, v71
	v_sub_f32_e32 v71, v92, v64
	v_add_f32_e32 v70, v88, v70
	v_exp_f32_e32 v92, v71
	v_sub_f32_e32 v71, v93, v64
	v_add_f32_e32 v70, v89, v70
	v_exp_f32_e32 v93, v71
	v_sub_f32_e32 v58, v58, v64
	v_add_f32_e32 v70, v90, v70
	v_exp_f32_e32 v142, v58
	v_sub_f32_e32 v59, v59, v64
	v_add_f32_e32 v70, v91, v70
	v_exp_f32_e32 v143, v59
	v_sub_f32_e32 v59, v60, v64
	v_add_f32_e32 v70, v92, v70
	v_exp_f32_e32 v144, v59
	v_sub_f32_e32 v59, v61, v64
	v_add_f32_e32 v70, v93, v70
	v_exp_f32_e32 v145, v59
	v_add_f32_e32 v58, v142, v70
	v_add_f32_e32 v58, v143, v58
	v_add_f32_e32 v58, v144, v58
	v_add_f32_e32 v58, v145, v58
	v_mov_b32_e32 v59, v58
	s_nop 1
	v_permlane16_swap_b32_e32 v58, v59
	v_cvt_pk_bf16_f32 v62, v62, v63
	v_cvt_pk_bf16_f32 v63, v65, v107
	s_waitcnt lgkmcnt(0)
	v_add_f32_e32 v58, v58, v59
	v_mov_b32_e32 v59, v58
	s_nop 1
	v_permlane32_swap_b32_e32 v58, v59
	s_waitcnt lgkmcnt(0)
	v_add_f32_e32 v58, v58, v59
	v_fma_f32 v59, v135, s2, -v64
	v_exp_f32_e32 v59, v59
	v_cvt_pk_bf16_f32 v64, v109, v111
	v_cvt_pk_bf16_f32 v65, v113, v136
	v_cvt_pk_bf16_f32 v70, v66, v67
	v_cvt_pk_bf16_f32 v71, v68, v69
	v_cvt_pk_bf16_f32 v72, v138, v137
	s_nop 0
	v_add_f32_e32 v135, v59, v58
	v_cvt_pk_bf16_f32 v73, v139, v73
	v_cvt_pk_bf16_f32 v66, v74, v75
	v_cvt_pk_bf16_f32 v67, v76, v77
	v_cvt_pk_bf16_f32 v68, v78, v79
	v_div_scale_f32 v78, s[52:53], v135, v135, 1.0
	v_rcp_f32_e32 v79, v78
	v_cvt_pk_bf16_f32 v69, v80, v81
	v_cvt_pk_bf16_f32 v58, v82, v83
	v_cvt_pk_bf16_f32 v59, v84, v85
	v_cvt_pk_bf16_f32 v60, v86, v87
	v_cvt_pk_bf16_f32 v61, v88, v89
	s_nop 0
	v_fma_f32 v80, -v78, v79, 1.0
	v_fmac_f32_e32 v79, v80, v79
	v_div_scale_f32 v80, vcc, 1.0, v135, 1.0
	v_mul_f32_e32 v81, v80, v79
	v_fma_f32 v82, -v78, v81, v80
	v_fmac_f32_e32 v81, v82, v79
	v_fma_f32 v78, -v78, v81, v80
	v_div_fmas_f32 v78, v78, v79, v81
	v_cvt_pk_bf16_f32 v74, v90, v91
	v_cvt_pk_bf16_f32 v75, v92, v93
	v_cvt_pk_bf16_f32 v76, v142, v143
	v_cvt_pk_bf16_f32 v77, v144, v145
	v_div_fixup_f32 v84, v78, v135, 1.0
	ds_read_b128 v[78:81], v0 offset:39168
	ds_read_b128 v[86:89], v0 offset:39232
	s_waitcnt lgkmcnt(1)
	v_mfma_f32_16x16x32_bf16 v[78:81], v[78:81], v[62:65], 0
	v_mad_i64_i32 v[82:83], s[52:53], v134, s33, v[100:101]
	s_waitcnt lgkmcnt(0)
	v_mfma_f32_16x16x32_bf16 v[78:81], v[86:89], v[70:73], v[78:81]
	ds_read_b128 v[86:89], v0 offset:39296
	s_waitcnt lgkmcnt(0)
	v_mfma_f32_16x16x32_bf16 v[78:81], v[86:89], v[66:69], v[78:81]
	ds_read_b128 v[86:89], v0 offset:39360
	s_waitcnt lgkmcnt(0)
	v_mfma_f32_16x16x32_bf16 v[78:81], v[86:89], v[58:61], v[78:81]
	ds_read_b128 v[86:89], v0 offset:39424
	s_waitcnt lgkmcnt(0)
	v_mfma_f32_16x16x32_bf16 v[78:81], v[86:89], v[74:77], v[78:81]
	s_and_saveexec_b64 vcc, s[70:71]
	s_cbranch_execz .LBB0_147
	s_nop 5
	v_mul_f32_e32 v78, v78, v84
	v_mul_f32_e32 v79, v79, v84
	v_cvt_pk_bf16_f32 v78, v78, v79
	v_mul_f32_e32 v79, v80, v84
	v_mul_f32_e32 v80, v81, v84
	v_cvt_pk_bf16_f32 v79, v79, v80
	global_store_dwordx2 v[82:83], v[78:79], off

.LBB0_153:
	s_or_b64 exec, exec, vcc
	s_and_b64 vcc, exec, s[44:45]
	s_cbranch_vccnz .LBB0_53
	s_nop 2
	ds_read_b128 v[58:61], v127 offset:2304
	ds_read_b128 v[62:65], v127 offset:2368
	s_mov_b32 s2, 0xff800000
	s_and_b64 s[44:45], s[22:23], s[20:21]
	s_waitcnt lgkmcnt(1)
	v_mfma_f32_16x16x32_bf16 v[58:61], v[58:61], v[54:57], 0
	s_waitcnt lgkmcnt(0)
	v_mfma_f32_16x16x32_bf16 v[58:61], v[62:65], v[50:53], v[58:61]
	ds_read_b128 v[62:65], v127 offset:2880
	ds_read_b128 v[66:69], v127 offset:2944
	s_waitcnt lgkmcnt(1)
	v_mfma_f32_16x16x32_bf16 v[62:65], v[62:65], v[54:57], 0
	s_waitcnt lgkmcnt(0)
	v_mfma_f32_16x16x32_bf16 v[62:65], v[66:69], v[50:53], v[62:65]
	ds_read_b128 v[66:69], v127 offset:6912
	ds_read_b128 v[70:73], v127 offset:6976
	s_waitcnt lgkmcnt(1)
	v_mfma_f32_16x16x32_bf16 v[66:69], v[66:69], v[54:57], 0
	s_waitcnt lgkmcnt(0)
	v_mfma_f32_16x16x32_bf16 v[66:69], v[70:73], v[50:53], v[66:69]
	ds_read_b128 v[70:73], v127 offset:7488
	ds_read_b128 v[74:77], v127 offset:7552
	s_waitcnt lgkmcnt(1)
	v_mfma_f32_16x16x32_bf16 v[70:73], v[70:73], v[54:57], 0
	s_waitcnt lgkmcnt(0)
	v_mfma_f32_16x16x32_bf16 v[70:73], v[74:77], v[50:53], v[70:73]
	ds_read_b128 v[74:77], v127 offset:11520
	ds_read_b128 v[78:81], v127 offset:11584
	s_waitcnt lgkmcnt(1)
	v_mfma_f32_16x16x32_bf16 v[74:77], v[74:77], v[54:57], 0
	s_waitcnt lgkmcnt(0)
	v_mfma_f32_16x16x32_bf16 v[74:77], v[78:81], v[50:53], v[74:77]
	ds_read_b128 v[78:81], v127 offset:12096
	ds_read_b128 v[82:85], v127 offset:12160
	s_waitcnt lgkmcnt(1)
	v_mfma_f32_16x16x32_bf16 v[78:81], v[78:81], v[54:57], 0
	s_waitcnt lgkmcnt(0)
	v_mfma_f32_16x16x32_bf16 v[78:81], v[82:85], v[50:53], v[78:81]
	ds_read_b128 v[82:85], v127 offset:16128
	ds_read_b128 v[86:89], v127 offset:16192
	s_waitcnt lgkmcnt(1)
	v_mfma_f32_16x16x32_bf16 v[82:85], v[82:85], v[54:57], 0
	s_waitcnt lgkmcnt(0)
	v_mfma_f32_16x16x32_bf16 v[82:85], v[86:89], v[50:53], v[82:85]
	ds_read_b128 v[86:89], v127 offset:16704
	ds_read_b128 v[90:93], v127 offset:16768
	s_waitcnt lgkmcnt(1)
	v_mfma_f32_16x16x32_bf16 v[86:89], v[86:89], v[54:57], 0
	s_waitcnt lgkmcnt(0)
	v_mfma_f32_16x16x32_bf16 v[86:89], v[90:93], v[50:53], v[86:89]
	ds_read_b128 v[90:93], v127 offset:20736
	ds_read_b128 v[134:137], v127 offset:20800
	s_waitcnt lgkmcnt(1)
	v_mfma_f32_16x16x32_bf16 v[90:93], v[90:93], v[54:57], 0
	s_waitcnt lgkmcnt(0)
	v_mfma_f32_16x16x32_bf16 v[90:93], v[134:137], v[50:53], v[90:93]
	ds_read_b128 v[134:137], v127 offset:21312
	ds_read_b128 v[142:145], v127 offset:21376
	s_waitcnt lgkmcnt(1)
	v_mfma_f32_16x16x32_bf16 v[54:57], v[134:137], v[54:57], 0
	s_waitcnt lgkmcnt(0)
	v_mfma_f32_16x16x32_bf16 v[50:53], v[142:145], v[50:53], v[54:57]
	s_nop 5
	v_cndmask_b32_e64 v54, v175, v58, s[24:25]
	v_cndmask_b32_e64 v55, v175, v59, s[26:27]
	v_max3_f32 v56, v54, s2, v55
	v_cndmask_b32_e64 v57, v175, v60, s[28:29]
	v_cndmask_b32_e64 v58, v175, v61, s[30:31]
	v_max3_f32 v56, v56, v57, v58
	v_cndmask_b32_e64 v59, v175, v62, s[34:35]
	v_cndmask_b32_e64 v60, v175, v63, s[36:37]
	v_max3_f32 v56, v56, v59, v60
	v_cndmask_b32_e64 v61, v175, v64, s[38:39]
	v_cndmask_b32_e64 v62, v175, v65, s[0:1]
	v_max3_f32 v56, v56, v61, v62
	v_cndmask_b32_e64 v63, v66, v175, s[22:23]
	v_cndmask_b32_e64 v64, v67, v175, s[22:23]
	v_max3_f32 v56, v56, v63, v64
	v_cndmask_b32_e64 v65, v68, v175, s[22:23]
	v_cndmask_b32_e64 v66, v69, v175, s[22:23]
	v_max3_f32 v56, v56, v65, v66
	v_cndmask_b32_e64 v67, v70, v175, s[22:23]
	v_cndmask_b32_e64 v68, v71, v175, s[22:23]
	v_max3_f32 v56, v56, v67, v68
	v_cndmask_b32_e64 v69, v72, v175, s[22:23]
	v_cndmask_b32_e64 v70, v73, v175, s[22:23]
	v_max3_f32 v56, v56, v69, v70
	v_cndmask_b32_e64 v71, v74, v175, s[22:23]
	v_cndmask_b32_e64 v72, v75, v175, s[22:23]
	v_max3_f32 v56, v56, v71, v72
	v_cndmask_b32_e64 v73, v76, v175, s[22:23]
	v_cndmask_b32_e64 v74, v77, v175, s[22:23]
	v_max3_f32 v56, v56, v73, v74
	v_cndmask_b32_e64 v75, v78, v175, s[22:23]
	v_cndmask_b32_e64 v76, v79, v175, s[22:23]
	v_max3_f32 v56, v56, v75, v76
	v_cndmask_b32_e64 v77, v80, v175, s[22:23]
	v_cndmask_b32_e64 v78, v81, v175, s[22:23]
	v_max3_f32 v56, v56, v77, v78
	v_cndmask_b32_e64 v79, v82, v175, s[44:45]
	v_cndmask_b32_e64 v80, v83, v175, s[44:45]
	v_max3_f32 v56, v56, v79, v80
	v_cndmask_b32_e64 v81, v84, v175, s[44:45]
	v_cndmask_b32_e64 v82, v85, v175, s[44:45]
	v_max3_f32 v56, v56, v81, v82
	v_cndmask_b32_e64 v83, v86, v175, s[44:45]
	v_cndmask_b32_e64 v84, v87, v175, s[44:45]
	v_max3_f32 v56, v56, v83, v84
	v_cndmask_b32_e64 v85, v88, v175, s[44:45]
	v_cndmask_b32_e64 v86, v89, v175, s[44:45]
	v_max3_f32 v56, v56, v85, v86
	v_cndmask_b32_e64 v87, v175, v90, s[4:5]
	v_cndmask_b32_e64 v88, v175, v91, s[6:7]
	v_max3_f32 v56, v56, v87, v88
	v_cndmask_b32_e64 v89, v175, v92, s[8:9]
	v_cndmask_b32_e64 v90, v175, v93, s[10:11]
	v_max3_f32 v56, v56, v89, v90
	v_cndmask_b32_e64 v50, v175, v50, s[12:13]
	v_cndmask_b32_e64 v51, v175, v51, s[14:15]
	v_max3_f32 v56, v56, v50, v51
	v_cndmask_b32_e64 v52, v175, v52, s[16:17]
	v_cndmask_b32_e64 v53, v175, v53, s[18:19]
	v_max3_f32 v56, v56, v52, v53
	v_mov_b32_e32 v91, v56
	s_nop 1
	v_permlane16_swap_b32_e32 v56, v91
	s_waitcnt lgkmcnt(0)
	v_max_f32_e32 v91, v91, v91
	v_max_f32_e32 v56, v56, v91
	v_mov_b32_e32 v91, v56
	s_nop 1
	v_permlane32_swap_b32_e32 v56, v91
	s_waitcnt lgkmcnt(0)
	v_max3_f32 v56, v56, v91, v99
	v_sub_f32_e32 v54, v54, v56
	v_exp_f32_e32 v54, v54
	v_sub_f32_e32 v55, v55, v56
	v_exp_f32_e32 v55, v55
	v_sub_f32_e32 v57, v57, v56
	v_exp_f32_e32 v57, v57
	v_sub_f32_e32 v58, v58, v56
	v_exp_f32_e32 v58, v58
	v_sub_f32_e32 v59, v59, v56
	v_add_f32_e32 v91, 0, v54
	v_exp_f32_e32 v59, v59
	v_sub_f32_e32 v60, v60, v56
	v_add_f32_e32 v91, v55, v91
	v_exp_f32_e32 v60, v60
	v_sub_f32_e32 v61, v61, v56
	v_add_f32_e32 v91, v57, v91
	v_exp_f32_e32 v61, v61
	v_sub_f32_e32 v62, v62, v56
	v_add_f32_e32 v91, v58, v91
	v_exp_f32_e32 v62, v62
	v_sub_f32_e32 v63, v63, v56
	v_add_f32_e32 v91, v59, v91
	v_exp_f32_e32 v63, v63
	v_sub_f32_e32 v64, v64, v56
	v_add_f32_e32 v91, v60, v91
	v_exp_f32_e32 v64, v64
	v_sub_f32_e32 v65, v65, v56
	v_add_f32_e32 v91, v61, v91
	v_exp_f32_e32 v65, v65
	v_sub_f32_e32 v66, v66, v56
	v_add_f32_e32 v91, v62, v91
	v_exp_f32_e32 v92, v66
	v_add_f32_e32 v91, v63, v91
	v_add_f32_e32 v91, v64, v91
	v_add_f32_e32 v91, v65, v91
	v_sub_f32_e32 v67, v67, v56
	v_add_f32_e32 v66, v92, v91
	v_exp_f32_e32 v91, v67
	v_sub_f32_e32 v67, v68, v56
	v_exp_f32_e32 v68, v67
	v_sub_f32_e32 v67, v69, v56
	v_exp_f32_e32 v69, v67
	v_sub_f32_e32 v67, v70, v56
	v_exp_f32_e32 v70, v67
	v_sub_f32_e32 v67, v71, v56
	v_add_f32_e32 v66, v91, v66
	v_exp_f32_e32 v71, v67
	v_sub_f32_e32 v67, v72, v56
	v_add_f32_e32 v66, v68, v66
	v_exp_f32_e32 v72, v67
	v_sub_f32_e32 v67, v73, v56
	v_add_f32_e32 v66, v69, v66
	v_exp_f32_e32 v73, v67
	v_sub_f32_e32 v67, v74, v56
	v_add_f32_e32 v66, v70, v66
	v_exp_f32_e32 v74, v67
	v_sub_f32_e32 v67, v75, v56
	v_add_f32_e32 v66, v71, v66
	v_exp_f32_e32 v75, v67
	v_sub_f32_e32 v67, v76, v56
	v_add_f32_e32 v66, v72, v66
	v_exp_f32_e32 v76, v67
	v_sub_f32_e32 v67, v77, v56
	v_add_f32_e32 v66, v73, v66
	v_exp_f32_e32 v77, v67
	v_sub_f32_e32 v67, v78, v56
	v_add_f32_e32 v66, v74, v66
	v_exp_f32_e32 v78, v67
	v_sub_f32_e32 v67, v79, v56
	v_add_f32_e32 v66, v75, v66
	v_exp_f32_e32 v79, v67
	v_sub_f32_e32 v67, v80, v56
	v_add_f32_e32 v66, v76, v66
	v_exp_f32_e32 v80, v67
	v_sub_f32_e32 v67, v81, v56
	v_add_f32_e32 v66, v77, v66
	v_exp_f32_e32 v81, v67
	v_sub_f32_e32 v67, v82, v56
	v_add_f32_e32 v66, v78, v66
	v_exp_f32_e32 v82, v67
	v_sub_f32_e32 v67, v83, v56
	v_add_f32_e32 v66, v79, v66
	v_exp_f32_e32 v83, v67
	v_sub_f32_e32 v67, v84, v56
	v_add_f32_e32 v66, v80, v66
	v_exp_f32_e32 v84, v67
	v_sub_f32_e32 v67, v85, v56
	v_add_f32_e32 v66, v81, v66
	v_exp_f32_e32 v85, v67
	v_sub_f32_e32 v67, v86, v56
	v_add_f32_e32 v66, v82, v66
	v_exp_f32_e32 v86, v67
	v_sub_f32_e32 v67, v87, v56
	v_add_f32_e32 v66, v83, v66
	v_exp_f32_e32 v87, v67
	v_sub_f32_e32 v67, v88, v56
	v_add_f32_e32 v66, v84, v66
	v_exp_f32_e32 v88, v67
	v_sub_f32_e32 v67, v89, v56
	v_add_f32_e32 v66, v85, v66
	v_exp_f32_e32 v89, v67
	v_sub_f32_e32 v67, v90, v56
	v_add_f32_e32 v66, v86, v66
	v_exp_f32_e32 v90, v67
	v_sub_f32_e32 v50, v50, v56
	v_add_f32_e32 v66, v87, v66
	v_exp_f32_e32 v93, v50
	v_sub_f32_e32 v51, v51, v56
	v_add_f32_e32 v66, v88, v66
	v_exp_f32_e32 v107, v51
	v_sub_f32_e32 v51, v52, v56
	v_add_f32_e32 v66, v89, v66
	v_exp_f32_e32 v109, v51
	v_sub_f32_e32 v51, v53, v56
	v_add_f32_e32 v66, v90, v66
	v_exp_f32_e32 v111, v51
	v_add_f32_e32 v50, v93, v66
	v_add_f32_e32 v50, v107, v50
	v_add_f32_e32 v50, v109, v50
	v_add_f32_e32 v50, v111, v50
	v_mov_b32_e32 v51, v50
	s_nop 1
	v_permlane16_swap_b32_e32 v50, v51
	v_cvt_pk_bf16_f32 v54, v54, v55
	v_cvt_pk_bf16_f32 v55, v57, v58
	s_waitcnt lgkmcnt(0)
	v_add_f32_e32 v50, v50, v51
	v_mov_b32_e32 v51, v50
	s_nop 1
	v_permlane32_swap_b32_e32 v50, v51
	s_waitcnt lgkmcnt(0)
	v_add_f32_e32 v50, v50, v51
	v_sub_f32_e32 v51, v99, v56
	v_exp_f32_e32 v51, v51
	v_cvt_pk_bf16_f32 v56, v59, v60
	v_cvt_pk_bf16_f32 v57, v61, v62
	v_cvt_pk_bf16_f32 v66, v63, v64
	v_cvt_pk_bf16_f32 v67, v65, v92
	v_cvt_pk_bf16_f32 v68, v91, v68
	s_nop 0
	v_add_f32_e32 v113, v51, v50
	v_cvt_pk_bf16_f32 v69, v69, v70
	v_div_scale_f32 v70, s[52:53], v113, v113, 1.0
	v_cvt_pk_bf16_f32 v62, v71, v72
	v_rcp_f32_e32 v71, v70
	v_cvt_pk_bf16_f32 v63, v73, v74
	v_cvt_pk_bf16_f32 v64, v75, v76
	v_cvt_pk_bf16_f32 v65, v77, v78
	v_cvt_pk_bf16_f32 v50, v79, v80
	v_cvt_pk_bf16_f32 v51, v81, v82
	s_nop 0
	v_fma_f32 v72, -v70, v71, 1.0
	v_fmac_f32_e32 v71, v72, v71
	v_div_scale_f32 v72, vcc, 1.0, v113, 1.0
	v_mul_f32_e32 v73, v72, v71
	v_fma_f32 v74, -v70, v73, v72
	v_fmac_f32_e32 v73, v74, v71
	v_fma_f32 v70, -v70, v73, v72
	v_cvt_pk_bf16_f32 v52, v83, v84
	v_cvt_pk_bf16_f32 v53, v85, v86
	v_cvt_pk_bf16_f32 v58, v87, v88
	v_cvt_pk_bf16_f32 v59, v89, v90
	v_cvt_pk_bf16_f32 v60, v93, v107
	v_cvt_pk_bf16_f32 v61, v109, v111
	v_div_fmas_f32 v70, v70, v71, v73
	ds_read_b128 v[72:75], v0 offset:39200
	ds_read_b128 v[76:79], v0 offset:39264
	s_waitcnt lgkmcnt(1)
	v_mfma_f32_16x16x32_bf16 v[72:75], v[72:75], v[54:57], 0
	v_div_fixup_f32 v80, v70, v113, 1.0
	v_mad_i64_i32 v[70:71], s[52:53], v112, s33, v[100:101]
	s_waitcnt lgkmcnt(0)
	v_mfma_f32_16x16x32_bf16 v[72:75], v[76:79], v[66:69], v[72:75]
	ds_read_b128 v[76:79], v0 offset:39328
	s_waitcnt lgkmcnt(0)
	v_mfma_f32_16x16x32_bf16 v[72:75], v[76:79], v[62:65], v[72:75]
	ds_read_b128 v[76:79], v0 offset:39392
	s_waitcnt lgkmcnt(0)
	v_mfma_f32_16x16x32_bf16 v[72:75], v[76:79], v[50:53], v[72:75]
	ds_read_b128 v[76:79], v0 offset:39456
	s_waitcnt lgkmcnt(0)
	v_mfma_f32_16x16x32_bf16 v[72:75], v[76:79], v[58:61], v[72:75]
	s_nop 7
	v_mul_f32_e32 v72, v72, v80
	v_mul_f32_e32 v73, v73, v80
	v_cvt_pk_bf16_f32 v72, v72, v73
	v_mul_f32_e32 v73, v74, v80
	v_mul_f32_e32 v74, v75, v80
	v_cvt_pk_bf16_f32 v73, v73, v74
	global_store_dwordx2 v[70:71], v[72:73], off
	ds_read_b128 v[72:75], v0 offset:48160
	ds_read_b128 v[76:79], v0 offset:48224
	s_waitcnt lgkmcnt(1)
	v_mfma_f32_16x16x32_bf16 v[72:75], v[72:75], v[54:57], 0
	s_waitcnt lgkmcnt(0)
	v_mfma_f32_16x16x32_bf16 v[72:75], v[76:79], v[66:69], v[72:75]
	ds_read_b128 v[76:79], v0 offset:48288
	s_waitcnt lgkmcnt(0)
	v_mfma_f32_16x16x32_bf16 v[72:75], v[76:79], v[62:65], v[72:75]
	ds_read_b128 v[76:79], v0 offset:48352
	s_waitcnt lgkmcnt(0)
	v_mfma_f32_16x16x32_bf16 v[72:75], v[76:79], v[50:53], v[72:75]
	ds_read_b128 v[76:79], v0 offset:48416
	s_waitcnt lgkmcnt(0)
	v_mfma_f32_16x16x32_bf16 v[72:75], v[76:79], v[58:61], v[72:75]
	s_nop 7
	v_mul_f32_e32 v72, v72, v80
	v_mul_f32_e32 v73, v73, v80
	v_cvt_pk_bf16_f32 v72, v72, v73
	v_mul_f32_e32 v73, v74, v80
	v_mul_f32_e32 v74, v75, v80
	v_cvt_pk_bf16_f32 v73, v73, v74
	global_store_dwordx2 v[70:71], v[72:73], off offset:32
	ds_read_b128 v[72:75], v0 offset:57120
	ds_read_b128 v[76:79], v0 offset:57184
	s_waitcnt lgkmcnt(1)
	v_mfma_f32_16x16x32_bf16 v[72:75], v[72:75], v[54:57], 0
	s_waitcnt lgkmcnt(0)
	v_mfma_f32_16x16x32_bf16 v[72:75], v[76:79], v[66:69], v[72:75]
	ds_read_b128 v[76:79], v0 offset:57248
	s_waitcnt lgkmcnt(0)
	v_mfma_f32_16x16x32_bf16 v[72:75], v[76:79], v[62:65], v[72:75]
	ds_read_b128 v[76:79], v0 offset:57312
	s_waitcnt lgkmcnt(0)
	v_mfma_f32_16x16x32_bf16 v[72:75], v[76:79], v[50:53], v[72:75]
	ds_read_b128 v[76:79], v0 offset:57376
	s_waitcnt lgkmcnt(0)
	v_mfma_f32_16x16x32_bf16 v[72:75], v[76:79], v[58:61], v[72:75]
	s_nop 7
	v_mul_f32_e32 v72, v80, v72
	v_mul_f32_e32 v73, v80, v73
	v_cvt_pk_bf16_f32 v72, v72, v73
	v_mul_f32_e32 v73, v80, v74
	v_mul_f32_e32 v74, v80, v75
	v_cvt_pk_bf16_f32 v73, v73, v74
	global_store_dwordx2 v[70:71], v[72:73], off offset:64
	ds_read_b128 v[72:75], v133 offset:39200
	s_waitcnt lgkmcnt(0)
	v_mfma_f32_16x16x32_bf16 v[54:57], v[72:75], v[54:57], 0
	ds_read_b128 v[72:75], v133 offset:39264
	s_waitcnt lgkmcnt(0)
	v_mfma_f32_16x16x32_bf16 v[54:57], v[72:75], v[66:69], v[54:57]
	ds_read_b128 v[66:69], v133 offset:39328
	s_waitcnt lgkmcnt(0)
	v_mfma_f32_16x16x32_bf16 v[54:57], v[66:69], v[62:65], v[54:57]
	ds_read_b128 v[62:65], v133 offset:39392
	s_waitcnt lgkmcnt(0)
	v_mfma_f32_16x16x32_bf16 v[50:53], v[62:65], v[50:53], v[54:57]
	s_nop 4
	ds_read_b128 v[54:57], v133 offset:39456
	s_waitcnt lgkmcnt(0)
	v_mfma_f32_16x16x32_bf16 v[50:53], v[54:57], v[58:61], v[50:53]
	s_nop 7
	v_mul_f32_e32 v50, v80, v50
	v_mul_f32_e32 v51, v80, v51
	v_cvt_pk_bf16_f32 v50, v50, v51
	v_mul_f32_e32 v51, v80, v52
	v_mul_f32_e32 v52, v80, v53
	v_cvt_pk_bf16_f32 v51, v51, v52
	global_store_dwordx2 v[70:71], v[50:51], off offset:96
	ds_read_b128 v[50:53], v127 offset:4608
	ds_read_b128 v[54:57], v127 offset:4672
	s_waitcnt lgkmcnt(1)
	v_mfma_f32_16x16x32_bf16 v[50:53], v[50:53], v[46:49], 0
	s_waitcnt lgkmcnt(0)
	v_mfma_f32_16x16x32_bf16 v[58:61], v[54:57], v[42:45], v[50:53]
	s_nop 5
	ds_read_b128 v[50:53], v127 offset:5184
	ds_read_b128 v[54:57], v127 offset:5248
	s_waitcnt lgkmcnt(1)
	v_mfma_f32_16x16x32_bf16 v[50:53], v[50:53], v[46:49], 0
	s_waitcnt lgkmcnt(0)
	v_mfma_f32_16x16x32_bf16 v[62:65], v[54:57], v[42:45], v[50:53]
	s_nop 5
	ds_read_b128 v[50:53], v127 offset:9216
	ds_read_b128 v[54:57], v127 offset:9280
	s_waitcnt lgkmcnt(1)
	v_mfma_f32_16x16x32_bf16 v[50:53], v[50:53], v[46:49], 0
	s_waitcnt lgkmcnt(0)
	v_mfma_f32_16x16x32_bf16 v[66:69], v[54:57], v[42:45], v[50:53]
	s_nop 5
	ds_read_b128 v[50:53], v127 offset:9792
	ds_read_b128 v[54:57], v127 offset:9856
	s_waitcnt lgkmcnt(1)
	v_mfma_f32_16x16x32_bf16 v[50:53], v[50:53], v[46:49], 0
	s_waitcnt lgkmcnt(0)
	v_mfma_f32_16x16x32_bf16 v[70:73], v[54:57], v[42:45], v[50:53]
	s_nop 5
	ds_read_b128 v[50:53], v127 offset:13824
	ds_read_b128 v[54:57], v127 offset:13888
	s_waitcnt lgkmcnt(1)
	v_mfma_f32_16x16x32_bf16 v[50:53], v[50:53], v[46:49], 0
	s_waitcnt lgkmcnt(0)
	v_mfma_f32_16x16x32_bf16 v[74:77], v[54:57], v[42:45], v[50:53]
	s_nop 5
	ds_read_b128 v[50:53], v127 offset:14400
	ds_read_b128 v[54:57], v127 offset:14464
	s_waitcnt lgkmcnt(1)
	v_mfma_f32_16x16x32_bf16 v[50:53], v[50:53], v[46:49], 0
	s_waitcnt lgkmcnt(0)
	v_mfma_f32_16x16x32_bf16 v[78:81], v[54:57], v[42:45], v[50:53]
	s_nop 5
	ds_read_b128 v[50:53], v127 offset:18432
	ds_read_b128 v[54:57], v127 offset:18496
	s_waitcnt lgkmcnt(1)
	v_mfma_f32_16x16x32_bf16 v[50:53], v[50:53], v[46:49], 0
	s_waitcnt lgkmcnt(0)
	v_mfma_f32_16x16x32_bf16 v[54:57], v[54:57], v[42:45], v[50:53]
	s_nop 5
	ds_read_b128 v[50:53], v127 offset:19008
	ds_read_b128 v[82:85], v127 offset:19072
	s_waitcnt lgkmcnt(1)
	v_mfma_f32_16x16x32_bf16 v[50:53], v[50:53], v[46:49], 0
	s_waitcnt lgkmcnt(0)
	v_mfma_f32_16x16x32_bf16 v[50:53], v[82:85], v[42:45], v[50:53]
	ds_read_b128 v[82:85], v127 offset:23040
	ds_read_b128 v[86:89], v127 offset:23104
	s_waitcnt lgkmcnt(1)
	v_mfma_f32_16x16x32_bf16 v[82:85], v[82:85], v[46:49], 0
	s_waitcnt lgkmcnt(0)
	v_mfma_f32_16x16x32_bf16 v[82:85], v[86:89], v[42:45], v[82:85]
	ds_read_b128 v[86:89], v127 offset:23616
	ds_read_b128 v[90:93], v127 offset:23680
	s_waitcnt lgkmcnt(1)
	v_mfma_f32_16x16x32_bf16 v[46:49], v[86:89], v[46:49], 0
	s_waitcnt lgkmcnt(0)
	v_mfma_f32_16x16x32_bf16 v[42:45], v[90:93], v[42:45], v[46:49]
	s_nop 5
	v_cndmask_b32_e64 v46, v175, v58, s[24:25]
	v_cndmask_b32_e64 v47, v175, v59, s[26:27]
	v_max3_f32 v48, v46, s2, v47
	v_cndmask_b32_e64 v49, v175, v60, s[28:29]
	v_cndmask_b32_e64 v58, v175, v61, s[30:31]
	v_max3_f32 v48, v48, v49, v58
	v_cndmask_b32_e64 v59, v175, v62, s[34:35]
	v_cndmask_b32_e64 v60, v175, v63, s[36:37]
	v_max3_f32 v48, v48, v59, v60
	v_cndmask_b32_e64 v61, v175, v64, s[38:39]
	v_cndmask_b32_e64 v62, v175, v65, s[0:1]
	v_max3_f32 v48, v48, v61, v62
	v_cndmask_b32_e64 v63, v66, v175, s[22:23]
	v_cndmask_b32_e64 v64, v67, v175, s[22:23]
	v_max3_f32 v48, v48, v63, v64
	v_cndmask_b32_e64 v65, v68, v175, s[22:23]
	v_cndmask_b32_e64 v66, v69, v175, s[22:23]
	v_max3_f32 v48, v48, v65, v66
	v_cndmask_b32_e64 v67, v70, v175, s[22:23]
	v_cndmask_b32_e64 v68, v71, v175, s[22:23]
	v_max3_f32 v48, v48, v67, v68
	v_cndmask_b32_e64 v69, v72, v175, s[22:23]
	v_cndmask_b32_e64 v70, v73, v175, s[22:23]
	v_max3_f32 v48, v48, v69, v70
	v_cndmask_b32_e64 v71, v74, v175, s[22:23]
	v_cndmask_b32_e64 v72, v75, v175, s[22:23]
	v_max3_f32 v48, v48, v71, v72
	v_cndmask_b32_e64 v73, v76, v175, s[22:23]
	v_cndmask_b32_e64 v74, v77, v175, s[22:23]
	v_max3_f32 v48, v48, v73, v74
	v_cndmask_b32_e64 v75, v78, v175, s[22:23]
	v_cndmask_b32_e64 v76, v79, v175, s[22:23]
	v_max3_f32 v48, v48, v75, v76
	v_cndmask_b32_e64 v77, v80, v175, s[22:23]
	v_cndmask_b32_e64 v78, v81, v175, s[22:23]
	v_max3_f32 v48, v48, v77, v78
	v_max3_f32 v48, v48, v54, v55
	v_max3_f32 v48, v48, v56, v57
	v_max3_f32 v48, v48, v50, v51
	v_max3_f32 v48, v48, v52, v53
	v_cndmask_b32_e64 v79, v175, v82, s[4:5]
	v_cndmask_b32_e64 v80, v175, v83, s[6:7]
	v_max3_f32 v48, v48, v79, v80
	v_cndmask_b32_e64 v81, v175, v84, s[8:9]
	v_cndmask_b32_e64 v82, v175, v85, s[10:11]
	v_max3_f32 v48, v48, v81, v82
	v_cndmask_b32_e64 v42, v175, v42, s[12:13]
	v_cndmask_b32_e64 v43, v175, v43, s[14:15]
	v_max3_f32 v48, v48, v42, v43
	v_cndmask_b32_e64 v44, v175, v44, s[16:17]
	v_cndmask_b32_e64 v45, v175, v45, s[18:19]
	v_max3_f32 v48, v48, v44, v45
	v_mov_b32_e32 v83, v48
	s_nop 1
	v_permlane16_swap_b32_e32 v48, v83
	s_waitcnt lgkmcnt(0)
	v_max_f32_e32 v83, v83, v83
	v_max_f32_e32 v48, v48, v83
	v_mov_b32_e32 v83, v48
	s_nop 1
	v_permlane32_swap_b32_e32 v48, v83
	s_waitcnt lgkmcnt(0)
	v_max3_f32 v48, v48, v83, v99
	v_sub_f32_e32 v46, v46, v48
	v_exp_f32_e32 v46, v46
	v_sub_f32_e32 v47, v47, v48
	v_exp_f32_e32 v47, v47
	v_sub_f32_e32 v49, v49, v48
	v_exp_f32_e32 v49, v49
	v_sub_f32_e32 v58, v58, v48
	v_exp_f32_e32 v58, v58
	v_sub_f32_e32 v59, v59, v48
	v_add_f32_e32 v83, 0, v46
	v_exp_f32_e32 v59, v59
	v_sub_f32_e32 v60, v60, v48
	v_add_f32_e32 v83, v47, v83
	v_exp_f32_e32 v60, v60
	v_sub_f32_e32 v61, v61, v48
	v_add_f32_e32 v83, v49, v83
	v_exp_f32_e32 v61, v61
	v_sub_f32_e32 v62, v62, v48
	v_add_f32_e32 v83, v58, v83
	v_exp_f32_e32 v62, v62
	v_sub_f32_e32 v63, v63, v48
	v_add_f32_e32 v83, v59, v83
	v_exp_f32_e32 v63, v63
	v_sub_f32_e32 v64, v64, v48
	v_add_f32_e32 v83, v60, v83
	v_exp_f32_e32 v64, v64
	v_sub_f32_e32 v65, v65, v48
	v_add_f32_e32 v83, v61, v83
	v_exp_f32_e32 v65, v65
	v_sub_f32_e32 v66, v66, v48
	v_add_f32_e32 v83, v62, v83
	v_exp_f32_e32 v66, v66
	v_sub_f32_e32 v67, v67, v48
	v_add_f32_e32 v83, v63, v83
	v_exp_f32_e32 v67, v67
	v_sub_f32_e32 v68, v68, v48
	v_add_f32_e32 v83, v64, v83
	v_exp_f32_e32 v68, v68
	v_sub_f32_e32 v69, v69, v48
	v_add_f32_e32 v83, v65, v83
	v_exp_f32_e32 v69, v69
	v_sub_f32_e32 v70, v70, v48
	v_add_f32_e32 v83, v66, v83
	v_exp_f32_e32 v70, v70
	v_sub_f32_e32 v71, v71, v48
	v_add_f32_e32 v83, v67, v83
	v_exp_f32_e32 v71, v71
	v_sub_f32_e32 v72, v72, v48
	v_add_f32_e32 v83, v68, v83
	v_exp_f32_e32 v72, v72
	v_sub_f32_e32 v73, v73, v48
	v_add_f32_e32 v83, v69, v83
	v_exp_f32_e32 v73, v73
	v_sub_f32_e32 v74, v74, v48
	v_add_f32_e32 v83, v70, v83
	v_exp_f32_e32 v74, v74
	v_sub_f32_e32 v75, v75, v48
	v_add_f32_e32 v83, v71, v83
	v_exp_f32_e32 v75, v75
	v_sub_f32_e32 v76, v76, v48
	v_add_f32_e32 v83, v72, v83
	v_exp_f32_e32 v76, v76
	v_sub_f32_e32 v77, v77, v48
	v_add_f32_e32 v83, v73, v83
	v_exp_f32_e32 v77, v77
	v_sub_f32_e32 v78, v78, v48
	v_add_f32_e32 v83, v74, v83
	v_exp_f32_e32 v78, v78
	v_sub_f32_e32 v54, v54, v48
	v_add_f32_e32 v83, v75, v83
	v_exp_f32_e32 v84, v54
	v_add_f32_e32 v83, v76, v83
	v_add_f32_e32 v83, v77, v83
	v_add_f32_e32 v83, v78, v83
	v_sub_f32_e32 v55, v55, v48
	v_add_f32_e32 v54, v84, v83
	v_exp_f32_e32 v83, v55
	v_sub_f32_e32 v55, v56, v48
	v_exp_f32_e32 v85, v55
	v_sub_f32_e32 v55, v57, v48
	v_exp_f32_e32 v86, v55
	v_sub_f32_e32 v50, v50, v48
	v_exp_f32_e32 v50, v50
	v_sub_f32_e32 v51, v51, v48
	v_add_f32_e32 v54, v83, v54
	v_exp_f32_e32 v51, v51
	v_sub_f32_e32 v52, v52, v48
	v_add_f32_e32 v54, v85, v54
	v_exp_f32_e32 v52, v52
	v_sub_f32_e32 v53, v53, v48
	v_add_f32_e32 v54, v86, v54
	v_exp_f32_e32 v53, v53
	v_sub_f32_e32 v55, v79, v48
	v_add_f32_e32 v54, v50, v54
	v_exp_f32_e32 v79, v55
	v_sub_f32_e32 v55, v80, v48
	v_add_f32_e32 v54, v51, v54
	v_exp_f32_e32 v80, v55
	v_sub_f32_e32 v55, v81, v48
	v_add_f32_e32 v54, v52, v54
	v_exp_f32_e32 v81, v55
	v_sub_f32_e32 v55, v82, v48
	v_add_f32_e32 v54, v53, v54
	v_exp_f32_e32 v82, v55
	v_sub_f32_e32 v42, v42, v48
	v_add_f32_e32 v54, v79, v54
	v_exp_f32_e32 v87, v42
	v_sub_f32_e32 v43, v43, v48
	v_add_f32_e32 v54, v80, v54
	v_exp_f32_e32 v88, v43
	v_sub_f32_e32 v43, v44, v48
	v_add_f32_e32 v54, v81, v54
	v_exp_f32_e32 v89, v43
	v_sub_f32_e32 v43, v45, v48
	v_add_f32_e32 v54, v82, v54
	v_exp_f32_e32 v90, v43
	v_add_f32_e32 v42, v87, v54
	v_add_f32_e32 v42, v88, v42
	v_add_f32_e32 v42, v89, v42
	v_add_f32_e32 v42, v90, v42
	v_mov_b32_e32 v43, v42
	s_nop 1
	v_permlane16_swap_b32_e32 v42, v43
	v_cvt_pk_bf16_f32 v46, v46, v47
	v_cvt_pk_bf16_f32 v47, v49, v58
	s_waitcnt lgkmcnt(0)
	v_add_f32_e32 v42, v42, v43
	v_mov_b32_e32 v43, v42
	s_nop 1
	v_permlane32_swap_b32_e32 v42, v43
	s_waitcnt lgkmcnt(0)
	v_add_f32_e32 v42, v42, v43
	v_sub_f32_e32 v43, v99, v48
	v_exp_f32_e32 v43, v43
	v_cvt_pk_bf16_f32 v48, v59, v60
	v_cvt_pk_bf16_f32 v49, v61, v62
	v_cvt_pk_bf16_f32 v58, v63, v64
	v_cvt_pk_bf16_f32 v59, v65, v66
	v_cvt_pk_bf16_f32 v60, v67, v68
	s_nop 0
	v_add_f32_e32 v91, v43, v42
	v_div_scale_f32 v62, s[52:53], v91, v91, 1.0
	v_rcp_f32_e32 v63, v62
	v_cvt_pk_bf16_f32 v61, v69, v70
	v_cvt_pk_bf16_f32 v54, v71, v72
	v_cvt_pk_bf16_f32 v55, v73, v74
	v_cvt_pk_bf16_f32 v56, v75, v76
	v_cvt_pk_bf16_f32 v57, v77, v78
	s_nop 0
	v_fma_f32 v64, -v62, v63, 1.0
	v_fmac_f32_e32 v63, v64, v63
	v_div_scale_f32 v64, vcc, 1.0, v91, 1.0
	v_mul_f32_e32 v65, v64, v63
	v_fma_f32 v66, -v62, v65, v64
	v_fmac_f32_e32 v65, v66, v63
	v_fma_f32 v62, -v62, v65, v64
	v_cvt_pk_bf16_f32 v42, v84, v83
	v_cvt_pk_bf16_f32 v43, v85, v86
	v_cvt_pk_bf16_f32 v44, v50, v51
	v_cvt_pk_bf16_f32 v45, v52, v53
	v_cvt_pk_bf16_f32 v50, v79, v80
	v_cvt_pk_bf16_f32 v51, v81, v82
	v_cvt_pk_bf16_f32 v52, v87, v88
	v_cvt_pk_bf16_f32 v53, v89, v90
	v_div_fmas_f32 v62, v62, v63, v65
	ds_read_b128 v[64:67], v0 offset:39232
	ds_read_b128 v[68:71], v0 offset:39296
	s_waitcnt lgkmcnt(1)
	v_mfma_f32_16x16x32_bf16 v[64:67], v[64:67], v[46:49], 0
	v_div_fixup_f32 v72, v62, v91, 1.0
	v_mad_i64_i32 v[62:63], s[52:53], v110, s33, v[100:101]
	s_waitcnt lgkmcnt(0)
	v_mfma_f32_16x16x32_bf16 v[64:67], v[68:71], v[58:61], v[64:67]
	ds_read_b128 v[68:71], v0 offset:39360
	s_waitcnt lgkmcnt(0)
	v_mfma_f32_16x16x32_bf16 v[64:67], v[68:71], v[54:57], v[64:67]
	ds_read_b128 v[68:71], v0 offset:39424
	s_waitcnt lgkmcnt(0)
	v_mfma_f32_16x16x32_bf16 v[64:67], v[68:71], v[42:45], v[64:67]
	ds_read_b128 v[68:71], v0 offset:39488
	s_waitcnt lgkmcnt(0)
	v_mfma_f32_16x16x32_bf16 v[64:67], v[68:71], v[50:53], v[64:67]
	s_nop 7
	v_mul_f32_e32 v64, v64, v72
	v_mul_f32_e32 v65, v65, v72
	v_cvt_pk_bf16_f32 v64, v64, v65
	v_mul_f32_e32 v65, v66, v72
	v_mul_f32_e32 v66, v67, v72
	v_cvt_pk_bf16_f32 v65, v65, v66
	global_store_dwordx2 v[62:63], v[64:65], off
	ds_read_b128 v[64:67], v0 offset:48192
	ds_read_b128 v[68:71], v0 offset:48256
	s_waitcnt lgkmcnt(1)
	v_mfma_f32_16x16x32_bf16 v[64:67], v[64:67], v[46:49], 0
	s_waitcnt lgkmcnt(0)
	v_mfma_f32_16x16x32_bf16 v[64:67], v[68:71], v[58:61], v[64:67]
	ds_read_b128 v[68:71], v0 offset:48320
	s_waitcnt lgkmcnt(0)
	v_mfma_f32_16x16x32_bf16 v[64:67], v[68:71], v[54:57], v[64:67]
	ds_read_b128 v[68:71], v0 offset:48384
	s_waitcnt lgkmcnt(0)
	v_mfma_f32_16x16x32_bf16 v[64:67], v[68:71], v[42:45], v[64:67]
	ds_read_b128 v[68:71], v0 offset:48448
	s_waitcnt lgkmcnt(0)
	v_mfma_f32_16x16x32_bf16 v[64:67], v[68:71], v[50:53], v[64:67]
	s_nop 7
	v_mul_f32_e32 v64, v64, v72
	v_mul_f32_e32 v65, v65, v72
	v_cvt_pk_bf16_f32 v64, v64, v65
	v_mul_f32_e32 v65, v66, v72
	v_mul_f32_e32 v66, v67, v72
	v_cvt_pk_bf16_f32 v65, v65, v66
	global_store_dwordx2 v[62:63], v[64:65], off offset:32
	ds_read_b128 v[64:67], v0 offset:57152
	ds_read_b128 v[68:71], v0 offset:57216
	s_waitcnt lgkmcnt(1)
	v_mfma_f32_16x16x32_bf16 v[64:67], v[64:67], v[46:49], 0
	s_waitcnt lgkmcnt(0)
	v_mfma_f32_16x16x32_bf16 v[64:67], v[68:71], v[58:61], v[64:67]
	ds_read_b128 v[68:71], v0 offset:57280
	s_waitcnt lgkmcnt(0)
	v_mfma_f32_16x16x32_bf16 v[64:67], v[68:71], v[54:57], v[64:67]
	ds_read_b128 v[68:71], v0 offset:57344
	s_waitcnt lgkmcnt(0)
	v_mfma_f32_16x16x32_bf16 v[64:67], v[68:71], v[42:45], v[64:67]
	ds_read_b128 v[68:71], v0 offset:57408
	s_waitcnt lgkmcnt(0)
	v_mfma_f32_16x16x32_bf16 v[64:67], v[68:71], v[50:53], v[64:67]
	s_nop 7
	v_mul_f32_e32 v64, v72, v64
	v_mul_f32_e32 v65, v72, v65
	v_cvt_pk_bf16_f32 v64, v64, v65
	v_mul_f32_e32 v65, v72, v66
	v_mul_f32_e32 v66, v72, v67
	v_cvt_pk_bf16_f32 v65, v65, v66
	global_store_dwordx2 v[62:63], v[64:65], off offset:64
	ds_read_b128 v[64:67], v133 offset:39232
	s_waitcnt lgkmcnt(0)
	v_mfma_f32_16x16x32_bf16 v[46:49], v[64:67], v[46:49], 0
	ds_read_b128 v[64:67], v133 offset:39296
	s_waitcnt lgkmcnt(0)
	v_mfma_f32_16x16x32_bf16 v[46:49], v[64:67], v[58:61], v[46:49]
	ds_read_b128 v[58:61], v133 offset:39360
	s_waitcnt lgkmcnt(0)
	v_mfma_f32_16x16x32_bf16 v[46:49], v[58:61], v[54:57], v[46:49]
	ds_read_b128 v[54:57], v133 offset:39424
	s_waitcnt lgkmcnt(0)
	v_mfma_f32_16x16x32_bf16 v[42:45], v[54:57], v[42:45], v[46:49]
	s_nop 4
	ds_read_b128 v[46:49], v133 offset:39488
	s_waitcnt lgkmcnt(0)
	v_mfma_f32_16x16x32_bf16 v[42:45], v[46:49], v[50:53], v[42:45]
	s_nop 7
	v_mul_f32_e32 v42, v72, v42
	v_mul_f32_e32 v43, v72, v43
	v_cvt_pk_bf16_f32 v42, v42, v43
	v_mul_f32_e32 v43, v72, v44
	v_mul_f32_e32 v44, v72, v45
	v_cvt_pk_bf16_f32 v43, v43, v44
	global_store_dwordx2 v[62:63], v[42:43], off offset:96
	ds_read_b128 v[42:45], v127 offset:6912
	ds_read_b128 v[46:49], v127 offset:6976
	s_waitcnt lgkmcnt(1)
	v_mfma_f32_16x16x32_bf16 v[42:45], v[42:45], v[38:41], 0
	s_waitcnt lgkmcnt(0)
	v_mfma_f32_16x16x32_bf16 v[50:53], v[46:49], v[34:37], v[42:45]
	s_nop 5
	ds_read_b128 v[42:45], v127 offset:7488
	ds_read_b128 v[46:49], v127 offset:7552
	s_waitcnt lgkmcnt(1)
	v_mfma_f32_16x16x32_bf16 v[42:45], v[42:45], v[38:41], 0
	s_waitcnt lgkmcnt(0)
	v_mfma_f32_16x16x32_bf16 v[54:57], v[46:49], v[34:37], v[42:45]
	s_nop 5
	ds_read_b128 v[42:45], v127 offset:11520
	ds_read_b128 v[46:49], v127 offset:11584
	s_waitcnt lgkmcnt(1)
	v_mfma_f32_16x16x32_bf16 v[42:45], v[42:45], v[38:41], 0
	s_waitcnt lgkmcnt(0)
	v_mfma_f32_16x16x32_bf16 v[58:61], v[46:49], v[34:37], v[42:45]
	s_nop 5
	ds_read_b128 v[42:45], v127 offset:12096
	ds_read_b128 v[46:49], v127 offset:12160
	s_waitcnt lgkmcnt(1)
	v_mfma_f32_16x16x32_bf16 v[42:45], v[42:45], v[38:41], 0
	s_waitcnt lgkmcnt(0)
	v_mfma_f32_16x16x32_bf16 v[62:65], v[46:49], v[34:37], v[42:45]
	s_nop 5
	ds_read_b128 v[42:45], v127 offset:16128
	ds_read_b128 v[46:49], v127 offset:16192
	s_waitcnt lgkmcnt(1)
	v_mfma_f32_16x16x32_bf16 v[42:45], v[42:45], v[38:41], 0
	s_waitcnt lgkmcnt(0)
	v_mfma_f32_16x16x32_bf16 v[66:69], v[46:49], v[34:37], v[42:45]
	s_nop 5
	ds_read_b128 v[42:45], v127 offset:16704
	ds_read_b128 v[46:49], v127 offset:16768
	s_waitcnt lgkmcnt(1)
	v_mfma_f32_16x16x32_bf16 v[42:45], v[42:45], v[38:41], 0
	s_waitcnt lgkmcnt(0)
	v_mfma_f32_16x16x32_bf16 v[70:73], v[46:49], v[34:37], v[42:45]
	s_nop 5
	ds_read_b128 v[42:45], v127 offset:20736
	ds_read_b128 v[46:49], v127 offset:20800
	s_waitcnt lgkmcnt(1)
	v_mfma_f32_16x16x32_bf16 v[42:45], v[42:45], v[38:41], 0
	s_waitcnt lgkmcnt(0)
	v_mfma_f32_16x16x32_bf16 v[46:49], v[46:49], v[34:37], v[42:45]
	s_nop 5
	ds_read_b128 v[42:45], v127 offset:21312
	ds_read_b128 v[74:77], v127 offset:21376
	s_waitcnt lgkmcnt(1)
	v_mfma_f32_16x16x32_bf16 v[42:45], v[42:45], v[38:41], 0
	s_waitcnt lgkmcnt(0)
	v_mfma_f32_16x16x32_bf16 v[42:45], v[74:77], v[34:37], v[42:45]
	ds_read_b128 v[74:77], v127 offset:25344
	ds_read_b128 v[78:81], v127 offset:25408
	s_waitcnt lgkmcnt(1)
	v_mfma_f32_16x16x32_bf16 v[74:77], v[74:77], v[38:41], 0
	s_waitcnt lgkmcnt(0)
	v_mfma_f32_16x16x32_bf16 v[74:77], v[78:81], v[34:37], v[74:77]
	ds_read_b128 v[78:81], v127 offset:25920
	ds_read_b128 v[82:85], v127 offset:25984
	s_waitcnt lgkmcnt(1)
	v_mfma_f32_16x16x32_bf16 v[38:41], v[78:81], v[38:41], 0
	s_waitcnt lgkmcnt(0)
	v_mfma_f32_16x16x32_bf16 v[34:37], v[82:85], v[34:37], v[38:41]
	s_nop 5
	v_cndmask_b32_e64 v38, v175, v50, s[24:25]
	v_cndmask_b32_e64 v39, v175, v51, s[26:27]
	v_max3_f32 v40, v38, s2, v39
	v_cndmask_b32_e64 v41, v175, v52, s[28:29]
	v_cndmask_b32_e64 v50, v175, v53, s[30:31]
	v_max3_f32 v40, v40, v41, v50
	v_cndmask_b32_e64 v51, v175, v54, s[34:35]
	v_cndmask_b32_e64 v52, v175, v55, s[36:37]
	v_max3_f32 v40, v40, v51, v52
	v_cndmask_b32_e64 v53, v175, v56, s[38:39]
	v_cndmask_b32_e64 v54, v175, v57, s[0:1]
	v_max3_f32 v40, v40, v53, v54
	v_cndmask_b32_e64 v55, v58, v175, s[22:23]
	v_cndmask_b32_e64 v56, v59, v175, s[22:23]
	v_max3_f32 v40, v40, v55, v56
	v_cndmask_b32_e64 v57, v60, v175, s[22:23]
	v_cndmask_b32_e64 v58, v61, v175, s[22:23]
	v_max3_f32 v40, v40, v57, v58
	v_cndmask_b32_e64 v59, v62, v175, s[22:23]
	v_cndmask_b32_e64 v60, v63, v175, s[22:23]
	v_max3_f32 v40, v40, v59, v60
	v_cndmask_b32_e64 v61, v64, v175, s[22:23]
	v_cndmask_b32_e64 v62, v65, v175, s[22:23]
	v_max3_f32 v40, v40, v61, v62
	v_cndmask_b32_e64 v63, v66, v175, s[44:45]
	v_cndmask_b32_e64 v64, v67, v175, s[44:45]
	v_max3_f32 v40, v40, v63, v64
	v_cndmask_b32_e64 v65, v68, v175, s[44:45]
	v_cndmask_b32_e64 v66, v69, v175, s[44:45]
	v_max3_f32 v40, v40, v65, v66
	v_cndmask_b32_e64 v67, v70, v175, s[44:45]
	v_cndmask_b32_e64 v68, v71, v175, s[44:45]
	v_max3_f32 v40, v40, v67, v68
	v_cndmask_b32_e64 v69, v72, v175, s[44:45]
	v_cndmask_b32_e64 v70, v73, v175, s[44:45]
	v_max3_f32 v40, v40, v69, v70
	v_max3_f32 v40, v40, v46, v47
	v_max3_f32 v40, v40, v48, v49
	v_max3_f32 v40, v40, v42, v43
	v_max3_f32 v40, v40, v44, v45
	v_cndmask_b32_e64 v71, v175, v74, s[4:5]
	v_cndmask_b32_e64 v72, v175, v75, s[6:7]
	v_max3_f32 v40, v40, v71, v72
	v_cndmask_b32_e64 v73, v175, v76, s[8:9]
	v_cndmask_b32_e64 v74, v175, v77, s[10:11]
	v_max3_f32 v40, v40, v73, v74
	v_cndmask_b32_e64 v34, v175, v34, s[12:13]
	v_cndmask_b32_e64 v35, v175, v35, s[14:15]
	v_max3_f32 v40, v40, v34, v35
	v_cndmask_b32_e64 v36, v175, v36, s[16:17]
	v_cndmask_b32_e64 v37, v175, v37, s[18:19]
	v_max3_f32 v40, v40, v36, v37
	v_mov_b32_e32 v75, v40
	s_nop 1
	v_permlane16_swap_b32_e32 v40, v75
	s_waitcnt lgkmcnt(0)
	v_max_f32_e32 v75, v75, v75
	v_max_f32_e32 v40, v40, v75
	v_mov_b32_e32 v75, v40
	s_nop 1
	v_permlane32_swap_b32_e32 v40, v75
	s_waitcnt lgkmcnt(0)
	v_max3_f32 v40, v40, v75, v99
	v_sub_f32_e32 v38, v38, v40
	v_exp_f32_e32 v38, v38
	v_sub_f32_e32 v39, v39, v40
	v_exp_f32_e32 v39, v39
	v_sub_f32_e32 v41, v41, v40
	v_exp_f32_e32 v41, v41
	v_sub_f32_e32 v50, v50, v40
	v_exp_f32_e32 v50, v50
	v_sub_f32_e32 v51, v51, v40
	v_add_f32_e32 v75, 0, v38
	v_exp_f32_e32 v51, v51
	v_sub_f32_e32 v52, v52, v40
	v_add_f32_e32 v75, v39, v75
	v_exp_f32_e32 v52, v52
	v_sub_f32_e32 v53, v53, v40
	v_add_f32_e32 v75, v41, v75
	v_exp_f32_e32 v53, v53
	v_sub_f32_e32 v54, v54, v40
	v_add_f32_e32 v75, v50, v75
	v_exp_f32_e32 v54, v54
	v_sub_f32_e32 v55, v55, v40
	v_add_f32_e32 v75, v51, v75
	v_exp_f32_e32 v55, v55
	v_sub_f32_e32 v56, v56, v40
	v_add_f32_e32 v75, v52, v75
	v_exp_f32_e32 v56, v56
	v_sub_f32_e32 v57, v57, v40
	v_add_f32_e32 v75, v53, v75
	v_exp_f32_e32 v57, v57
	v_sub_f32_e32 v58, v58, v40
	v_add_f32_e32 v75, v54, v75
	v_exp_f32_e32 v58, v58
	v_sub_f32_e32 v59, v59, v40
	v_add_f32_e32 v75, v55, v75
	v_exp_f32_e32 v59, v59
	v_sub_f32_e32 v60, v60, v40
	v_add_f32_e32 v75, v56, v75
	v_exp_f32_e32 v60, v60
	v_sub_f32_e32 v61, v61, v40
	v_add_f32_e32 v75, v57, v75
	v_exp_f32_e32 v61, v61
	v_sub_f32_e32 v62, v62, v40
	v_add_f32_e32 v75, v58, v75
	v_exp_f32_e32 v62, v62
	v_sub_f32_e32 v63, v63, v40
	v_add_f32_e32 v75, v59, v75
	v_exp_f32_e32 v63, v63
	v_sub_f32_e32 v64, v64, v40
	v_add_f32_e32 v75, v60, v75
	v_exp_f32_e32 v64, v64
	v_sub_f32_e32 v65, v65, v40
	v_add_f32_e32 v75, v61, v75
	v_exp_f32_e32 v65, v65
	v_sub_f32_e32 v66, v66, v40
	v_add_f32_e32 v75, v62, v75
	v_exp_f32_e32 v66, v66
	v_sub_f32_e32 v67, v67, v40
	v_add_f32_e32 v75, v63, v75
	v_exp_f32_e32 v67, v67
	v_sub_f32_e32 v68, v68, v40
	v_add_f32_e32 v75, v64, v75
	v_exp_f32_e32 v68, v68
	v_sub_f32_e32 v69, v69, v40
	v_add_f32_e32 v75, v65, v75
	v_exp_f32_e32 v69, v69
	v_sub_f32_e32 v70, v70, v40
	v_add_f32_e32 v75, v66, v75
	v_exp_f32_e32 v70, v70
	v_sub_f32_e32 v46, v46, v40
	v_add_f32_e32 v75, v67, v75
	v_exp_f32_e32 v76, v46
	v_add_f32_e32 v75, v68, v75
	v_add_f32_e32 v75, v69, v75
	v_add_f32_e32 v75, v70, v75
	v_sub_f32_e32 v47, v47, v40
	v_add_f32_e32 v46, v76, v75
	v_exp_f32_e32 v75, v47
	v_sub_f32_e32 v47, v48, v40
	v_exp_f32_e32 v77, v47
	v_sub_f32_e32 v47, v49, v40
	v_exp_f32_e32 v78, v47
	v_sub_f32_e32 v42, v42, v40
	v_exp_f32_e32 v42, v42
	v_sub_f32_e32 v43, v43, v40
	v_add_f32_e32 v46, v75, v46
	v_exp_f32_e32 v43, v43
	v_sub_f32_e32 v44, v44, v40
	v_add_f32_e32 v46, v77, v46
	v_exp_f32_e32 v44, v44
	v_sub_f32_e32 v45, v45, v40
	v_add_f32_e32 v46, v78, v46
	v_exp_f32_e32 v45, v45
	v_sub_f32_e32 v47, v71, v40
	v_add_f32_e32 v46, v42, v46
	v_exp_f32_e32 v71, v47
	v_sub_f32_e32 v47, v72, v40
	v_add_f32_e32 v46, v43, v46
	v_exp_f32_e32 v72, v47
	v_sub_f32_e32 v47, v73, v40
	v_add_f32_e32 v46, v44, v46
	v_exp_f32_e32 v73, v47
	v_sub_f32_e32 v47, v74, v40
	v_add_f32_e32 v46, v45, v46
	v_exp_f32_e32 v74, v47
	v_sub_f32_e32 v34, v34, v40
	v_add_f32_e32 v46, v71, v46
	v_exp_f32_e32 v79, v34
	v_sub_f32_e32 v35, v35, v40
	v_add_f32_e32 v46, v72, v46
	v_exp_f32_e32 v80, v35
	v_sub_f32_e32 v35, v36, v40
	v_add_f32_e32 v46, v73, v46
	v_exp_f32_e32 v81, v35
	v_sub_f32_e32 v35, v37, v40
	v_add_f32_e32 v46, v74, v46
	v_exp_f32_e32 v82, v35
	v_add_f32_e32 v34, v79, v46
	v_add_f32_e32 v34, v80, v34
	v_add_f32_e32 v34, v81, v34
	v_add_f32_e32 v34, v82, v34
	v_mov_b32_e32 v35, v34
	s_nop 1
	v_permlane16_swap_b32_e32 v34, v35
	v_cvt_pk_bf16_f32 v38, v38, v39
	v_cvt_pk_bf16_f32 v39, v41, v50
	s_waitcnt lgkmcnt(0)
	v_add_f32_e32 v34, v34, v35
	v_mov_b32_e32 v35, v34
	s_nop 1
	v_permlane32_swap_b32_e32 v34, v35
	s_waitcnt lgkmcnt(0)
	v_add_f32_e32 v34, v34, v35
	v_sub_f32_e32 v35, v99, v40
	v_exp_f32_e32 v35, v35
	v_cvt_pk_bf16_f32 v40, v51, v52
	v_cvt_pk_bf16_f32 v41, v53, v54
	v_cvt_pk_bf16_f32 v50, v55, v56
	v_cvt_pk_bf16_f32 v51, v57, v58
	v_cvt_pk_bf16_f32 v52, v59, v60
	s_nop 0
	v_add_f32_e32 v83, v35, v34
	v_div_scale_f32 v54, s[52:53], v83, v83, 1.0
	v_rcp_f32_e32 v55, v54
	v_cvt_pk_bf16_f32 v53, v61, v62
	v_cvt_pk_bf16_f32 v46, v63, v64
	v_cvt_pk_bf16_f32 v47, v65, v66
	v_cvt_pk_bf16_f32 v48, v67, v68
	v_cvt_pk_bf16_f32 v49, v69, v70
	s_nop 0
	v_fma_f32 v56, -v54, v55, 1.0
	v_fmac_f32_e32 v55, v56, v55
	v_div_scale_f32 v56, vcc, 1.0, v83, 1.0
	v_mul_f32_e32 v57, v56, v55
	v_fma_f32 v58, -v54, v57, v56
	v_fmac_f32_e32 v57, v58, v55
	v_fma_f32 v54, -v54, v57, v56
	v_cvt_pk_bf16_f32 v34, v76, v75
	v_cvt_pk_bf16_f32 v35, v77, v78
	v_cvt_pk_bf16_f32 v36, v42, v43
	v_cvt_pk_bf16_f32 v37, v44, v45
	v_cvt_pk_bf16_f32 v42, v71, v72
	v_cvt_pk_bf16_f32 v43, v73, v74
	v_cvt_pk_bf16_f32 v44, v79, v80
	v_cvt_pk_bf16_f32 v45, v81, v82
	v_div_fmas_f32 v54, v54, v55, v57
	ds_read_b128 v[56:59], v0 offset:39264
	ds_read_b128 v[60:63], v0 offset:39328
	s_waitcnt lgkmcnt(1)
	v_mfma_f32_16x16x32_bf16 v[56:59], v[56:59], v[38:41], 0
	v_div_fixup_f32 v64, v54, v83, 1.0
	v_mad_i64_i32 v[54:55], s[52:53], v108, s33, v[100:101]
	s_waitcnt lgkmcnt(0)
	v_mfma_f32_16x16x32_bf16 v[56:59], v[60:63], v[50:53], v[56:59]
	ds_read_b128 v[60:63], v0 offset:39392
	s_waitcnt lgkmcnt(0)
	v_mfma_f32_16x16x32_bf16 v[56:59], v[60:63], v[46:49], v[56:59]
	ds_read_b128 v[60:63], v0 offset:39456
	s_waitcnt lgkmcnt(0)
	v_mfma_f32_16x16x32_bf16 v[56:59], v[60:63], v[34:37], v[56:59]
	ds_read_b128 v[60:63], v0 offset:39520
	s_waitcnt lgkmcnt(0)
	v_mfma_f32_16x16x32_bf16 v[56:59], v[60:63], v[42:45], v[56:59]
	s_nop 7
	v_mul_f32_e32 v56, v56, v64
	v_mul_f32_e32 v57, v57, v64
	v_cvt_pk_bf16_f32 v56, v56, v57
	v_mul_f32_e32 v57, v58, v64
	v_mul_f32_e32 v58, v59, v64
	v_cvt_pk_bf16_f32 v57, v57, v58
	global_store_dwordx2 v[54:55], v[56:57], off
	ds_read_b128 v[56:59], v0 offset:48224
	ds_read_b128 v[60:63], v0 offset:48288
	s_waitcnt lgkmcnt(1)
	v_mfma_f32_16x16x32_bf16 v[56:59], v[56:59], v[38:41], 0
	s_waitcnt lgkmcnt(0)
	v_mfma_f32_16x16x32_bf16 v[56:59], v[60:63], v[50:53], v[56:59]
	ds_read_b128 v[60:63], v0 offset:48352
	s_waitcnt lgkmcnt(0)
	v_mfma_f32_16x16x32_bf16 v[56:59], v[60:63], v[46:49], v[56:59]
	ds_read_b128 v[60:63], v0 offset:48416
	s_waitcnt lgkmcnt(0)
	v_mfma_f32_16x16x32_bf16 v[56:59], v[60:63], v[34:37], v[56:59]
	ds_read_b128 v[60:63], v0 offset:48480
	s_waitcnt lgkmcnt(0)
	v_mfma_f32_16x16x32_bf16 v[56:59], v[60:63], v[42:45], v[56:59]
	s_nop 7
	v_mul_f32_e32 v56, v56, v64
	v_mul_f32_e32 v57, v57, v64
	v_cvt_pk_bf16_f32 v56, v56, v57
	v_mul_f32_e32 v57, v58, v64
	v_mul_f32_e32 v58, v59, v64
	v_cvt_pk_bf16_f32 v57, v57, v58
	global_store_dwordx2 v[54:55], v[56:57], off offset:32
	ds_read_b128 v[56:59], v0 offset:57184
	ds_read_b128 v[60:63], v0 offset:57248
	s_waitcnt lgkmcnt(1)
	v_mfma_f32_16x16x32_bf16 v[56:59], v[56:59], v[38:41], 0
	s_waitcnt lgkmcnt(0)
	v_mfma_f32_16x16x32_bf16 v[56:59], v[60:63], v[50:53], v[56:59]
	ds_read_b128 v[60:63], v0 offset:57312
	s_waitcnt lgkmcnt(0)
	v_mfma_f32_16x16x32_bf16 v[56:59], v[60:63], v[46:49], v[56:59]
	ds_read_b128 v[60:63], v0 offset:57376
	s_waitcnt lgkmcnt(0)
	v_mfma_f32_16x16x32_bf16 v[56:59], v[60:63], v[34:37], v[56:59]
	ds_read_b128 v[60:63], v0 offset:57440
	s_waitcnt lgkmcnt(0)
	v_mfma_f32_16x16x32_bf16 v[56:59], v[60:63], v[42:45], v[56:59]
	s_nop 7
	v_mul_f32_e32 v56, v64, v56
	v_mul_f32_e32 v57, v64, v57
	v_cvt_pk_bf16_f32 v56, v56, v57
	v_mul_f32_e32 v57, v64, v58
	v_mul_f32_e32 v58, v64, v59
	v_cvt_pk_bf16_f32 v57, v57, v58
	global_store_dwordx2 v[54:55], v[56:57], off offset:64
	ds_read_b128 v[56:59], v133 offset:39264
	s_waitcnt lgkmcnt(0)
	v_mfma_f32_16x16x32_bf16 v[38:41], v[56:59], v[38:41], 0
	ds_read_b128 v[56:59], v133 offset:39328
	s_waitcnt lgkmcnt(0)
	v_mfma_f32_16x16x32_bf16 v[38:41], v[56:59], v[50:53], v[38:41]
	ds_read_b128 v[50:53], v133 offset:39392
	s_waitcnt lgkmcnt(0)
	v_mfma_f32_16x16x32_bf16 v[38:41], v[50:53], v[46:49], v[38:41]
	ds_read_b128 v[46:49], v133 offset:39456
	s_waitcnt lgkmcnt(0)
	v_mfma_f32_16x16x32_bf16 v[34:37], v[46:49], v[34:37], v[38:41]
	s_nop 4
	ds_read_b128 v[38:41], v133 offset:39520
	s_waitcnt lgkmcnt(0)
	v_mfma_f32_16x16x32_bf16 v[34:37], v[38:41], v[42:45], v[34:37]
	s_nop 7
	v_mul_f32_e32 v34, v64, v34
	v_mul_f32_e32 v35, v64, v35
	v_cvt_pk_bf16_f32 v34, v34, v35
	v_mul_f32_e32 v35, v64, v36
	v_mul_f32_e32 v36, v64, v37
	v_cvt_pk_bf16_f32 v35, v35, v36
	global_store_dwordx2 v[54:55], v[34:35], off offset:96
	ds_read_b128 v[34:37], v127 offset:9216
	ds_read_b128 v[38:41], v127 offset:9280
	s_waitcnt lgkmcnt(1)
	v_mfma_f32_16x16x32_bf16 v[34:37], v[34:37], v[30:33], 0
	s_waitcnt lgkmcnt(0)
	v_mfma_f32_16x16x32_bf16 v[50:53], v[38:41], v[26:29], v[34:37]
	s_nop 5
	ds_read_b128 v[34:37], v127 offset:9792
	ds_read_b128 v[38:41], v127 offset:9856
	s_waitcnt lgkmcnt(1)
	v_mfma_f32_16x16x32_bf16 v[34:37], v[34:37], v[30:33], 0
	s_waitcnt lgkmcnt(0)
	v_mfma_f32_16x16x32_bf16 v[54:57], v[38:41], v[26:29], v[34:37]
	s_nop 5
	ds_read_b128 v[34:37], v127 offset:13824
	ds_read_b128 v[38:41], v127 offset:13888
	s_waitcnt lgkmcnt(1)
	v_mfma_f32_16x16x32_bf16 v[34:37], v[34:37], v[30:33], 0
	s_waitcnt lgkmcnt(0)
	v_mfma_f32_16x16x32_bf16 v[58:61], v[38:41], v[26:29], v[34:37]
	s_nop 5
	ds_read_b128 v[34:37], v127 offset:14400
	ds_read_b128 v[38:41], v127 offset:14464
	s_waitcnt lgkmcnt(1)
	v_mfma_f32_16x16x32_bf16 v[34:37], v[34:37], v[30:33], 0
	s_waitcnt lgkmcnt(0)
	v_mfma_f32_16x16x32_bf16 v[62:65], v[38:41], v[26:29], v[34:37]
	s_nop 5
	ds_read_b128 v[34:37], v127 offset:18432
	ds_read_b128 v[38:41], v127 offset:18496
	s_waitcnt lgkmcnt(1)
	v_mfma_f32_16x16x32_bf16 v[34:37], v[34:37], v[30:33], 0
	s_waitcnt lgkmcnt(0)
	v_mfma_f32_16x16x32_bf16 v[46:49], v[38:41], v[26:29], v[34:37]
	s_nop 5
	ds_read_b128 v[34:37], v127 offset:19008
	ds_read_b128 v[38:41], v127 offset:19072
	s_waitcnt lgkmcnt(1)
	v_mfma_f32_16x16x32_bf16 v[34:37], v[34:37], v[30:33], 0
	s_waitcnt lgkmcnt(0)
	v_mfma_f32_16x16x32_bf16 v[42:45], v[38:41], v[26:29], v[34:37]
	s_nop 5
	ds_read_b128 v[34:37], v127 offset:23040
	ds_read_b128 v[38:41], v127 offset:23104
	s_waitcnt lgkmcnt(1)
	v_mfma_f32_16x16x32_bf16 v[34:37], v[34:37], v[30:33], 0
	s_waitcnt lgkmcnt(0)
	v_mfma_f32_16x16x32_bf16 v[38:41], v[38:41], v[26:29], v[34:37]
	s_nop 5
	ds_read_b128 v[34:37], v127 offset:23616
	ds_read_b128 v[66:69], v127 offset:23680
	s_waitcnt lgkmcnt(1)
	v_mfma_f32_16x16x32_bf16 v[34:37], v[34:37], v[30:33], 0
	s_waitcnt lgkmcnt(0)
	v_mfma_f32_16x16x32_bf16 v[34:37], v[66:69], v[26:29], v[34:37]
	ds_read_b128 v[66:69], v127 offset:27648
	ds_read_b128 v[70:73], v127 offset:27712
	s_waitcnt lgkmcnt(1)
	v_mfma_f32_16x16x32_bf16 v[66:69], v[66:69], v[30:33], 0
	s_waitcnt lgkmcnt(0)
	v_mfma_f32_16x16x32_bf16 v[66:69], v[70:73], v[26:29], v[66:69]
	ds_read_b128 v[70:73], v127 offset:28224
	ds_read_b128 v[74:77], v127 offset:28288
	s_waitcnt lgkmcnt(1)
	v_mfma_f32_16x16x32_bf16 v[30:33], v[70:73], v[30:33], 0
	s_waitcnt lgkmcnt(0)
	v_mfma_f32_16x16x32_bf16 v[26:29], v[74:77], v[26:29], v[30:33]
	s_nop 5
	v_cndmask_b32_e64 v30, v175, v50, s[24:25]
	v_cndmask_b32_e64 v31, v175, v51, s[26:27]
	v_max3_f32 v32, v30, s2, v31
	v_cndmask_b32_e64 v33, v175, v52, s[28:29]
	v_cndmask_b32_e64 v50, v175, v53, s[30:31]
	v_max3_f32 v32, v32, v33, v50
	v_cndmask_b32_e64 v51, v175, v54, s[34:35]
	v_cndmask_b32_e64 v52, v175, v55, s[36:37]
	v_max3_f32 v32, v32, v51, v52
	v_cndmask_b32_e64 v53, v175, v56, s[38:39]
	v_cndmask_b32_e64 v54, v175, v57, s[0:1]
	v_max3_f32 v32, v32, v53, v54
	v_cndmask_b32_e64 v55, v58, v175, s[22:23]
	v_cndmask_b32_e64 v56, v59, v175, s[22:23]
	v_max3_f32 v32, v32, v55, v56
	v_cndmask_b32_e64 v57, v60, v175, s[22:23]
	v_cndmask_b32_e64 v58, v61, v175, s[22:23]
	v_max3_f32 v32, v32, v57, v58
	v_cndmask_b32_e64 v59, v62, v175, s[22:23]
	v_cndmask_b32_e64 v60, v63, v175, s[22:23]
	v_max3_f32 v32, v32, v59, v60
	v_cndmask_b32_e64 v61, v64, v175, s[22:23]
	v_cndmask_b32_e64 v62, v65, v175, s[22:23]
	v_max3_f32 v32, v32, v61, v62
	v_max3_f32 v32, v32, v46, v47
	v_max3_f32 v32, v32, v48, v49
	v_max3_f32 v32, v32, v42, v43
	v_max3_f32 v32, v32, v44, v45
	v_max3_f32 v32, v32, v38, v39
	v_max3_f32 v32, v32, v40, v41
	v_max3_f32 v32, v32, v34, v35
	v_max3_f32 v32, v32, v36, v37
	v_cndmask_b32_e64 v63, v175, v66, s[4:5]
	v_cndmask_b32_e64 v64, v175, v67, s[6:7]
	v_max3_f32 v32, v32, v63, v64
	v_cndmask_b32_e64 v65, v175, v68, s[8:9]
	v_cndmask_b32_e64 v66, v175, v69, s[10:11]
	v_max3_f32 v32, v32, v65, v66
	v_cndmask_b32_e64 v26, v175, v26, s[12:13]
	v_cndmask_b32_e64 v27, v175, v27, s[14:15]
	v_max3_f32 v32, v32, v26, v27
	v_cndmask_b32_e64 v28, v175, v28, s[16:17]
	v_cndmask_b32_e64 v29, v175, v29, s[18:19]
	v_max3_f32 v32, v32, v28, v29
	v_mov_b32_e32 v67, v32
	s_nop 1
	v_permlane16_swap_b32_e32 v32, v67
	s_waitcnt lgkmcnt(0)
	v_max_f32_e32 v67, v67, v67
	v_max_f32_e32 v32, v32, v67
	v_mov_b32_e32 v67, v32
	s_nop 1
	v_permlane32_swap_b32_e32 v32, v67
	s_waitcnt lgkmcnt(0)
	v_max3_f32 v32, v32, v67, v99
	v_sub_f32_e32 v30, v30, v32
	v_exp_f32_e32 v30, v30
	v_sub_f32_e32 v31, v31, v32
	v_exp_f32_e32 v31, v31
	v_sub_f32_e32 v33, v33, v32
	v_exp_f32_e32 v33, v33
	v_sub_f32_e32 v50, v50, v32
	v_exp_f32_e32 v50, v50
	v_sub_f32_e32 v51, v51, v32
	v_add_f32_e32 v67, 0, v30
	v_exp_f32_e32 v51, v51
	v_sub_f32_e32 v52, v52, v32
	v_add_f32_e32 v67, v31, v67
	v_exp_f32_e32 v52, v52
	v_sub_f32_e32 v53, v53, v32
	v_add_f32_e32 v67, v33, v67
	v_exp_f32_e32 v53, v53
	v_sub_f32_e32 v54, v54, v32
	v_add_f32_e32 v67, v50, v67
	v_exp_f32_e32 v54, v54
	v_sub_f32_e32 v55, v55, v32
	v_add_f32_e32 v67, v51, v67
	v_exp_f32_e32 v55, v55
	v_sub_f32_e32 v56, v56, v32
	v_add_f32_e32 v67, v52, v67
	v_exp_f32_e32 v56, v56
	v_sub_f32_e32 v57, v57, v32
	v_add_f32_e32 v67, v53, v67
	v_exp_f32_e32 v57, v57
	v_sub_f32_e32 v58, v58, v32
	v_add_f32_e32 v67, v54, v67
	v_exp_f32_e32 v58, v58
	v_sub_f32_e32 v59, v59, v32
	v_add_f32_e32 v67, v55, v67
	v_exp_f32_e32 v59, v59
	v_sub_f32_e32 v60, v60, v32
	v_add_f32_e32 v67, v56, v67
	v_exp_f32_e32 v60, v60
	v_sub_f32_e32 v61, v61, v32
	v_add_f32_e32 v67, v57, v67
	v_exp_f32_e32 v61, v61
	v_sub_f32_e32 v62, v62, v32
	v_add_f32_e32 v67, v58, v67
	v_exp_f32_e32 v62, v62
	v_sub_f32_e32 v46, v46, v32
	v_add_f32_e32 v67, v59, v67
	v_exp_f32_e32 v46, v46
	v_sub_f32_e32 v47, v47, v32
	v_add_f32_e32 v67, v60, v67
	v_exp_f32_e32 v47, v47
	v_sub_f32_e32 v48, v48, v32
	v_add_f32_e32 v67, v61, v67
	v_exp_f32_e32 v48, v48
	v_sub_f32_e32 v49, v49, v32
	v_add_f32_e32 v67, v62, v67
	v_exp_f32_e32 v49, v49
	v_sub_f32_e32 v42, v42, v32
	v_add_f32_e32 v67, v46, v67
	v_exp_f32_e32 v68, v42
	v_add_f32_e32 v67, v47, v67
	v_add_f32_e32 v67, v48, v67
	v_add_f32_e32 v67, v49, v67
	v_sub_f32_e32 v43, v43, v32
	v_add_f32_e32 v42, v68, v67
	v_exp_f32_e32 v67, v43
	v_sub_f32_e32 v43, v44, v32
	v_exp_f32_e32 v69, v43
	v_sub_f32_e32 v43, v45, v32
	v_exp_f32_e32 v70, v43
	v_sub_f32_e32 v38, v38, v32
	v_exp_f32_e32 v71, v38
	v_sub_f32_e32 v39, v39, v32
	v_add_f32_e32 v42, v67, v42
	v_exp_f32_e32 v72, v39
	v_sub_f32_e32 v39, v40, v32
	v_add_f32_e32 v42, v69, v42
	v_exp_f32_e32 v73, v39
	v_sub_f32_e32 v39, v41, v32
	v_add_f32_e32 v42, v70, v42
	v_exp_f32_e32 v74, v39
	v_sub_f32_e32 v34, v34, v32
	v_add_f32_e32 v38, v71, v42
	v_exp_f32_e32 v34, v34
	v_sub_f32_e32 v35, v35, v32
	v_add_f32_e32 v38, v72, v38
	v_exp_f32_e32 v35, v35
	v_sub_f32_e32 v36, v36, v32
	v_add_f32_e32 v38, v73, v38
	v_exp_f32_e32 v36, v36
	v_sub_f32_e32 v37, v37, v32
	v_add_f32_e32 v38, v74, v38
	v_exp_f32_e32 v37, v37
	v_sub_f32_e32 v39, v63, v32
	v_add_f32_e32 v38, v34, v38
	v_exp_f32_e32 v63, v39
	v_sub_f32_e32 v39, v64, v32
	v_add_f32_e32 v38, v35, v38
	v_exp_f32_e32 v64, v39
	v_sub_f32_e32 v39, v65, v32
	v_add_f32_e32 v38, v36, v38
	v_exp_f32_e32 v65, v39
	v_sub_f32_e32 v39, v66, v32
	v_add_f32_e32 v38, v37, v38
	v_exp_f32_e32 v66, v39
	v_sub_f32_e32 v26, v26, v32
	v_add_f32_e32 v38, v63, v38
	v_exp_f32_e32 v75, v26
	v_sub_f32_e32 v27, v27, v32
	v_add_f32_e32 v38, v64, v38
	v_exp_f32_e32 v76, v27
	v_sub_f32_e32 v27, v28, v32
	v_add_f32_e32 v38, v65, v38
	v_exp_f32_e32 v77, v27
	v_sub_f32_e32 v27, v29, v32
	v_add_f32_e32 v38, v66, v38
	v_exp_f32_e32 v78, v27
	v_add_f32_e32 v26, v75, v38
	v_add_f32_e32 v26, v76, v26
	v_add_f32_e32 v26, v77, v26
	v_add_f32_e32 v26, v78, v26
	v_mov_b32_e32 v27, v26
	s_nop 1
	v_permlane16_swap_b32_e32 v26, v27
	v_cvt_pk_bf16_f32 v30, v30, v31
	v_cvt_pk_bf16_f32 v31, v33, v50
	s_waitcnt lgkmcnt(0)
	v_add_f32_e32 v26, v26, v27
	v_mov_b32_e32 v27, v26
	s_nop 1
	v_permlane32_swap_b32_e32 v26, v27
	s_waitcnt lgkmcnt(0)
	v_add_f32_e32 v26, v26, v27
	v_sub_f32_e32 v27, v99, v32
	v_exp_f32_e32 v27, v27
	v_cvt_pk_bf16_f32 v32, v51, v52
	v_cvt_pk_bf16_f32 v33, v53, v54
	v_cvt_pk_bf16_f32 v42, v55, v56
	v_cvt_pk_bf16_f32 v43, v57, v58
	v_cvt_pk_bf16_f32 v44, v59, v60
	s_nop 0
	v_add_f32_e32 v79, v27, v26
	v_cvt_pk_bf16_f32 v45, v61, v62
	v_cvt_pk_bf16_f32 v38, v46, v47
	v_div_scale_f32 v46, s[52:53], v79, v79, 1.0
	v_rcp_f32_e32 v47, v46
	v_cvt_pk_bf16_f32 v39, v48, v49
	v_cvt_pk_bf16_f32 v40, v68, v67
	v_cvt_pk_bf16_f32 v41, v69, v70
	v_cvt_pk_bf16_f32 v26, v71, v72
	v_cvt_pk_bf16_f32 v27, v73, v74
	s_nop 0
	v_fma_f32 v48, -v46, v47, 1.0
	v_fmac_f32_e32 v47, v48, v47
	v_div_scale_f32 v48, vcc, 1.0, v79, 1.0
	v_mul_f32_e32 v49, v48, v47
	v_fma_f32 v50, -v46, v49, v48
	v_fmac_f32_e32 v49, v50, v47
	v_fma_f32 v46, -v46, v49, v48
	v_cvt_pk_bf16_f32 v28, v34, v35
	v_cvt_pk_bf16_f32 v29, v36, v37
	v_cvt_pk_bf16_f32 v34, v63, v64
	v_cvt_pk_bf16_f32 v35, v65, v66
	v_cvt_pk_bf16_f32 v36, v75, v76
	v_cvt_pk_bf16_f32 v37, v77, v78
	v_div_fmas_f32 v46, v46, v47, v49
	ds_read_b128 v[48:51], v0 offset:39296
	ds_read_b128 v[52:55], v0 offset:39360
	s_waitcnt lgkmcnt(1)
	v_mfma_f32_16x16x32_bf16 v[48:51], v[48:51], v[30:33], 0
	v_div_fixup_f32 v56, v46, v79, 1.0
	v_mad_i64_i32 v[46:47], s[52:53], v106, s33, v[100:101]
	s_waitcnt lgkmcnt(0)
	v_mfma_f32_16x16x32_bf16 v[48:51], v[52:55], v[42:45], v[48:51]
	ds_read_b128 v[52:55], v0 offset:39424
	s_waitcnt lgkmcnt(0)
	v_mfma_f32_16x16x32_bf16 v[48:51], v[52:55], v[38:41], v[48:51]
	ds_read_b128 v[52:55], v0 offset:39488
	s_waitcnt lgkmcnt(0)
	v_mfma_f32_16x16x32_bf16 v[48:51], v[52:55], v[26:29], v[48:51]
	ds_read_b128 v[52:55], v0 offset:39552
	s_waitcnt lgkmcnt(0)
	v_mfma_f32_16x16x32_bf16 v[48:51], v[52:55], v[34:37], v[48:51]
	s_nop 7
	v_mul_f32_e32 v48, v48, v56
	v_mul_f32_e32 v49, v49, v56
	v_cvt_pk_bf16_f32 v48, v48, v49
	v_mul_f32_e32 v49, v50, v56
	v_mul_f32_e32 v50, v51, v56
	v_cvt_pk_bf16_f32 v49, v49, v50
	global_store_dwordx2 v[46:47], v[48:49], off
	ds_read_b128 v[48:51], v0 offset:48256
	ds_read_b128 v[52:55], v0 offset:48320
	s_waitcnt lgkmcnt(1)
	v_mfma_f32_16x16x32_bf16 v[48:51], v[48:51], v[30:33], 0
	s_waitcnt lgkmcnt(0)
	v_mfma_f32_16x16x32_bf16 v[48:51], v[52:55], v[42:45], v[48:51]
	ds_read_b128 v[52:55], v0 offset:48384
	s_waitcnt lgkmcnt(0)
	v_mfma_f32_16x16x32_bf16 v[48:51], v[52:55], v[38:41], v[48:51]
	ds_read_b128 v[52:55], v0 offset:48448
	s_waitcnt lgkmcnt(0)
	v_mfma_f32_16x16x32_bf16 v[48:51], v[52:55], v[26:29], v[48:51]
	ds_read_b128 v[52:55], v0 offset:48512
	s_waitcnt lgkmcnt(0)
	v_mfma_f32_16x16x32_bf16 v[48:51], v[52:55], v[34:37], v[48:51]
	s_nop 7
	v_mul_f32_e32 v48, v48, v56
	v_mul_f32_e32 v49, v49, v56
	v_cvt_pk_bf16_f32 v48, v48, v49
	v_mul_f32_e32 v49, v50, v56
	v_mul_f32_e32 v50, v51, v56
	v_cvt_pk_bf16_f32 v49, v49, v50
	global_store_dwordx2 v[46:47], v[48:49], off offset:32
	ds_read_b128 v[48:51], v0 offset:57216
	ds_read_b128 v[52:55], v0 offset:57280
	s_waitcnt lgkmcnt(1)
	v_mfma_f32_16x16x32_bf16 v[48:51], v[48:51], v[30:33], 0
	s_waitcnt lgkmcnt(0)
	v_mfma_f32_16x16x32_bf16 v[48:51], v[52:55], v[42:45], v[48:51]
	ds_read_b128 v[52:55], v0 offset:57344
	s_waitcnt lgkmcnt(0)
	v_mfma_f32_16x16x32_bf16 v[48:51], v[52:55], v[38:41], v[48:51]
	ds_read_b128 v[52:55], v0 offset:57408
	s_waitcnt lgkmcnt(0)
	v_mfma_f32_16x16x32_bf16 v[48:51], v[52:55], v[26:29], v[48:51]
	ds_read_b128 v[52:55], v0 offset:57472
	s_waitcnt lgkmcnt(0)
	v_mfma_f32_16x16x32_bf16 v[48:51], v[52:55], v[34:37], v[48:51]
	s_nop 7
	v_mul_f32_e32 v48, v56, v48
	v_mul_f32_e32 v49, v56, v49
	v_cvt_pk_bf16_f32 v48, v48, v49
	v_mul_f32_e32 v49, v56, v50
	v_mul_f32_e32 v50, v56, v51
	v_cvt_pk_bf16_f32 v49, v49, v50
	global_store_dwordx2 v[46:47], v[48:49], off offset:64
	ds_read_b128 v[48:51], v133 offset:39296
	s_waitcnt lgkmcnt(0)
	v_mfma_f32_16x16x32_bf16 v[30:33], v[48:51], v[30:33], 0
	ds_read_b128 v[48:51], v133 offset:39360
	s_waitcnt lgkmcnt(0)
	v_mfma_f32_16x16x32_bf16 v[30:33], v[48:51], v[42:45], v[30:33]
	ds_read_b128 v[42:45], v133 offset:39424
	s_waitcnt lgkmcnt(0)
	v_mfma_f32_16x16x32_bf16 v[30:33], v[42:45], v[38:41], v[30:33]
	ds_read_b128 v[38:41], v133 offset:39488
	s_waitcnt lgkmcnt(0)
	v_mfma_f32_16x16x32_bf16 v[26:29], v[38:41], v[26:29], v[30:33]
	s_nop 4
	ds_read_b128 v[30:33], v133 offset:39552
	s_waitcnt lgkmcnt(0)
	v_mfma_f32_16x16x32_bf16 v[26:29], v[30:33], v[34:37], v[26:29]
	s_nop 7
	v_mul_f32_e32 v26, v56, v26
	v_mul_f32_e32 v27, v56, v27
	v_cvt_pk_bf16_f32 v26, v26, v27
	v_mul_f32_e32 v27, v56, v28
	v_mul_f32_e32 v28, v56, v29
	v_cvt_pk_bf16_f32 v27, v27, v28
	global_store_dwordx2 v[46:47], v[26:27], off offset:96
	ds_read_b128 v[26:29], v127 offset:11520
	ds_read_b128 v[30:33], v127 offset:11584
	s_waitcnt lgkmcnt(1)
	v_mfma_f32_16x16x32_bf16 v[26:29], v[26:29], v[22:25], 0
	s_waitcnt lgkmcnt(0)
	v_mfma_f32_16x16x32_bf16 v[42:45], v[30:33], v[18:21], v[26:29]
	s_nop 5
	ds_read_b128 v[26:29], v127 offset:12096
	ds_read_b128 v[30:33], v127 offset:12160
	s_waitcnt lgkmcnt(1)
	v_mfma_f32_16x16x32_bf16 v[26:29], v[26:29], v[22:25], 0
	s_waitcnt lgkmcnt(0)
	v_mfma_f32_16x16x32_bf16 v[46:49], v[30:33], v[18:21], v[26:29]
	s_nop 5
	ds_read_b128 v[26:29], v127 offset:16128
	ds_read_b128 v[30:33], v127 offset:16192
	s_waitcnt lgkmcnt(1)
	v_mfma_f32_16x16x32_bf16 v[26:29], v[26:29], v[22:25], 0
	s_waitcnt lgkmcnt(0)
	v_mfma_f32_16x16x32_bf16 v[50:53], v[30:33], v[18:21], v[26:29]
	s_nop 5
	ds_read_b128 v[26:29], v127 offset:16704
	ds_read_b128 v[30:33], v127 offset:16768
	s_waitcnt lgkmcnt(1)
	v_mfma_f32_16x16x32_bf16 v[26:29], v[26:29], v[22:25], 0
	s_waitcnt lgkmcnt(0)
	v_mfma_f32_16x16x32_bf16 v[54:57], v[30:33], v[18:21], v[26:29]
	s_nop 5
	ds_read_b128 v[26:29], v127 offset:20736
	ds_read_b128 v[30:33], v127 offset:20800
	s_waitcnt lgkmcnt(1)
	v_mfma_f32_16x16x32_bf16 v[26:29], v[26:29], v[22:25], 0
	s_waitcnt lgkmcnt(0)
	v_mfma_f32_16x16x32_bf16 v[38:41], v[30:33], v[18:21], v[26:29]
	s_nop 5
	ds_read_b128 v[26:29], v127 offset:21312
	ds_read_b128 v[30:33], v127 offset:21376
	s_waitcnt lgkmcnt(1)
	v_mfma_f32_16x16x32_bf16 v[26:29], v[26:29], v[22:25], 0
	s_waitcnt lgkmcnt(0)
	v_mfma_f32_16x16x32_bf16 v[34:37], v[30:33], v[18:21], v[26:29]
	s_nop 5
	ds_read_b128 v[26:29], v127 offset:25344
	ds_read_b128 v[30:33], v127 offset:25408
	s_waitcnt lgkmcnt(1)
	v_mfma_f32_16x16x32_bf16 v[26:29], v[26:29], v[22:25], 0
	s_waitcnt lgkmcnt(0)
	v_mfma_f32_16x16x32_bf16 v[30:33], v[30:33], v[18:21], v[26:29]
	s_nop 5
	ds_read_b128 v[26:29], v127 offset:25920
	ds_read_b128 v[58:61], v127 offset:25984
	s_waitcnt lgkmcnt(1)
	v_mfma_f32_16x16x32_bf16 v[26:29], v[26:29], v[22:25], 0
	s_waitcnt lgkmcnt(0)
	v_mfma_f32_16x16x32_bf16 v[26:29], v[58:61], v[18:21], v[26:29]
	ds_read_b128 v[58:61], v127 offset:29952
	ds_read_b128 v[62:65], v127 offset:30016
	s_waitcnt lgkmcnt(1)
	v_mfma_f32_16x16x32_bf16 v[58:61], v[58:61], v[22:25], 0
	s_waitcnt lgkmcnt(0)
	v_mfma_f32_16x16x32_bf16 v[58:61], v[62:65], v[18:21], v[58:61]
	ds_read_b128 v[62:65], v127 offset:30528
	ds_read_b128 v[66:69], v127 offset:30592
	s_waitcnt lgkmcnt(1)
	v_mfma_f32_16x16x32_bf16 v[22:25], v[62:65], v[22:25], 0
	s_waitcnt lgkmcnt(0)
	v_mfma_f32_16x16x32_bf16 v[18:21], v[66:69], v[18:21], v[22:25]
	s_nop 5
	v_cndmask_b32_e64 v22, v175, v42, s[24:25]
	v_cndmask_b32_e64 v23, v175, v43, s[26:27]
	v_max3_f32 v24, v22, s2, v23
	v_cndmask_b32_e64 v25, v175, v44, s[28:29]
	v_cndmask_b32_e64 v42, v175, v45, s[30:31]
	v_max3_f32 v24, v24, v25, v42
	v_cndmask_b32_e64 v43, v175, v46, s[34:35]
	v_cndmask_b32_e64 v44, v175, v47, s[36:37]
	v_max3_f32 v24, v24, v43, v44
	v_cndmask_b32_e64 v45, v175, v48, s[38:39]
	v_cndmask_b32_e64 v46, v175, v49, s[0:1]
	v_max3_f32 v24, v24, v45, v46
	v_cndmask_b32_e64 v47, v50, v175, s[44:45]
	v_cndmask_b32_e64 v48, v51, v175, s[44:45]
	v_max3_f32 v24, v24, v47, v48
	v_cndmask_b32_e64 v49, v52, v175, s[44:45]
	v_cndmask_b32_e64 v50, v53, v175, s[44:45]
	v_max3_f32 v24, v24, v49, v50
	v_cndmask_b32_e64 v51, v54, v175, s[44:45]
	v_cndmask_b32_e64 v52, v55, v175, s[44:45]
	v_max3_f32 v24, v24, v51, v52
	v_cndmask_b32_e64 v53, v56, v175, s[44:45]
	v_cndmask_b32_e64 v54, v57, v175, s[44:45]
	v_max3_f32 v24, v24, v53, v54
	v_max3_f32 v24, v24, v38, v39
	v_max3_f32 v24, v24, v40, v41
	v_max3_f32 v24, v24, v34, v35
	v_max3_f32 v24, v24, v36, v37
	v_max3_f32 v24, v24, v30, v31
	v_max3_f32 v24, v24, v32, v33
	v_max3_f32 v24, v24, v26, v27
	v_max3_f32 v24, v24, v28, v29
	v_cndmask_b32_e64 v55, v175, v58, s[4:5]
	v_cndmask_b32_e64 v56, v175, v59, s[6:7]
	v_max3_f32 v24, v24, v55, v56
	v_cndmask_b32_e64 v57, v175, v60, s[8:9]
	v_cndmask_b32_e64 v58, v175, v61, s[10:11]
	v_max3_f32 v24, v24, v57, v58
	v_cndmask_b32_e64 v18, v175, v18, s[12:13]
	v_cndmask_b32_e64 v19, v175, v19, s[14:15]
	v_max3_f32 v24, v24, v18, v19
	v_cndmask_b32_e64 v20, v175, v20, s[16:17]
	v_cndmask_b32_e64 v21, v175, v21, s[18:19]
	v_max3_f32 v24, v24, v20, v21
	v_mov_b32_e32 v59, v24
	s_nop 1
	v_permlane16_swap_b32_e32 v24, v59
	s_waitcnt lgkmcnt(0)
	v_max_f32_e32 v59, v59, v59
	v_max_f32_e32 v24, v24, v59
	v_mov_b32_e32 v59, v24
	s_nop 1
	v_permlane32_swap_b32_e32 v24, v59
	s_waitcnt lgkmcnt(0)
	v_max3_f32 v24, v24, v59, v99
	v_sub_f32_e32 v22, v22, v24
	v_exp_f32_e32 v22, v22
	v_sub_f32_e32 v23, v23, v24
	v_exp_f32_e32 v23, v23
	v_sub_f32_e32 v25, v25, v24
	v_exp_f32_e32 v25, v25
	v_sub_f32_e32 v42, v42, v24
	v_exp_f32_e32 v42, v42
	v_sub_f32_e32 v43, v43, v24
	v_add_f32_e32 v59, 0, v22
	v_exp_f32_e32 v43, v43
	v_sub_f32_e32 v44, v44, v24
	v_add_f32_e32 v59, v23, v59
	v_exp_f32_e32 v44, v44
	v_sub_f32_e32 v45, v45, v24
	v_add_f32_e32 v59, v25, v59
	v_exp_f32_e32 v45, v45
	v_sub_f32_e32 v46, v46, v24
	v_add_f32_e32 v59, v42, v59
	v_exp_f32_e32 v46, v46
	v_sub_f32_e32 v47, v47, v24
	v_add_f32_e32 v59, v43, v59
	v_exp_f32_e32 v47, v47
	v_sub_f32_e32 v48, v48, v24
	v_add_f32_e32 v59, v44, v59
	v_exp_f32_e32 v48, v48
	v_sub_f32_e32 v49, v49, v24
	v_add_f32_e32 v59, v45, v59
	v_exp_f32_e32 v49, v49
	v_sub_f32_e32 v50, v50, v24
	v_add_f32_e32 v59, v46, v59
	v_exp_f32_e32 v50, v50
	v_sub_f32_e32 v51, v51, v24
	v_add_f32_e32 v59, v47, v59
	v_exp_f32_e32 v51, v51
	v_sub_f32_e32 v52, v52, v24
	v_add_f32_e32 v59, v48, v59
	v_exp_f32_e32 v52, v52
	v_sub_f32_e32 v53, v53, v24
	v_add_f32_e32 v59, v49, v59
	v_exp_f32_e32 v53, v53
	v_sub_f32_e32 v54, v54, v24
	v_add_f32_e32 v59, v50, v59
	v_exp_f32_e32 v54, v54
	v_sub_f32_e32 v38, v38, v24
	v_add_f32_e32 v59, v51, v59
	v_exp_f32_e32 v38, v38
	v_sub_f32_e32 v39, v39, v24
	v_add_f32_e32 v59, v52, v59
	v_exp_f32_e32 v39, v39
	v_sub_f32_e32 v40, v40, v24
	v_add_f32_e32 v59, v53, v59
	v_exp_f32_e32 v40, v40
	v_sub_f32_e32 v41, v41, v24
	v_add_f32_e32 v59, v54, v59
	v_exp_f32_e32 v41, v41
	v_sub_f32_e32 v34, v34, v24
	v_add_f32_e32 v59, v38, v59
	v_exp_f32_e32 v60, v34
	v_add_f32_e32 v59, v39, v59
	v_add_f32_e32 v59, v40, v59
	v_add_f32_e32 v59, v41, v59
	v_sub_f32_e32 v35, v35, v24
	v_add_f32_e32 v34, v60, v59
	v_exp_f32_e32 v59, v35
	v_sub_f32_e32 v35, v36, v24
	v_exp_f32_e32 v61, v35
	v_sub_f32_e32 v35, v37, v24
	v_exp_f32_e32 v62, v35
	v_sub_f32_e32 v30, v30, v24
	v_exp_f32_e32 v63, v30
	v_sub_f32_e32 v31, v31, v24
	v_add_f32_e32 v34, v59, v34
	v_exp_f32_e32 v64, v31
	v_sub_f32_e32 v31, v32, v24
	v_add_f32_e32 v34, v61, v34
	v_exp_f32_e32 v65, v31
	v_sub_f32_e32 v31, v33, v24
	v_add_f32_e32 v34, v62, v34
	v_exp_f32_e32 v66, v31
	v_sub_f32_e32 v26, v26, v24
	v_add_f32_e32 v30, v63, v34
	v_exp_f32_e32 v26, v26
	v_sub_f32_e32 v27, v27, v24
	v_add_f32_e32 v30, v64, v30
	v_exp_f32_e32 v27, v27
	v_sub_f32_e32 v28, v28, v24
	v_add_f32_e32 v30, v65, v30
	v_exp_f32_e32 v28, v28
	v_sub_f32_e32 v29, v29, v24
	v_add_f32_e32 v30, v66, v30
	v_exp_f32_e32 v29, v29
	v_sub_f32_e32 v31, v55, v24
	v_add_f32_e32 v30, v26, v30
	v_exp_f32_e32 v55, v31
	v_sub_f32_e32 v31, v56, v24
	v_add_f32_e32 v30, v27, v30
	v_exp_f32_e32 v56, v31
	v_sub_f32_e32 v31, v57, v24
	v_add_f32_e32 v30, v28, v30
	v_exp_f32_e32 v57, v31
	v_sub_f32_e32 v31, v58, v24
	v_add_f32_e32 v30, v29, v30
	v_exp_f32_e32 v58, v31
	v_sub_f32_e32 v18, v18, v24
	v_add_f32_e32 v30, v55, v30
	v_exp_f32_e32 v67, v18
	v_sub_f32_e32 v19, v19, v24
	v_add_f32_e32 v30, v56, v30
	v_exp_f32_e32 v68, v19
	v_sub_f32_e32 v19, v20, v24
	v_add_f32_e32 v30, v57, v30
	v_exp_f32_e32 v69, v19
	v_sub_f32_e32 v19, v21, v24
	v_add_f32_e32 v30, v58, v30
	v_exp_f32_e32 v70, v19
	v_add_f32_e32 v18, v67, v30
	v_add_f32_e32 v18, v68, v18
	v_add_f32_e32 v18, v69, v18
	v_add_f32_e32 v18, v70, v18
	v_mov_b32_e32 v19, v18
	s_nop 1
	v_permlane16_swap_b32_e32 v18, v19
	v_cvt_pk_bf16_f32 v22, v22, v23
	v_cvt_pk_bf16_f32 v23, v25, v42
	s_waitcnt lgkmcnt(0)
	v_add_f32_e32 v18, v18, v19
	v_mov_b32_e32 v19, v18
	s_nop 1
	v_permlane32_swap_b32_e32 v18, v19
	s_waitcnt lgkmcnt(0)
	v_add_f32_e32 v18, v18, v19
	v_sub_f32_e32 v19, v99, v24
	v_exp_f32_e32 v19, v19
	v_cvt_pk_bf16_f32 v24, v43, v44
	v_cvt_pk_bf16_f32 v25, v45, v46
	v_cvt_pk_bf16_f32 v34, v47, v48
	v_cvt_pk_bf16_f32 v35, v49, v50
	v_cvt_pk_bf16_f32 v36, v51, v52
	s_nop 0
	v_add_f32_e32 v71, v19, v18
	v_cvt_pk_bf16_f32 v37, v53, v54
	v_cvt_pk_bf16_f32 v30, v38, v39
	v_div_scale_f32 v38, s[44:45], v71, v71, 1.0
	v_rcp_f32_e32 v39, v38
	v_cvt_pk_bf16_f32 v31, v40, v41
	v_cvt_pk_bf16_f32 v32, v60, v59
	v_cvt_pk_bf16_f32 v33, v61, v62
	v_cvt_pk_bf16_f32 v18, v63, v64
	v_cvt_pk_bf16_f32 v19, v65, v66
	s_nop 0
	v_fma_f32 v40, -v38, v39, 1.0
	v_fmac_f32_e32 v39, v40, v39
	v_div_scale_f32 v40, vcc, 1.0, v71, 1.0
	v_mul_f32_e32 v41, v40, v39
	v_fma_f32 v42, -v38, v41, v40
	v_fmac_f32_e32 v41, v42, v39
	v_fma_f32 v38, -v38, v41, v40
	v_cvt_pk_bf16_f32 v20, v26, v27
	v_cvt_pk_bf16_f32 v21, v28, v29
	v_cvt_pk_bf16_f32 v26, v55, v56
	v_cvt_pk_bf16_f32 v27, v57, v58
	v_cvt_pk_bf16_f32 v28, v67, v68
	v_cvt_pk_bf16_f32 v29, v69, v70
	v_div_fmas_f32 v38, v38, v39, v41
	ds_read_b128 v[40:43], v0 offset:39328
	ds_read_b128 v[44:47], v0 offset:39392
	s_waitcnt lgkmcnt(1)
	v_mfma_f32_16x16x32_bf16 v[40:43], v[40:43], v[22:25], 0
	v_div_fixup_f32 v48, v38, v71, 1.0
	v_mad_i64_i32 v[38:39], s[44:45], v104, s33, v[100:101]
	s_waitcnt lgkmcnt(0)
	v_mfma_f32_16x16x32_bf16 v[40:43], v[44:47], v[34:37], v[40:43]
	ds_read_b128 v[44:47], v0 offset:39456
	s_waitcnt lgkmcnt(0)
	v_mfma_f32_16x16x32_bf16 v[40:43], v[44:47], v[30:33], v[40:43]
	ds_read_b128 v[44:47], v0 offset:39520
	s_waitcnt lgkmcnt(0)
	v_mfma_f32_16x16x32_bf16 v[40:43], v[44:47], v[18:21], v[40:43]
	ds_read_b128 v[44:47], v0 offset:39584
	s_waitcnt lgkmcnt(0)
	v_mfma_f32_16x16x32_bf16 v[40:43], v[44:47], v[26:29], v[40:43]
	s_nop 7
	v_mul_f32_e32 v40, v40, v48
	v_mul_f32_e32 v41, v41, v48
	v_cvt_pk_bf16_f32 v40, v40, v41
	v_mul_f32_e32 v41, v42, v48
	v_mul_f32_e32 v42, v43, v48
	v_cvt_pk_bf16_f32 v41, v41, v42
	global_store_dwordx2 v[38:39], v[40:41], off
	ds_read_b128 v[40:43], v0 offset:48288
	ds_read_b128 v[44:47], v0 offset:48352
	s_waitcnt lgkmcnt(1)
	v_mfma_f32_16x16x32_bf16 v[40:43], v[40:43], v[22:25], 0
	s_waitcnt lgkmcnt(0)
	v_mfma_f32_16x16x32_bf16 v[40:43], v[44:47], v[34:37], v[40:43]
	ds_read_b128 v[44:47], v0 offset:48416
	s_waitcnt lgkmcnt(0)
	v_mfma_f32_16x16x32_bf16 v[40:43], v[44:47], v[30:33], v[40:43]
	ds_read_b128 v[44:47], v0 offset:48480
	s_waitcnt lgkmcnt(0)
	v_mfma_f32_16x16x32_bf16 v[40:43], v[44:47], v[18:21], v[40:43]
	ds_read_b128 v[44:47], v0 offset:48544
	s_waitcnt lgkmcnt(0)
	v_mfma_f32_16x16x32_bf16 v[40:43], v[44:47], v[26:29], v[40:43]
	s_nop 7
	v_mul_f32_e32 v40, v40, v48
	v_mul_f32_e32 v41, v41, v48
	v_cvt_pk_bf16_f32 v40, v40, v41
	v_mul_f32_e32 v41, v42, v48
	v_mul_f32_e32 v42, v43, v48
	v_cvt_pk_bf16_f32 v41, v41, v42
	global_store_dwordx2 v[38:39], v[40:41], off offset:32
	ds_read_b128 v[40:43], v0 offset:57248
	ds_read_b128 v[44:47], v0 offset:57312
	s_waitcnt lgkmcnt(1)
	v_mfma_f32_16x16x32_bf16 v[40:43], v[40:43], v[22:25], 0
	s_waitcnt lgkmcnt(0)
	v_mfma_f32_16x16x32_bf16 v[40:43], v[44:47], v[34:37], v[40:43]
	ds_read_b128 v[44:47], v0 offset:57376
	s_waitcnt lgkmcnt(0)
	v_mfma_f32_16x16x32_bf16 v[40:43], v[44:47], v[30:33], v[40:43]
	ds_read_b128 v[44:47], v0 offset:57440
	s_waitcnt lgkmcnt(0)
	v_mfma_f32_16x16x32_bf16 v[40:43], v[44:47], v[18:21], v[40:43]
	ds_read_b128 v[44:47], v0 offset:57504
	s_waitcnt lgkmcnt(0)
	v_mfma_f32_16x16x32_bf16 v[40:43], v[44:47], v[26:29], v[40:43]
	s_nop 7
	v_mul_f32_e32 v40, v48, v40
	v_mul_f32_e32 v41, v48, v41
	v_cvt_pk_bf16_f32 v40, v40, v41
	v_mul_f32_e32 v41, v48, v42
	v_mul_f32_e32 v42, v48, v43
	v_cvt_pk_bf16_f32 v41, v41, v42
	global_store_dwordx2 v[38:39], v[40:41], off offset:64
	ds_read_b128 v[40:43], v133 offset:39328
	s_waitcnt lgkmcnt(0)
	v_mfma_f32_16x16x32_bf16 v[22:25], v[40:43], v[22:25], 0
	ds_read_b128 v[40:43], v133 offset:39392
	s_waitcnt lgkmcnt(0)
	v_mfma_f32_16x16x32_bf16 v[22:25], v[40:43], v[34:37], v[22:25]
	ds_read_b128 v[34:37], v133 offset:39456
	s_waitcnt lgkmcnt(0)
	v_mfma_f32_16x16x32_bf16 v[22:25], v[34:37], v[30:33], v[22:25]
	ds_read_b128 v[30:33], v133 offset:39520
	s_waitcnt lgkmcnt(0)
	v_mfma_f32_16x16x32_bf16 v[18:21], v[30:33], v[18:21], v[22:25]
	s_nop 4
	ds_read_b128 v[22:25], v133 offset:39584
	s_waitcnt lgkmcnt(0)
	v_mfma_f32_16x16x32_bf16 v[18:21], v[22:25], v[26:29], v[18:21]
	s_nop 7
	v_mul_f32_e32 v18, v48, v18
	v_mul_f32_e32 v19, v48, v19
	v_cvt_pk_bf16_f32 v18, v18, v19
	v_mul_f32_e32 v19, v48, v20
	v_mul_f32_e32 v20, v48, v21
	v_cvt_pk_bf16_f32 v19, v19, v20
	global_store_dwordx2 v[38:39], v[18:19], off offset:96
	ds_read_b128 v[18:21], v127 offset:13824
	ds_read_b128 v[22:25], v127 offset:13888
	s_waitcnt lgkmcnt(1)
	v_mfma_f32_16x16x32_bf16 v[18:21], v[18:21], v[14:17], 0
	s_waitcnt lgkmcnt(0)
	v_mfma_f32_16x16x32_bf16 v[38:41], v[22:25], v[10:13], v[18:21]
	s_nop 5
	ds_read_b128 v[18:21], v127 offset:14400
	ds_read_b128 v[22:25], v127 offset:14464
	s_waitcnt lgkmcnt(1)
	v_mfma_f32_16x16x32_bf16 v[18:21], v[18:21], v[14:17], 0
	s_waitcnt lgkmcnt(0)
	v_mfma_f32_16x16x32_bf16 v[42:45], v[22:25], v[10:13], v[18:21]
	s_nop 5
	ds_read_b128 v[18:21], v127 offset:18432
	ds_read_b128 v[22:25], v127 offset:18496
	s_waitcnt lgkmcnt(1)
	v_mfma_f32_16x16x32_bf16 v[18:21], v[18:21], v[14:17], 0
	s_waitcnt lgkmcnt(0)
	v_mfma_f32_16x16x32_bf16 v[46:49], v[22:25], v[10:13], v[18:21]
	s_nop 5
	ds_read_b128 v[18:21], v127 offset:19008
	ds_read_b128 v[22:25], v127 offset:19072
	s_waitcnt lgkmcnt(1)
	v_mfma_f32_16x16x32_bf16 v[18:21], v[18:21], v[14:17], 0
	s_waitcnt lgkmcnt(0)
	v_mfma_f32_16x16x32_bf16 v[34:37], v[22:25], v[10:13], v[18:21]
	s_nop 5
	ds_read_b128 v[18:21], v127 offset:23040
	ds_read_b128 v[22:25], v127 offset:23104
	s_waitcnt lgkmcnt(1)
	v_mfma_f32_16x16x32_bf16 v[18:21], v[18:21], v[14:17], 0
	s_waitcnt lgkmcnt(0)
	v_mfma_f32_16x16x32_bf16 v[30:33], v[22:25], v[10:13], v[18:21]
	s_nop 5
	ds_read_b128 v[18:21], v127 offset:23616
	ds_read_b128 v[22:25], v127 offset:23680
	s_waitcnt lgkmcnt(1)
	v_mfma_f32_16x16x32_bf16 v[18:21], v[18:21], v[14:17], 0
	s_waitcnt lgkmcnt(0)
	v_mfma_f32_16x16x32_bf16 v[26:29], v[22:25], v[10:13], v[18:21]
	s_nop 5
	ds_read_b128 v[18:21], v127 offset:27648
	ds_read_b128 v[22:25], v127 offset:27712
	s_waitcnt lgkmcnt(1)
	v_mfma_f32_16x16x32_bf16 v[18:21], v[18:21], v[14:17], 0
	s_waitcnt lgkmcnt(0)
	v_mfma_f32_16x16x32_bf16 v[22:25], v[22:25], v[10:13], v[18:21]
	s_nop 5
	ds_read_b128 v[18:21], v127 offset:28224
	ds_read_b128 v[50:53], v127 offset:28288
	s_waitcnt lgkmcnt(1)
	v_mfma_f32_16x16x32_bf16 v[18:21], v[18:21], v[14:17], 0
	s_waitcnt lgkmcnt(0)
	v_mfma_f32_16x16x32_bf16 v[18:21], v[50:53], v[10:13], v[18:21]
	ds_read_b128 v[50:53], v127 offset:32256
	ds_read_b128 v[54:57], v127 offset:32320
	s_waitcnt lgkmcnt(1)
	v_mfma_f32_16x16x32_bf16 v[50:53], v[50:53], v[14:17], 0
	s_waitcnt lgkmcnt(0)
	v_mfma_f32_16x16x32_bf16 v[50:53], v[54:57], v[10:13], v[50:53]
	ds_read_b128 v[54:57], v127 offset:32832
	ds_read_b128 v[58:61], v127 offset:32896
	s_waitcnt lgkmcnt(1)
	v_mfma_f32_16x16x32_bf16 v[14:17], v[54:57], v[14:17], 0
	s_waitcnt lgkmcnt(0)
	v_mfma_f32_16x16x32_bf16 v[10:13], v[58:61], v[10:13], v[14:17]
	s_nop 5
	v_cndmask_b32_e64 v14, v175, v38, s[24:25]
	v_cndmask_b32_e64 v15, v175, v39, s[26:27]
	v_max3_f32 v16, v14, s2, v15
	v_cndmask_b32_e64 v17, v175, v40, s[28:29]
	v_cndmask_b32_e64 v38, v175, v41, s[30:31]
	v_max3_f32 v16, v16, v17, v38
	v_cndmask_b32_e64 v39, v175, v42, s[34:35]
	v_cndmask_b32_e64 v40, v175, v43, s[36:37]
	v_max3_f32 v16, v16, v39, v40
	v_cndmask_b32_e64 v41, v175, v44, s[38:39]
	v_cndmask_b32_e64 v42, v175, v45, s[0:1]
	v_max3_f32 v16, v16, v41, v42
	v_max3_f32 v16, v16, v46, v47
	v_max3_f32 v16, v16, v48, v49
	v_max3_f32 v16, v16, v34, v35
	v_max3_f32 v16, v16, v36, v37
	v_max3_f32 v16, v16, v30, v31
	v_max3_f32 v16, v16, v32, v33
	v_max3_f32 v16, v16, v26, v27
	v_max3_f32 v16, v16, v28, v29
	v_max3_f32 v16, v16, v22, v23
	v_max3_f32 v16, v16, v24, v25
	v_max3_f32 v16, v16, v18, v19
	v_max3_f32 v16, v16, v20, v21
	v_cndmask_b32_e64 v43, v175, v50, s[4:5]
	v_cndmask_b32_e64 v44, v175, v51, s[6:7]
	v_max3_f32 v16, v16, v43, v44
	v_cndmask_b32_e64 v45, v175, v52, s[8:9]
	v_cndmask_b32_e64 v50, v175, v53, s[10:11]
	v_max3_f32 v16, v16, v45, v50
	v_cndmask_b32_e64 v10, v175, v10, s[12:13]
	v_cndmask_b32_e64 v11, v175, v11, s[14:15]
	v_max3_f32 v16, v16, v10, v11
	v_cndmask_b32_e64 v12, v175, v12, s[16:17]
	v_cndmask_b32_e64 v13, v175, v13, s[18:19]
	v_max3_f32 v16, v16, v12, v13
	v_mov_b32_e32 v51, v16
	s_nop 1
	v_permlane16_swap_b32_e32 v16, v51
	s_waitcnt lgkmcnt(0)
	v_max_f32_e32 v51, v51, v51
	v_max_f32_e32 v16, v16, v51
	v_mov_b32_e32 v51, v16
	s_nop 1
	v_permlane32_swap_b32_e32 v16, v51
	s_waitcnt lgkmcnt(0)
	v_max3_f32 v16, v16, v51, v99
	v_sub_f32_e32 v14, v14, v16
	v_exp_f32_e32 v14, v14
	v_sub_f32_e32 v15, v15, v16
	v_exp_f32_e32 v15, v15
	v_sub_f32_e32 v17, v17, v16
	v_exp_f32_e32 v17, v17
	v_sub_f32_e32 v38, v38, v16
	v_exp_f32_e32 v38, v38
	v_sub_f32_e32 v39, v39, v16
	v_add_f32_e32 v51, 0, v14
	v_exp_f32_e32 v39, v39
	v_sub_f32_e32 v40, v40, v16
	v_add_f32_e32 v51, v15, v51
	v_exp_f32_e32 v40, v40
	v_sub_f32_e32 v41, v41, v16
	v_add_f32_e32 v51, v17, v51
	v_exp_f32_e32 v41, v41
	v_sub_f32_e32 v42, v42, v16
	v_add_f32_e32 v51, v38, v51
	v_exp_f32_e32 v42, v42
	v_sub_f32_e32 v46, v46, v16
	v_add_f32_e32 v51, v39, v51
	v_exp_f32_e32 v46, v46
	v_sub_f32_e32 v47, v47, v16
	v_add_f32_e32 v51, v40, v51
	v_exp_f32_e32 v47, v47
	v_sub_f32_e32 v48, v48, v16
	v_add_f32_e32 v51, v41, v51
	v_exp_f32_e32 v48, v48
	v_sub_f32_e32 v49, v49, v16
	v_add_f32_e32 v51, v42, v51
	v_exp_f32_e32 v49, v49
	v_sub_f32_e32 v34, v34, v16
	v_add_f32_e32 v51, v46, v51
	v_exp_f32_e32 v34, v34
	v_sub_f32_e32 v35, v35, v16
	v_add_f32_e32 v51, v47, v51
	v_exp_f32_e32 v35, v35
	v_sub_f32_e32 v36, v36, v16
	v_add_f32_e32 v51, v48, v51
	v_exp_f32_e32 v36, v36
	v_sub_f32_e32 v37, v37, v16
	v_add_f32_e32 v51, v49, v51
	v_exp_f32_e32 v37, v37
	v_sub_f32_e32 v30, v30, v16
	v_add_f32_e32 v51, v34, v51
	v_exp_f32_e32 v30, v30
	v_sub_f32_e32 v31, v31, v16
	v_add_f32_e32 v51, v35, v51
	v_exp_f32_e32 v31, v31
	v_sub_f32_e32 v32, v32, v16
	v_add_f32_e32 v51, v36, v51
	v_exp_f32_e32 v32, v32
	v_sub_f32_e32 v33, v33, v16
	v_add_f32_e32 v51, v37, v51
	v_exp_f32_e32 v33, v33
	v_sub_f32_e32 v26, v26, v16
	v_add_f32_e32 v51, v30, v51
	v_exp_f32_e32 v52, v26
	v_add_f32_e32 v51, v31, v51
	v_add_f32_e32 v51, v32, v51
	v_add_f32_e32 v51, v33, v51
	v_sub_f32_e32 v27, v27, v16
	v_add_f32_e32 v26, v52, v51
	v_exp_f32_e32 v51, v27
	v_sub_f32_e32 v27, v28, v16
	v_exp_f32_e32 v53, v27
	v_sub_f32_e32 v27, v29, v16
	v_exp_f32_e32 v54, v27
	v_sub_f32_e32 v22, v22, v16
	v_exp_f32_e32 v55, v22
	v_sub_f32_e32 v23, v23, v16
	v_add_f32_e32 v26, v51, v26
	v_exp_f32_e32 v56, v23
	v_sub_f32_e32 v23, v24, v16
	v_add_f32_e32 v26, v53, v26
	v_exp_f32_e32 v57, v23
	v_sub_f32_e32 v23, v25, v16
	v_add_f32_e32 v26, v54, v26
	v_exp_f32_e32 v58, v23
	v_sub_f32_e32 v18, v18, v16
	v_add_f32_e32 v22, v55, v26
	v_exp_f32_e32 v18, v18
	v_sub_f32_e32 v19, v19, v16
	v_add_f32_e32 v22, v56, v22
	v_exp_f32_e32 v19, v19
	v_sub_f32_e32 v20, v20, v16
	v_add_f32_e32 v22, v57, v22
	v_exp_f32_e32 v20, v20
	v_sub_f32_e32 v21, v21, v16
	v_add_f32_e32 v22, v58, v22
	v_exp_f32_e32 v21, v21
	v_sub_f32_e32 v23, v43, v16
	v_add_f32_e32 v22, v18, v22
	v_exp_f32_e32 v43, v23
	v_sub_f32_e32 v23, v44, v16
	v_add_f32_e32 v22, v19, v22
	v_exp_f32_e32 v44, v23
	v_sub_f32_e32 v23, v45, v16
	v_add_f32_e32 v22, v20, v22
	v_exp_f32_e32 v45, v23
	v_sub_f32_e32 v23, v50, v16
	v_add_f32_e32 v22, v21, v22
	v_exp_f32_e32 v50, v23
	v_sub_f32_e32 v10, v10, v16
	v_add_f32_e32 v22, v43, v22
	v_exp_f32_e32 v59, v10
	v_sub_f32_e32 v11, v11, v16
	v_add_f32_e32 v22, v44, v22
	v_exp_f32_e32 v60, v11
	v_sub_f32_e32 v11, v12, v16
	v_add_f32_e32 v22, v45, v22
	v_exp_f32_e32 v61, v11
	v_sub_f32_e32 v11, v13, v16
	v_add_f32_e32 v22, v50, v22
	v_exp_f32_e32 v62, v11
	v_add_f32_e32 v10, v59, v22
	v_add_f32_e32 v10, v60, v10
	v_add_f32_e32 v10, v61, v10
	v_add_f32_e32 v10, v62, v10
	v_mov_b32_e32 v11, v10
	s_nop 1
	v_permlane16_swap_b32_e32 v10, v11
	v_cvt_pk_bf16_f32 v14, v14, v15
	v_cvt_pk_bf16_f32 v15, v17, v38
	s_waitcnt lgkmcnt(0)
	v_add_f32_e32 v10, v10, v11
	v_mov_b32_e32 v11, v10
	s_nop 1
	v_permlane32_swap_b32_e32 v10, v11
	s_waitcnt lgkmcnt(0)
	v_add_f32_e32 v10, v10, v11
	v_sub_f32_e32 v11, v99, v16
	v_exp_f32_e32 v11, v11
	v_cvt_pk_bf16_f32 v16, v39, v40
	v_cvt_pk_bf16_f32 v17, v41, v42
	v_cvt_pk_bf16_f32 v26, v46, v47
	v_cvt_pk_bf16_f32 v27, v48, v49
	v_cvt_pk_bf16_f32 v28, v34, v35
	s_nop 0
	v_add_f32_e32 v63, v11, v10
	v_cvt_pk_bf16_f32 v29, v36, v37
	v_cvt_pk_bf16_f32 v22, v30, v31
	v_div_scale_f32 v30, s[0:1], v63, v63, 1.0
	v_rcp_f32_e32 v31, v30
	v_cvt_pk_bf16_f32 v23, v32, v33
	v_cvt_pk_bf16_f32 v24, v52, v51
	v_cvt_pk_bf16_f32 v25, v53, v54
	v_cvt_pk_bf16_f32 v10, v55, v56
	v_cvt_pk_bf16_f32 v11, v57, v58
	s_nop 0
	v_fma_f32 v32, -v30, v31, 1.0
	v_fmac_f32_e32 v31, v32, v31
	v_div_scale_f32 v32, vcc, 1.0, v63, 1.0
	v_mul_f32_e32 v33, v32, v31
	v_fma_f32 v34, -v30, v33, v32
	v_fmac_f32_e32 v33, v34, v31
	v_fma_f32 v30, -v30, v33, v32
	v_cvt_pk_bf16_f32 v12, v18, v19
	v_cvt_pk_bf16_f32 v13, v20, v21
	v_cvt_pk_bf16_f32 v18, v43, v44
	v_cvt_pk_bf16_f32 v19, v45, v50
	v_cvt_pk_bf16_f32 v20, v59, v60
	v_cvt_pk_bf16_f32 v21, v61, v62
	v_div_fmas_f32 v30, v30, v31, v33
	ds_read_b128 v[32:35], v0 offset:39360
	ds_read_b128 v[36:39], v0 offset:39424
	s_waitcnt lgkmcnt(1)
	v_mfma_f32_16x16x32_bf16 v[32:35], v[32:35], v[14:17], 0
	v_div_fixup_f32 v40, v30, v63, 1.0
	v_mad_i64_i32 v[30:31], s[0:1], v102, s33, v[100:101]
	s_waitcnt lgkmcnt(0)
	v_mfma_f32_16x16x32_bf16 v[32:35], v[36:39], v[26:29], v[32:35]
	ds_read_b128 v[36:39], v0 offset:39488
	v_readlane_b32 s0, v254, 59
	v_readlane_b32 s1, v254, 60
	s_waitcnt lgkmcnt(0)
	v_mfma_f32_16x16x32_bf16 v[32:35], v[36:39], v[22:25], v[32:35]
	ds_read_b128 v[36:39], v0 offset:39552
	s_waitcnt lgkmcnt(0)
	v_mfma_f32_16x16x32_bf16 v[32:35], v[36:39], v[10:13], v[32:35]
	ds_read_b128 v[36:39], v0 offset:39616
	s_waitcnt lgkmcnt(0)
	v_mfma_f32_16x16x32_bf16 v[32:35], v[36:39], v[18:21], v[32:35]
	s_nop 7
	v_mul_f32_e32 v32, v32, v40
	v_mul_f32_e32 v33, v33, v40
	v_cvt_pk_bf16_f32 v32, v32, v33
	v_mul_f32_e32 v33, v34, v40
	v_mul_f32_e32 v34, v35, v40
	v_cvt_pk_bf16_f32 v33, v33, v34
	global_store_dwordx2 v[30:31], v[32:33], off
	ds_read_b128 v[32:35], v0 offset:48320
	ds_read_b128 v[36:39], v0 offset:48384
	s_waitcnt lgkmcnt(1)
	v_mfma_f32_16x16x32_bf16 v[32:35], v[32:35], v[14:17], 0
	s_waitcnt lgkmcnt(0)
	v_mfma_f32_16x16x32_bf16 v[32:35], v[36:39], v[26:29], v[32:35]
	ds_read_b128 v[36:39], v0 offset:48448
	s_waitcnt lgkmcnt(0)
	v_mfma_f32_16x16x32_bf16 v[32:35], v[36:39], v[22:25], v[32:35]
	ds_read_b128 v[36:39], v0 offset:48512
	s_waitcnt lgkmcnt(0)
	v_mfma_f32_16x16x32_bf16 v[32:35], v[36:39], v[10:13], v[32:35]
	ds_read_b128 v[36:39], v0 offset:48576
	s_waitcnt lgkmcnt(0)
	v_mfma_f32_16x16x32_bf16 v[32:35], v[36:39], v[18:21], v[32:35]
	s_nop 7
	v_mul_f32_e32 v32, v32, v40
	v_mul_f32_e32 v33, v33, v40
	v_cvt_pk_bf16_f32 v32, v32, v33
	v_mul_f32_e32 v33, v34, v40
	v_mul_f32_e32 v34, v35, v40
	v_cvt_pk_bf16_f32 v33, v33, v34
	global_store_dwordx2 v[30:31], v[32:33], off offset:32
	ds_read_b128 v[32:35], v0 offset:57280
	ds_read_b128 v[36:39], v0 offset:57344
	s_waitcnt lgkmcnt(1)
	v_mfma_f32_16x16x32_bf16 v[32:35], v[32:35], v[14:17], 0
	s_waitcnt lgkmcnt(0)
	v_mfma_f32_16x16x32_bf16 v[32:35], v[36:39], v[26:29], v[32:35]
	ds_read_b128 v[36:39], v0 offset:57408
	s_waitcnt lgkmcnt(0)
	v_mfma_f32_16x16x32_bf16 v[32:35], v[36:39], v[22:25], v[32:35]
	ds_read_b128 v[36:39], v0 offset:57472
	s_waitcnt lgkmcnt(0)
	v_mfma_f32_16x16x32_bf16 v[32:35], v[36:39], v[10:13], v[32:35]
	ds_read_b128 v[36:39], v0 offset:57536
	s_waitcnt lgkmcnt(0)
	v_mfma_f32_16x16x32_bf16 v[32:35], v[36:39], v[18:21], v[32:35]
	s_nop 7
	v_mul_f32_e32 v32, v40, v32
	v_mul_f32_e32 v33, v40, v33
	v_cvt_pk_bf16_f32 v32, v32, v33
	v_mul_f32_e32 v33, v40, v34
	v_mul_f32_e32 v34, v40, v35
	v_cvt_pk_bf16_f32 v33, v33, v34
	global_store_dwordx2 v[30:31], v[32:33], off offset:64
	ds_read_b128 v[32:35], v133 offset:39360
	s_waitcnt lgkmcnt(0)
	v_mfma_f32_16x16x32_bf16 v[14:17], v[32:35], v[14:17], 0
	ds_read_b128 v[32:35], v133 offset:39424
	s_waitcnt lgkmcnt(0)
	v_mfma_f32_16x16x32_bf16 v[14:17], v[32:35], v[26:29], v[14:17]
	ds_read_b128 v[26:29], v133 offset:39488
	s_waitcnt lgkmcnt(0)
	v_mfma_f32_16x16x32_bf16 v[14:17], v[26:29], v[22:25], v[14:17]
	ds_read_b128 v[22:25], v133 offset:39552
	s_waitcnt lgkmcnt(0)
	v_mfma_f32_16x16x32_bf16 v[10:13], v[22:25], v[10:13], v[14:17]
	s_nop 4
	ds_read_b128 v[14:17], v133 offset:39616
	s_waitcnt lgkmcnt(0)
	v_mfma_f32_16x16x32_bf16 v[10:13], v[14:17], v[18:21], v[10:13]
	s_nop 7
	v_mul_f32_e32 v10, v40, v10
	v_mul_f32_e32 v11, v40, v11
	v_cvt_pk_bf16_f32 v10, v10, v11
	v_mul_f32_e32 v11, v40, v12
	v_mul_f32_e32 v12, v40, v13
	v_cvt_pk_bf16_f32 v11, v11, v12
	global_store_dwordx2 v[30:31], v[10:11], off offset:96
	ds_read_b128 v[10:13], v127 offset:16128
	ds_read_b128 v[14:17], v127 offset:16192
	s_waitcnt lgkmcnt(1)
	v_mfma_f32_16x16x32_bf16 v[10:13], v[10:13], v[6:9], 0
	s_waitcnt lgkmcnt(0)
	v_mfma_f32_16x16x32_bf16 v[34:37], v[14:17], v[2:5], v[10:13]
	s_nop 5
	ds_read_b128 v[10:13], v127 offset:16704
	ds_read_b128 v[14:17], v127 offset:16768
	s_waitcnt lgkmcnt(1)
	v_mfma_f32_16x16x32_bf16 v[10:13], v[10:13], v[6:9], 0
	s_waitcnt lgkmcnt(0)
	v_mfma_f32_16x16x32_bf16 v[38:41], v[14:17], v[2:5], v[10:13]
	s_nop 5
	ds_read_b128 v[10:13], v127 offset:20736
	ds_read_b128 v[14:17], v127 offset:20800
	s_waitcnt lgkmcnt(1)
	v_mfma_f32_16x16x32_bf16 v[10:13], v[10:13], v[6:9], 0
	s_waitcnt lgkmcnt(0)
	v_mfma_f32_16x16x32_bf16 v[30:33], v[14:17], v[2:5], v[10:13]
	s_nop 5
	ds_read_b128 v[10:13], v127 offset:21312
	ds_read_b128 v[14:17], v127 offset:21376
	s_waitcnt lgkmcnt(1)
	v_mfma_f32_16x16x32_bf16 v[10:13], v[10:13], v[6:9], 0
	s_waitcnt lgkmcnt(0)
	v_mfma_f32_16x16x32_bf16 v[26:29], v[14:17], v[2:5], v[10:13]
	s_nop 5
	ds_read_b128 v[10:13], v127 offset:25344
	ds_read_b128 v[14:17], v127 offset:25408
	s_waitcnt lgkmcnt(1)
	v_mfma_f32_16x16x32_bf16 v[10:13], v[10:13], v[6:9], 0
	s_waitcnt lgkmcnt(0)
	v_mfma_f32_16x16x32_bf16 v[22:25], v[14:17], v[2:5], v[10:13]
	s_nop 5
	ds_read_b128 v[10:13], v127 offset:25920
	ds_read_b128 v[14:17], v127 offset:25984
	s_waitcnt lgkmcnt(1)
	v_mfma_f32_16x16x32_bf16 v[10:13], v[10:13], v[6:9], 0
	s_waitcnt lgkmcnt(0)
	v_mfma_f32_16x16x32_bf16 v[18:21], v[14:17], v[2:5], v[10:13]
	s_nop 5
	ds_read_b128 v[10:13], v127 offset:29952
	ds_read_b128 v[14:17], v127 offset:30016
	s_waitcnt lgkmcnt(1)
	v_mfma_f32_16x16x32_bf16 v[10:13], v[10:13], v[6:9], 0
	s_waitcnt lgkmcnt(0)
	v_mfma_f32_16x16x32_bf16 v[14:17], v[14:17], v[2:5], v[10:13]
	s_nop 5
	ds_read_b128 v[10:13], v127 offset:30528
	ds_read_b128 v[42:45], v127 offset:30592
	s_waitcnt lgkmcnt(1)
	v_mfma_f32_16x16x32_bf16 v[10:13], v[10:13], v[6:9], 0
	s_waitcnt lgkmcnt(0)
	v_mfma_f32_16x16x32_bf16 v[10:13], v[42:45], v[2:5], v[10:13]
	ds_read_b128 v[42:45], v127 offset:34560
	ds_read_b128 v[46:49], v127 offset:34624
	s_waitcnt lgkmcnt(1)
	v_mfma_f32_16x16x32_bf16 v[42:45], v[42:45], v[6:9], 0
	s_waitcnt lgkmcnt(0)
	v_mfma_f32_16x16x32_bf16 v[42:45], v[46:49], v[2:5], v[42:45]
	ds_read_b128 v[46:49], v127 offset:35136
	ds_read_b128 v[50:53], v127 offset:35200
	s_waitcnt lgkmcnt(1)
	v_mfma_f32_16x16x32_bf16 v[6:9], v[46:49], v[6:9], 0
	s_waitcnt lgkmcnt(0)
	v_mfma_f32_16x16x32_bf16 v[2:5], v[50:53], v[2:5], v[6:9]
	s_nop 5
	v_cndmask_b32_e64 v6, 0, 1, s[0:1]
	v_readlane_b32 s0, v254, 61
	v_cndmask_b32_e64 v7, 0, 1, s[76:77]
	v_readlane_b32 s1, v254, 62
	v_cndmask_b32_e64 v6, v7, v6, s[22:23]
	v_cndmask_b32_e64 v8, 0, 1, s[78:79]
	v_cndmask_b32_e64 v7, 0, 1, s[0:1]
	v_readlane_b32 s0, v254, 63
	v_and_b32_e32 v6, 1, v6
	v_cndmask_b32_e64 v7, v8, v7, s[22:23]
	v_readlane_b32 s1, v255, 0
	v_cmp_eq_u32_e32 vcc, 1, v6
	v_and_b32_e32 v7, 1, v7
	v_cndmask_b32_e64 v9, 0, 1, s[0:1]
	v_readlane_b32 s0, v255, 1
	v_cndmask_b32_e32 v6, v175, v34, vcc
	v_cmp_eq_u32_e32 vcc, 1, v7
	v_cndmask_b32_e64 v34, 0, 1, s[80:81]
	v_readlane_b32 s1, v255, 2
	v_cndmask_b32_e32 v7, v175, v35, vcc
	v_cndmask_b32_e64 v9, v34, v9, s[22:23]
	v_cndmask_b32_e64 v34, 0, 1, s[0:1]
	v_cndmask_b32_e64 v35, 0, 1, s[82:83]
	v_readlane_b32 s0, v255, 3
	v_and_b32_e32 v9, 1, v9
	v_cndmask_b32_e64 v34, v35, v34, s[22:23]
	v_readlane_b32 s1, v255, 4
	v_cmp_eq_u32_e32 vcc, 1, v9
	v_and_b32_e32 v34, 1, v34
	v_cndmask_b32_e64 v35, 0, 1, s[0:1]
	v_readlane_b32 s0, v255, 5
	v_cndmask_b32_e32 v9, v175, v36, vcc
	v_cmp_eq_u32_e32 vcc, 1, v34
	v_cndmask_b32_e64 v36, 0, 1, s[84:85]
	v_readlane_b32 s1, v255, 6
	v_cndmask_b32_e32 v34, v175, v37, vcc
	v_cndmask_b32_e64 v35, v36, v35, s[22:23]
	v_cndmask_b32_e64 v36, 0, 1, s[0:1]
	v_cndmask_b32_e64 v37, 0, 1, s[86:87]
	v_readlane_b32 s0, v255, 7
	v_and_b32_e32 v35, 1, v35
	v_cndmask_b32_e64 v36, v37, v36, s[22:23]
	v_readlane_b32 s1, v255, 8
	v_cmp_eq_u32_e32 vcc, 1, v35
	v_and_b32_e32 v36, 1, v36
	v_cndmask_b32_e64 v37, 0, 1, s[0:1]
	v_readlane_b32 s0, v255, 9
	v_cndmask_b32_e32 v35, v175, v38, vcc
	v_cmp_eq_u32_e32 vcc, 1, v36
	v_cndmask_b32_e64 v38, 0, 1, s[88:89]
	v_readlane_b32 s1, v255, 10
	v_cndmask_b32_e32 v36, v175, v39, vcc
	v_cndmask_b32_e64 v37, v38, v37, s[22:23]
	v_cndmask_b32_e64 v38, 0, 1, s[0:1]
	v_cndmask_b32_e64 v39, 0, 1, s[90:91]
	v_and_b32_e32 v37, 1, v37
	v_cndmask_b32_e64 v38, v39, v38, s[22:23]
	v_max3_f32 v8, v6, s2, v7
	v_cmp_eq_u32_e32 vcc, 1, v37
	v_and_b32_e32 v38, 1, v38
	v_max3_f32 v8, v8, v9, v34
	v_cndmask_b32_e32 v37, v175, v40, vcc
	v_cmp_eq_u32_e32 vcc, 1, v38
	v_max3_f32 v8, v8, v35, v36
	v_cndmask_b32_e64 v39, v175, v42, s[4:5]
	v_cndmask_b32_e32 v38, v175, v41, vcc
	v_max3_f32 v8, v8, v37, v38
	v_max3_f32 v8, v8, v30, v31
	v_max3_f32 v8, v8, v32, v33
	v_max3_f32 v8, v8, v26, v27
	v_max3_f32 v8, v8, v28, v29
	v_max3_f32 v8, v8, v22, v23
	v_max3_f32 v8, v8, v24, v25
	v_max3_f32 v8, v8, v18, v19
	v_max3_f32 v8, v8, v20, v21
	v_max3_f32 v8, v8, v14, v15
	v_max3_f32 v8, v8, v16, v17
	v_max3_f32 v8, v8, v10, v11
	v_max3_f32 v8, v8, v12, v13
	v_cndmask_b32_e64 v40, v175, v43, s[6:7]
	v_max3_f32 v8, v8, v39, v40
	v_cndmask_b32_e64 v41, v175, v44, s[8:9]
	v_cndmask_b32_e64 v42, v175, v45, s[10:11]
	v_max3_f32 v8, v8, v41, v42
	v_cndmask_b32_e64 v2, v175, v2, s[12:13]
	v_cndmask_b32_e64 v3, v175, v3, s[14:15]
	v_max3_f32 v8, v8, v2, v3
	v_cndmask_b32_e64 v4, v175, v4, s[16:17]
	v_cndmask_b32_e64 v5, v175, v5, s[18:19]
	v_max3_f32 v8, v8, v4, v5
	v_mov_b32_e32 v43, v8
	s_nop 1
	v_permlane16_swap_b32_e32 v8, v43
	s_waitcnt lgkmcnt(0)
	v_max_f32_e32 v43, v43, v43
	v_max_f32_e32 v8, v8, v43
	v_mov_b32_e32 v43, v8
	s_nop 1
	v_permlane32_swap_b32_e32 v8, v43
	s_waitcnt lgkmcnt(0)
	v_max3_f32 v8, v8, v43, v99
	v_sub_f32_e32 v6, v6, v8
	v_exp_f32_e32 v6, v6
	v_sub_f32_e32 v7, v7, v8
	v_exp_f32_e32 v7, v7
	v_sub_f32_e32 v9, v9, v8
	v_exp_f32_e32 v9, v9
	v_sub_f32_e32 v34, v34, v8
	v_exp_f32_e32 v34, v34
	v_sub_f32_e32 v35, v35, v8
	v_add_f32_e32 v43, 0, v6
	v_exp_f32_e32 v35, v35
	v_sub_f32_e32 v36, v36, v8
	v_add_f32_e32 v43, v7, v43
	v_exp_f32_e32 v36, v36
	v_sub_f32_e32 v37, v37, v8
	v_add_f32_e32 v43, v9, v43
	v_exp_f32_e32 v37, v37
	v_sub_f32_e32 v38, v38, v8
	v_add_f32_e32 v43, v34, v43
	v_exp_f32_e32 v38, v38
	v_sub_f32_e32 v30, v30, v8
	v_add_f32_e32 v43, v35, v43
	v_exp_f32_e32 v30, v30
	v_sub_f32_e32 v31, v31, v8
	v_add_f32_e32 v43, v36, v43
	v_exp_f32_e32 v31, v31
	v_sub_f32_e32 v32, v32, v8
	v_add_f32_e32 v43, v37, v43
	v_exp_f32_e32 v32, v32
	v_sub_f32_e32 v33, v33, v8
	v_add_f32_e32 v43, v38, v43
	v_exp_f32_e32 v33, v33
	v_sub_f32_e32 v26, v26, v8
	v_add_f32_e32 v43, v30, v43
	v_exp_f32_e32 v26, v26
	v_sub_f32_e32 v27, v27, v8
	v_add_f32_e32 v43, v31, v43
	v_exp_f32_e32 v27, v27
	v_sub_f32_e32 v28, v28, v8
	v_add_f32_e32 v43, v32, v43
	v_exp_f32_e32 v28, v28
	v_sub_f32_e32 v29, v29, v8
	v_add_f32_e32 v43, v33, v43
	v_exp_f32_e32 v29, v29
	v_sub_f32_e32 v22, v22, v8
	v_add_f32_e32 v43, v26, v43
	v_exp_f32_e32 v22, v22
	v_sub_f32_e32 v23, v23, v8
	v_add_f32_e32 v43, v27, v43
	v_exp_f32_e32 v23, v23
	v_sub_f32_e32 v24, v24, v8
	v_add_f32_e32 v43, v28, v43
	v_exp_f32_e32 v24, v24
	v_sub_f32_e32 v25, v25, v8
	v_add_f32_e32 v43, v29, v43
	v_exp_f32_e32 v25, v25
	v_sub_f32_e32 v18, v18, v8
	v_add_f32_e32 v43, v22, v43
	v_exp_f32_e32 v44, v18
	v_add_f32_e32 v43, v23, v43
	v_add_f32_e32 v43, v24, v43
	v_add_f32_e32 v43, v25, v43
	v_sub_f32_e32 v19, v19, v8
	v_add_f32_e32 v18, v44, v43
	v_exp_f32_e32 v43, v19
	v_sub_f32_e32 v19, v20, v8
	v_exp_f32_e32 v45, v19
	v_sub_f32_e32 v19, v21, v8
	v_exp_f32_e32 v46, v19
	v_sub_f32_e32 v14, v14, v8
	v_exp_f32_e32 v47, v14
	v_sub_f32_e32 v15, v15, v8
	v_add_f32_e32 v18, v43, v18
	v_exp_f32_e32 v48, v15
	v_sub_f32_e32 v15, v16, v8
	v_add_f32_e32 v18, v45, v18
	v_exp_f32_e32 v49, v15
	v_sub_f32_e32 v15, v17, v8
	v_add_f32_e32 v18, v46, v18
	v_exp_f32_e32 v50, v15
	v_sub_f32_e32 v10, v10, v8
	v_add_f32_e32 v14, v47, v18
	v_exp_f32_e32 v10, v10
	v_sub_f32_e32 v11, v11, v8
	v_add_f32_e32 v14, v48, v14
	v_exp_f32_e32 v11, v11
	v_sub_f32_e32 v12, v12, v8
	v_add_f32_e32 v14, v49, v14
	v_exp_f32_e32 v12, v12
	v_sub_f32_e32 v13, v13, v8
	v_add_f32_e32 v14, v50, v14
	v_exp_f32_e32 v13, v13
	v_sub_f32_e32 v15, v39, v8
	v_add_f32_e32 v14, v10, v14
	v_exp_f32_e32 v39, v15
	v_sub_f32_e32 v15, v40, v8
	v_add_f32_e32 v14, v11, v14
	v_exp_f32_e32 v40, v15
	v_sub_f32_e32 v15, v41, v8
	v_add_f32_e32 v14, v12, v14
	v_exp_f32_e32 v41, v15
	v_sub_f32_e32 v15, v42, v8
	v_add_f32_e32 v14, v13, v14
	v_exp_f32_e32 v42, v15
	v_sub_f32_e32 v2, v2, v8
	v_add_f32_e32 v14, v39, v14
	v_exp_f32_e32 v51, v2
	v_sub_f32_e32 v3, v3, v8
	v_add_f32_e32 v14, v40, v14
	v_exp_f32_e32 v52, v3
	v_sub_f32_e32 v3, v4, v8
	v_add_f32_e32 v14, v41, v14
	v_exp_f32_e32 v53, v3
	v_sub_f32_e32 v3, v5, v8
	v_add_f32_e32 v14, v42, v14
	v_exp_f32_e32 v54, v3
	v_add_f32_e32 v2, v51, v14
	v_add_f32_e32 v2, v52, v2
	v_add_f32_e32 v2, v53, v2
	v_add_f32_e32 v2, v54, v2
	v_mov_b32_e32 v3, v2
	s_nop 1
	v_permlane16_swap_b32_e32 v2, v3
	v_cvt_pk_bf16_f32 v6, v6, v7
	v_cvt_pk_bf16_f32 v7, v9, v34
	s_waitcnt lgkmcnt(0)
	v_add_f32_e32 v2, v2, v3
	v_mov_b32_e32 v3, v2
	s_nop 1
	v_permlane32_swap_b32_e32 v2, v3
	s_waitcnt lgkmcnt(0)
	v_add_f32_e32 v2, v2, v3
	v_sub_f32_e32 v3, v99, v8
	v_exp_f32_e32 v3, v3
	v_cvt_pk_bf16_f32 v8, v35, v36
	v_cvt_pk_bf16_f32 v9, v37, v38
	v_cvt_pk_bf16_f32 v18, v30, v31
	v_cvt_pk_bf16_f32 v19, v32, v33
	v_cvt_pk_bf16_f32 v20, v26, v27
	s_nop 0
	v_add_f32_e32 v55, v3, v2
	v_cvt_pk_bf16_f32 v21, v28, v29
	v_cvt_pk_bf16_f32 v14, v22, v23
	v_div_scale_f32 v22, s[0:1], v55, v55, 1.0
	v_rcp_f32_e32 v23, v22
	v_cvt_pk_bf16_f32 v15, v24, v25
	v_cvt_pk_bf16_f32 v16, v44, v43
	v_cvt_pk_bf16_f32 v17, v45, v46
	v_cvt_pk_bf16_f32 v2, v47, v48
	v_cvt_pk_bf16_f32 v3, v49, v50
	s_nop 0
	v_fma_f32 v24, -v22, v23, 1.0
	v_fmac_f32_e32 v23, v24, v23
	v_div_scale_f32 v24, vcc, 1.0, v55, 1.0
	v_mul_f32_e32 v25, v24, v23
	v_fma_f32 v26, -v22, v25, v24
	v_fmac_f32_e32 v25, v26, v23
	v_fma_f32 v22, -v22, v25, v24
	v_cvt_pk_bf16_f32 v4, v10, v11
	v_cvt_pk_bf16_f32 v5, v12, v13
	v_cvt_pk_bf16_f32 v10, v39, v40
	v_cvt_pk_bf16_f32 v11, v41, v42
	v_cvt_pk_bf16_f32 v12, v51, v52
	v_cvt_pk_bf16_f32 v13, v53, v54
	v_div_fmas_f32 v22, v22, v23, v25
	ds_read_b128 v[24:27], v0 offset:39392
	ds_read_b128 v[28:31], v0 offset:39456
	s_waitcnt lgkmcnt(1)
	v_mfma_f32_16x16x32_bf16 v[24:27], v[24:27], v[6:9], 0
	v_div_fixup_f32 v32, v22, v55, 1.0
	v_mad_i64_i32 v[22:23], s[0:1], v98, s33, v[100:101]
	s_waitcnt lgkmcnt(0)
	v_mfma_f32_16x16x32_bf16 v[24:27], v[28:31], v[18:21], v[24:27]
	ds_read_b128 v[28:31], v0 offset:39520
	s_waitcnt lgkmcnt(0)
	v_mfma_f32_16x16x32_bf16 v[24:27], v[28:31], v[14:17], v[24:27]
	ds_read_b128 v[28:31], v0 offset:39584
	s_waitcnt lgkmcnt(0)
	v_mfma_f32_16x16x32_bf16 v[24:27], v[28:31], v[2:5], v[24:27]
	ds_read_b128 v[28:31], v0 offset:39648
	s_waitcnt lgkmcnt(0)
	v_mfma_f32_16x16x32_bf16 v[24:27], v[28:31], v[10:13], v[24:27]
	s_nop 7
	v_mul_f32_e32 v24, v24, v32
	v_mul_f32_e32 v25, v25, v32
	v_cvt_pk_bf16_f32 v24, v24, v25
	v_mul_f32_e32 v25, v26, v32
	v_mul_f32_e32 v26, v27, v32
	v_cvt_pk_bf16_f32 v25, v25, v26
	global_store_dwordx2 v[22:23], v[24:25], off
	ds_read_b128 v[24:27], v0 offset:48352
	ds_read_b128 v[28:31], v0 offset:48416
	s_waitcnt lgkmcnt(1)
	v_mfma_f32_16x16x32_bf16 v[24:27], v[24:27], v[6:9], 0
	s_waitcnt lgkmcnt(0)
	v_mfma_f32_16x16x32_bf16 v[24:27], v[28:31], v[18:21], v[24:27]
	ds_read_b128 v[28:31], v0 offset:48480
	s_waitcnt lgkmcnt(0)
	v_mfma_f32_16x16x32_bf16 v[24:27], v[28:31], v[14:17], v[24:27]
	ds_read_b128 v[28:31], v0 offset:48544
	s_waitcnt lgkmcnt(0)
	v_mfma_f32_16x16x32_bf16 v[24:27], v[28:31], v[2:5], v[24:27]
	ds_read_b128 v[28:31], v0 offset:48608
	s_waitcnt lgkmcnt(0)
	v_mfma_f32_16x16x32_bf16 v[24:27], v[28:31], v[10:13], v[24:27]
	s_nop 7
	v_mul_f32_e32 v24, v24, v32
	v_mul_f32_e32 v25, v25, v32
	v_cvt_pk_bf16_f32 v24, v24, v25
	v_mul_f32_e32 v25, v26, v32
	v_mul_f32_e32 v26, v27, v32
	v_cvt_pk_bf16_f32 v25, v25, v26
	global_store_dwordx2 v[22:23], v[24:25], off offset:32
	ds_read_b128 v[24:27], v0 offset:57312
	ds_read_b128 v[28:31], v0 offset:57376
	s_waitcnt lgkmcnt(1)
	v_mfma_f32_16x16x32_bf16 v[24:27], v[24:27], v[6:9], 0
	s_waitcnt lgkmcnt(0)
	v_mfma_f32_16x16x32_bf16 v[24:27], v[28:31], v[18:21], v[24:27]
	ds_read_b128 v[28:31], v0 offset:57440
	s_waitcnt lgkmcnt(0)
	v_mfma_f32_16x16x32_bf16 v[24:27], v[28:31], v[14:17], v[24:27]
	ds_read_b128 v[28:31], v0 offset:57504
	s_waitcnt lgkmcnt(0)
	v_mfma_f32_16x16x32_bf16 v[24:27], v[28:31], v[2:5], v[24:27]
	ds_read_b128 v[28:31], v0 offset:57568
	s_waitcnt lgkmcnt(0)
	v_mfma_f32_16x16x32_bf16 v[24:27], v[28:31], v[10:13], v[24:27]
	s_nop 7
	v_mul_f32_e32 v24, v32, v24
	v_mul_f32_e32 v25, v32, v25
	v_cvt_pk_bf16_f32 v24, v24, v25
	v_mul_f32_e32 v25, v32, v26
	v_mul_f32_e32 v26, v32, v27
	v_cvt_pk_bf16_f32 v25, v25, v26
	global_store_dwordx2 v[22:23], v[24:25], off offset:64
	ds_read_b128 v[24:27], v133 offset:39392
	s_waitcnt lgkmcnt(0)
	v_mfma_f32_16x16x32_bf16 v[6:9], v[24:27], v[6:9], 0
	ds_read_b128 v[24:27], v133 offset:39456
	s_waitcnt lgkmcnt(0)
	v_mfma_f32_16x16x32_bf16 v[6:9], v[24:27], v[18:21], v[6:9]
	ds_read_b128 v[18:21], v133 offset:39520
	s_waitcnt lgkmcnt(0)
	v_mfma_f32_16x16x32_bf16 v[6:9], v[18:21], v[14:17], v[6:9]
	ds_read_b128 v[14:17], v133 offset:39584
	s_waitcnt lgkmcnt(0)
	v_mfma_f32_16x16x32_bf16 v[2:5], v[14:17], v[2:5], v[6:9]
	s_nop 4
	ds_read_b128 v[6:9], v133 offset:39648
	s_waitcnt lgkmcnt(0)
	v_mfma_f32_16x16x32_bf16 v[2:5], v[6:9], v[10:13], v[2:5]
	s_nop 7
	v_mul_f32_e32 v2, v32, v2
	v_mul_f32_e32 v3, v32, v3
	v_cvt_pk_bf16_f32 v2, v2, v3
	v_mul_f32_e32 v3, v32, v4
	v_mul_f32_e32 v4, v32, v5
	v_cvt_pk_bf16_f32 v3, v3, v4
	global_store_dwordx2 v[22:23], v[2:3], off offset:96
	s_branch .LBB0_53

.LBB0_315:
	s_and_b64 vcc, exec, s[12:13]
	s_cbranch_vccz .LBB0_336
	s_mov_b64 s[12:13], -1
	s_cmp_eq_u32 s84, 1
	v_lshl_or_b32 v132, s2, 8, v150
	s_cbranch_scc1 .LBB0_334
	v_ashrrev_i32_e32 v133, 31, v132
	v_lshl_add_u64 v[134:135], v[132:133], 1, s[14:15]
	v_mad_i64_i32 v[158:159], s[12:13], v2, s33, v[134:135]
	v_cvt_pk_bf16_f32 v136, v4, v5
	v_cvt_pk_bf16_f32 v137, v6, v7
	v_cvt_pk_bf16_f32 v138, v8, v9
	v_cvt_pk_bf16_f32 v139, v10, v11
	global_store_dwordx4 v[158:159], v[136:139], off
	v_and_b32_e32 v133, 0xffff0000, v136
	v_lshlrev_b32_e32 v0, 16, v136
	v_lshlrev_b32_e32 v136, 16, v137
	v_and_b32_e32 v137, 0xffff0000, v137
	v_mul_f32_e32 v133, v133, v133
	v_fmac_f32_e32 v133, v0, v0
	v_mul_f32_e32 v0, v137, v137
	v_lshlrev_b32_e32 v160, 16, v138
	v_and_b32_e32 v138, 0xffff0000, v138
	v_fmac_f32_e32 v0, v136, v136
	v_add_f32_e32 v0, v133, v0
	v_mul_f32_e32 v133, v138, v138
	v_lshlrev_b32_e32 v161, 16, v139
	v_and_b32_e32 v139, 0xffff0000, v139
	v_fmac_f32_e32 v133, v160, v160
	v_add_f32_e32 v0, v0, v133
	v_mul_f32_e32 v133, v139, v139
	v_fmac_f32_e32 v133, v161, v161
	v_cvt_pk_bf16_f32 v136, v12, v13
	v_add_f32_e32 v0, v0, v133
	v_cvt_pk_bf16_f32 v137, v14, v15
	v_cvt_pk_bf16_f32 v138, v16, v17
	v_cvt_pk_bf16_f32 v139, v18, v19
	global_store_dwordx4 v[158:159], v[136:139], off offset:256
	v_lshlrev_b32_e32 v133, 16, v136
	v_lshlrev_b32_e32 v158, 16, v137
	v_and_b32_e32 v136, 0xffff0000, v136
	v_and_b32_e32 v137, 0xffff0000, v137
	v_mul_f32_e32 v136, v136, v136
	v_fmac_f32_e32 v136, v133, v133
	v_mul_f32_e32 v133, v137, v137
	v_lshlrev_b32_e32 v159, 16, v138
	v_and_b32_e32 v138, 0xffff0000, v138
	v_fmac_f32_e32 v133, v158, v158
	v_add_f32_e32 v133, v136, v133
	v_mul_f32_e32 v136, v138, v138
	v_lshlrev_b32_e32 v160, 16, v139
	v_and_b32_e32 v139, 0xffff0000, v139
	v_fmac_f32_e32 v136, v159, v159
	v_add_f32_e32 v133, v133, v136
	v_mul_f32_e32 v136, v139, v139
	v_fmac_f32_e32 v136, v160, v160
	v_add_f32_e32 v133, v133, v136
	v_and_b32_e32 v136, 64, v174
	v_add_f32_e32 v133, v0, v133
	v_xor_b32_e32 v0, 16, v174
	v_add_u32_e32 v136, 64, v136
	v_cmp_lt_i32_e32 vcc, v0, v136
	v_ashrrev_i32_e32 v3, 31, v2
	s_nop 0
	v_cndmask_b32_e32 v0, v174, v0, vcc
	v_lshlrev_b32_e32 v0, 2, v0
	v_mov_b32_e32 v137, v133
	s_nop 1
	v_permlane16_swap_b32_e32 v133, v137
	s_waitcnt lgkmcnt(0)
	v_add_f32_e32 v138, v133, v137
	v_xor_b32_e32 v133, 32, v174
	v_cmp_lt_i32_e32 vcc, v133, v136
	v_lshl_add_u64 v[136:137], v[2:3], 3, s[26:27]
	s_nop 0
	v_cndmask_b32_e32 v133, v174, v133, vcc
	v_lshlrev_b32_e32 v133, 2, v133
	v_mov_b32_e32 v139, v138
	s_nop 1
	v_permlane32_swap_b32_e32 v138, v139
	s_and_saveexec_b64 s[12:13], s[6:7]
	s_cbranch_execz .LBB0_319
	s_waitcnt lgkmcnt(0)
	v_add_f32_e32 v3, v138, v139
	v_mul_f32_e32 v3, 0x4f800000, v3
	v_trunc_f32_e32 v3, v3
	v_mul_f32_e32 v138, 0x2f800000, v3
	v_floor_f32_e32 v139, v138
	v_fmac_f32_e32 v3, 0xcf800000, v139
	v_cvt_u32_f32_e32 v138, v3
	v_cvt_u32_f32_e32 v139, v139
	global_atomic_add_x2 v[136:137], v[138:139], off
.LBB0_319:
	s_or_b64 exec, exec, s[12:13]
	v_or_b32_e32 v3, 16, v2
	s_waitcnt lgkmcnt(0)
	v_mad_i64_i32 v[138:139], s[12:13], v3, s33, v[134:135]
	v_cvt_pk_bf16_f32 v158, v20, v21
	v_cvt_pk_bf16_f32 v159, v22, v23
	v_cvt_pk_bf16_f32 v160, v24, v25
	v_cvt_pk_bf16_f32 v161, v26, v27
	global_store_dwordx4 v[138:139], v[158:161], off
	v_lshlrev_b32_e32 v3, 16, v158
	v_lshlrev_b32_e32 v162, 16, v159
	v_and_b32_e32 v158, 0xffff0000, v158
	v_and_b32_e32 v159, 0xffff0000, v159
	v_mul_f32_e32 v158, v158, v158
	v_fmac_f32_e32 v158, v3, v3
	v_mul_f32_e32 v3, v159, v159
	v_lshlrev_b32_e32 v163, 16, v160
	v_and_b32_e32 v160, 0xffff0000, v160
	v_fmac_f32_e32 v3, v162, v162
	v_add_f32_e32 v3, v158, v3
	v_mul_f32_e32 v158, v160, v160
	v_lshlrev_b32_e32 v164, 16, v161
	v_and_b32_e32 v161, 0xffff0000, v161
	v_fmac_f32_e32 v158, v163, v163
	v_add_f32_e32 v3, v3, v158
	v_mul_f32_e32 v158, v161, v161
	v_fmac_f32_e32 v158, v164, v164
	v_add_f32_e32 v3, v3, v158
	v_cvt_pk_bf16_f32 v158, v28, v29
	v_cvt_pk_bf16_f32 v159, v30, v31
	v_cvt_pk_bf16_f32 v160, v32, v33
	v_cvt_pk_bf16_f32 v161, v34, v35
	global_store_dwordx4 v[138:139], v[158:161], off offset:256
	v_and_b32_e32 v139, 0xffff0000, v158
	v_lshlrev_b32_e32 v138, 16, v158
	v_lshlrev_b32_e32 v158, 16, v159
	v_and_b32_e32 v159, 0xffff0000, v159
	v_mul_f32_e32 v139, v139, v139
	v_fmac_f32_e32 v139, v138, v138
	v_mul_f32_e32 v138, v159, v159
	v_lshlrev_b32_e32 v162, 16, v160
	v_and_b32_e32 v160, 0xffff0000, v160
	v_fmac_f32_e32 v138, v158, v158
	v_add_f32_e32 v138, v139, v138
	v_mul_f32_e32 v139, v160, v160
	v_lshlrev_b32_e32 v163, 16, v161
	v_and_b32_e32 v161, 0xffff0000, v161
	v_fmac_f32_e32 v139, v162, v162
	v_add_f32_e32 v138, v138, v139
	v_mul_f32_e32 v139, v161, v161
	v_fmac_f32_e32 v139, v163, v163
	v_add_f32_e32 v138, v138, v139
	v_add_f32_e32 v3, v3, v138
	v_mov_b32_e32 v138, v3
	s_nop 1
	v_permlane16_swap_b32_e32 v3, v138
	s_waitcnt lgkmcnt(0)
	v_add_f32_e32 v3, v3, v138
	v_mov_b32_e32 v138, v3
	s_nop 1
	v_permlane32_swap_b32_e32 v3, v138
	s_and_saveexec_b64 s[12:13], s[6:7]
	s_cbranch_execz .LBB0_321
	s_waitcnt lgkmcnt(0)
	v_add_f32_e32 v3, v3, v138
	v_mul_f32_e32 v3, 0x4f800000, v3
	v_trunc_f32_e32 v3, v3
	v_mul_f32_e32 v138, 0x2f800000, v3
	v_floor_f32_e32 v139, v138
	v_fmac_f32_e32 v3, 0xcf800000, v139
	v_cvt_u32_f32_e32 v138, v3
	v_cvt_u32_f32_e32 v139, v139
	global_atomic_add_x2 v[136:137], v[138:139], off offset:128
.LBB0_321:
	s_or_b64 exec, exec, s[12:13]
	v_or_b32_e32 v3, 32, v2
	s_waitcnt lgkmcnt(0)
	v_mad_i64_i32 v[138:139], s[12:13], v3, s33, v[134:135]
	v_cvt_pk_bf16_f32 v158, v36, v37
	v_cvt_pk_bf16_f32 v159, v38, v39
	v_cvt_pk_bf16_f32 v160, v40, v41
	v_cvt_pk_bf16_f32 v161, v42, v43
	global_store_dwordx4 v[138:139], v[158:161], off
	v_lshlrev_b32_e32 v3, 16, v158
	v_lshlrev_b32_e32 v162, 16, v159
	v_and_b32_e32 v158, 0xffff0000, v158
	v_and_b32_e32 v159, 0xffff0000, v159
	v_mul_f32_e32 v158, v158, v158
	v_fmac_f32_e32 v158, v3, v3
	v_mul_f32_e32 v3, v159, v159
	v_lshlrev_b32_e32 v163, 16, v160
	v_and_b32_e32 v160, 0xffff0000, v160
	v_fmac_f32_e32 v3, v162, v162
	v_add_f32_e32 v3, v158, v3
	v_mul_f32_e32 v158, v160, v160
	v_lshlrev_b32_e32 v164, 16, v161
	v_and_b32_e32 v161, 0xffff0000, v161
	v_fmac_f32_e32 v158, v163, v163
	v_add_f32_e32 v3, v3, v158
	v_mul_f32_e32 v158, v161, v161
	v_fmac_f32_e32 v158, v164, v164
	v_add_f32_e32 v3, v3, v158
	v_cvt_pk_bf16_f32 v158, v44, v45
	v_cvt_pk_bf16_f32 v159, v46, v47
	v_cvt_pk_bf16_f32 v160, v48, v49
	v_cvt_pk_bf16_f32 v161, v50, v51
	global_store_dwordx4 v[138:139], v[158:161], off offset:256
	v_and_b32_e32 v139, 0xffff0000, v158
	v_lshlrev_b32_e32 v138, 16, v158
	v_lshlrev_b32_e32 v158, 16, v159
	v_and_b32_e32 v159, 0xffff0000, v159
	v_mul_f32_e32 v139, v139, v139
	v_fmac_f32_e32 v139, v138, v138
	v_mul_f32_e32 v138, v159, v159
	v_lshlrev_b32_e32 v162, 16, v160
	v_and_b32_e32 v160, 0xffff0000, v160
	v_fmac_f32_e32 v138, v158, v158
	v_add_f32_e32 v138, v139, v138
	v_mul_f32_e32 v139, v160, v160
	v_lshlrev_b32_e32 v163, 16, v161
	v_and_b32_e32 v161, 0xffff0000, v161
	v_fmac_f32_e32 v139, v162, v162
	v_add_f32_e32 v138, v138, v139
	v_mul_f32_e32 v139, v161, v161
	v_fmac_f32_e32 v139, v163, v163
	v_add_f32_e32 v138, v138, v139
	v_add_f32_e32 v3, v3, v138
	v_mov_b32_e32 v138, v3
	s_nop 1
	v_permlane16_swap_b32_e32 v3, v138
	s_waitcnt lgkmcnt(0)
	v_add_f32_e32 v3, v3, v138
	v_mov_b32_e32 v138, v3
	s_nop 1
	v_permlane32_swap_b32_e32 v3, v138
	s_and_saveexec_b64 s[12:13], s[6:7]
	s_cbranch_execz .LBB0_323
	s_waitcnt lgkmcnt(0)
	v_add_f32_e32 v3, v3, v138
	v_mul_f32_e32 v3, 0x4f800000, v3
	v_trunc_f32_e32 v3, v3
	v_mul_f32_e32 v138, 0x2f800000, v3
	v_floor_f32_e32 v139, v138
	v_fmac_f32_e32 v3, 0xcf800000, v139
	v_cvt_u32_f32_e32 v138, v3
	v_cvt_u32_f32_e32 v139, v139
	global_atomic_add_x2 v[136:137], v[138:139], off offset:256
.LBB0_323:
	s_or_b64 exec, exec, s[12:13]
	v_or_b32_e32 v3, 48, v2
	s_waitcnt lgkmcnt(0)
	v_mad_i64_i32 v[138:139], s[12:13], v3, s33, v[134:135]
	v_cvt_pk_bf16_f32 v158, v52, v53
	v_cvt_pk_bf16_f32 v159, v54, v55
	v_cvt_pk_bf16_f32 v160, v56, v57
	v_cvt_pk_bf16_f32 v161, v58, v59
	global_store_dwordx4 v[138:139], v[158:161], off
	v_lshlrev_b32_e32 v3, 16, v158
	v_lshlrev_b32_e32 v162, 16, v159
	v_and_b32_e32 v158, 0xffff0000, v158
	v_and_b32_e32 v159, 0xffff0000, v159
	v_mul_f32_e32 v158, v158, v158
	v_fmac_f32_e32 v158, v3, v3
	v_mul_f32_e32 v3, v159, v159
	v_lshlrev_b32_e32 v163, 16, v160
	v_and_b32_e32 v160, 0xffff0000, v160
	v_fmac_f32_e32 v3, v162, v162
	v_add_f32_e32 v3, v158, v3
	v_mul_f32_e32 v158, v160, v160
	v_lshlrev_b32_e32 v164, 16, v161
	v_and_b32_e32 v161, 0xffff0000, v161
	v_fmac_f32_e32 v158, v163, v163
	v_add_f32_e32 v3, v3, v158
	v_mul_f32_e32 v158, v161, v161
	v_fmac_f32_e32 v158, v164, v164
	v_add_f32_e32 v3, v3, v158
	v_cvt_pk_bf16_f32 v158, v60, v61
	v_cvt_pk_bf16_f32 v159, v62, v63
	v_cvt_pk_bf16_f32 v160, v64, v65
	v_cvt_pk_bf16_f32 v161, v66, v67
	global_store_dwordx4 v[138:139], v[158:161], off offset:256
	v_and_b32_e32 v139, 0xffff0000, v158
	v_lshlrev_b32_e32 v138, 16, v158
	v_lshlrev_b32_e32 v158, 16, v159
	v_and_b32_e32 v159, 0xffff0000, v159
	v_mul_f32_e32 v139, v139, v139
	v_fmac_f32_e32 v139, v138, v138
	v_mul_f32_e32 v138, v159, v159
	v_lshlrev_b32_e32 v162, 16, v160
	v_and_b32_e32 v160, 0xffff0000, v160
	v_fmac_f32_e32 v138, v158, v158
	v_add_f32_e32 v138, v139, v138
	v_mul_f32_e32 v139, v160, v160
	v_lshlrev_b32_e32 v163, 16, v161
	v_and_b32_e32 v161, 0xffff0000, v161
	v_fmac_f32_e32 v139, v162, v162
	v_add_f32_e32 v138, v138, v139
	v_mul_f32_e32 v139, v161, v161
	v_fmac_f32_e32 v139, v163, v163
	v_add_f32_e32 v138, v138, v139
	v_add_f32_e32 v3, v3, v138
	v_mov_b32_e32 v138, v3
	s_nop 1
	v_permlane16_swap_b32_e32 v3, v138
	s_waitcnt lgkmcnt(0)
	v_add_f32_e32 v3, v3, v138
	v_mov_b32_e32 v138, v3
	s_nop 1
	v_permlane32_swap_b32_e32 v3, v138
	s_and_saveexec_b64 s[12:13], s[6:7]
	s_cbranch_execz .LBB0_325
	s_waitcnt lgkmcnt(0)
	v_add_f32_e32 v3, v3, v138
	v_mul_f32_e32 v3, 0x4f800000, v3
	v_trunc_f32_e32 v3, v3
	v_mul_f32_e32 v138, 0x2f800000, v3
	v_floor_f32_e32 v139, v138
	v_fmac_f32_e32 v3, 0xcf800000, v139
	v_cvt_u32_f32_e32 v138, v3
	v_cvt_u32_f32_e32 v139, v139
	global_atomic_add_x2 v[136:137], v[138:139], off offset:384
.LBB0_325:
	s_or_b64 exec, exec, s[12:13]
	v_add_u32_e32 v3, 0x80, v2
	s_waitcnt lgkmcnt(0)
	v_mad_i64_i32 v[138:139], s[12:13], v3, s33, v[134:135]
	v_cvt_pk_bf16_f32 v158, v68, v69
	v_cvt_pk_bf16_f32 v159, v70, v71
	v_cvt_pk_bf16_f32 v160, v72, v73
	v_cvt_pk_bf16_f32 v161, v74, v75
	global_store_dwordx4 v[138:139], v[158:161], off
	v_lshlrev_b32_e32 v3, 16, v158
	v_lshlrev_b32_e32 v162, 16, v159
	v_and_b32_e32 v158, 0xffff0000, v158
	v_and_b32_e32 v159, 0xffff0000, v159
	v_mul_f32_e32 v158, v158, v158
	v_fmac_f32_e32 v158, v3, v3
	v_mul_f32_e32 v3, v159, v159
	v_lshlrev_b32_e32 v163, 16, v160
	v_and_b32_e32 v160, 0xffff0000, v160
	v_fmac_f32_e32 v3, v162, v162
	v_add_f32_e32 v3, v158, v3
	v_mul_f32_e32 v158, v160, v160
	v_lshlrev_b32_e32 v164, 16, v161
	v_and_b32_e32 v161, 0xffff0000, v161
	v_fmac_f32_e32 v158, v163, v163
	v_add_f32_e32 v3, v3, v158
	v_mul_f32_e32 v158, v161, v161
	v_fmac_f32_e32 v158, v164, v164
	v_add_f32_e32 v3, v3, v158
	v_cvt_pk_bf16_f32 v158, v76, v77
	v_cvt_pk_bf16_f32 v159, v78, v79
	v_cvt_pk_bf16_f32 v160, v80, v81
	v_cvt_pk_bf16_f32 v161, v82, v83
	global_store_dwordx4 v[138:139], v[158:161], off offset:256
	v_and_b32_e32 v139, 0xffff0000, v158
	v_lshlrev_b32_e32 v138, 16, v158
	v_lshlrev_b32_e32 v158, 16, v159
	v_and_b32_e32 v159, 0xffff0000, v159
	v_mul_f32_e32 v139, v139, v139
	v_fmac_f32_e32 v139, v138, v138
	v_mul_f32_e32 v138, v159, v159
	v_lshlrev_b32_e32 v162, 16, v160
	v_and_b32_e32 v160, 0xffff0000, v160
	v_fmac_f32_e32 v138, v158, v158
	v_add_f32_e32 v138, v139, v138
	v_mul_f32_e32 v139, v160, v160
	v_lshlrev_b32_e32 v163, 16, v161
	v_and_b32_e32 v161, 0xffff0000, v161
	v_fmac_f32_e32 v139, v162, v162
	v_add_f32_e32 v138, v138, v139
	v_mul_f32_e32 v139, v161, v161
	v_fmac_f32_e32 v139, v163, v163
	v_add_f32_e32 v138, v138, v139
	v_add_f32_e32 v3, v3, v138
	v_mov_b32_e32 v138, v3
	s_nop 1
	v_permlane16_swap_b32_e32 v3, v138
	s_waitcnt lgkmcnt(0)
	v_add_f32_e32 v3, v3, v138
	v_mov_b32_e32 v138, v3
	s_nop 1
	v_permlane32_swap_b32_e32 v3, v138
	s_and_saveexec_b64 s[12:13], s[6:7]
	s_cbranch_execz .LBB0_327
	s_waitcnt lgkmcnt(0)
	v_add_f32_e32 v3, v3, v138
	v_mul_f32_e32 v3, 0x4f800000, v3
	v_trunc_f32_e32 v3, v3
	v_mul_f32_e32 v138, 0x2f800000, v3
	v_floor_f32_e32 v139, v138
	v_fmac_f32_e32 v3, 0xcf800000, v139
	v_cvt_u32_f32_e32 v138, v3
	v_cvt_u32_f32_e32 v139, v139
	global_atomic_add_x2 v[136:137], v[138:139], off offset:1024
.LBB0_327:
	s_or_b64 exec, exec, s[12:13]
	v_add_u32_e32 v3, 0x90, v2
	s_waitcnt lgkmcnt(0)
	v_mad_i64_i32 v[138:139], s[12:13], v3, s33, v[134:135]
	v_cvt_pk_bf16_f32 v158, v84, v85
	v_cvt_pk_bf16_f32 v159, v86, v87
	v_cvt_pk_bf16_f32 v160, v88, v89
	v_cvt_pk_bf16_f32 v161, v90, v91
	global_store_dwordx4 v[138:139], v[158:161], off
	v_lshlrev_b32_e32 v3, 16, v158
	v_lshlrev_b32_e32 v162, 16, v159
	v_and_b32_e32 v158, 0xffff0000, v158
	v_and_b32_e32 v159, 0xffff0000, v159
	v_mul_f32_e32 v158, v158, v158
	v_fmac_f32_e32 v158, v3, v3
	v_mul_f32_e32 v3, v159, v159
	v_lshlrev_b32_e32 v163, 16, v160
	v_and_b32_e32 v160, 0xffff0000, v160
	v_fmac_f32_e32 v3, v162, v162
	v_add_f32_e32 v3, v158, v3
	v_mul_f32_e32 v158, v160, v160
	v_lshlrev_b32_e32 v164, 16, v161
	v_and_b32_e32 v161, 0xffff0000, v161
	v_fmac_f32_e32 v158, v163, v163
	v_add_f32_e32 v3, v3, v158
	v_mul_f32_e32 v158, v161, v161
	v_fmac_f32_e32 v158, v164, v164
	v_add_f32_e32 v3, v3, v158
	v_cvt_pk_bf16_f32 v158, v92, v93
	v_cvt_pk_bf16_f32 v159, v94, v95
	v_cvt_pk_bf16_f32 v160, v96, v97
	v_cvt_pk_bf16_f32 v161, v98, v99
	global_store_dwordx4 v[138:139], v[158:161], off offset:256
	v_and_b32_e32 v139, 0xffff0000, v158
	v_lshlrev_b32_e32 v138, 16, v158
	v_lshlrev_b32_e32 v158, 16, v159
	v_and_b32_e32 v159, 0xffff0000, v159
	v_mul_f32_e32 v139, v139, v139
	v_fmac_f32_e32 v139, v138, v138
	v_mul_f32_e32 v138, v159, v159
	v_lshlrev_b32_e32 v162, 16, v160
	v_and_b32_e32 v160, 0xffff0000, v160
	v_fmac_f32_e32 v138, v158, v158
	v_add_f32_e32 v138, v139, v138
	v_mul_f32_e32 v139, v160, v160
	v_lshlrev_b32_e32 v163, 16, v161
	v_and_b32_e32 v161, 0xffff0000, v161
	v_fmac_f32_e32 v139, v162, v162
	v_add_f32_e32 v138, v138, v139
	v_mul_f32_e32 v139, v161, v161
	v_fmac_f32_e32 v139, v163, v163
	v_add_f32_e32 v138, v138, v139
	v_add_f32_e32 v3, v3, v138
	v_mov_b32_e32 v138, v3
	s_nop 1
	v_permlane16_swap_b32_e32 v3, v138
	s_waitcnt lgkmcnt(0)
	v_add_f32_e32 v3, v3, v138
	v_mov_b32_e32 v138, v3
	s_nop 1
	v_permlane32_swap_b32_e32 v3, v138
	s_and_saveexec_b64 s[12:13], s[6:7]
	s_cbranch_execz .LBB0_329
	s_waitcnt lgkmcnt(0)
	v_add_f32_e32 v3, v3, v138
	v_mul_f32_e32 v3, 0x4f800000, v3
	v_trunc_f32_e32 v3, v3
	v_mul_f32_e32 v138, 0x2f800000, v3
	v_floor_f32_e32 v139, v138
	v_fmac_f32_e32 v3, 0xcf800000, v139
	v_cvt_u32_f32_e32 v138, v3
	v_cvt_u32_f32_e32 v139, v139
	global_atomic_add_x2 v[136:137], v[138:139], off offset:1152
.LBB0_329:
	s_or_b64 exec, exec, s[12:13]
	v_add_u32_e32 v3, 0xa0, v2
	s_waitcnt lgkmcnt(0)
	v_mad_i64_i32 v[138:139], s[12:13], v3, s33, v[134:135]
	v_cvt_pk_bf16_f32 v158, v100, v101
	v_cvt_pk_bf16_f32 v159, v102, v103
	v_cvt_pk_bf16_f32 v160, v104, v105
	v_cvt_pk_bf16_f32 v161, v106, v107
	global_store_dwordx4 v[138:139], v[158:161], off
	v_lshlrev_b32_e32 v3, 16, v158
	v_lshlrev_b32_e32 v162, 16, v159
	v_and_b32_e32 v158, 0xffff0000, v158
	v_and_b32_e32 v159, 0xffff0000, v159
	v_mul_f32_e32 v158, v158, v158
	v_fmac_f32_e32 v158, v3, v3
	v_mul_f32_e32 v3, v159, v159
	v_lshlrev_b32_e32 v163, 16, v160
	v_and_b32_e32 v160, 0xffff0000, v160
	v_fmac_f32_e32 v3, v162, v162
	v_add_f32_e32 v3, v158, v3
	v_mul_f32_e32 v158, v160, v160
	v_lshlrev_b32_e32 v164, 16, v161
	v_and_b32_e32 v161, 0xffff0000, v161
	v_fmac_f32_e32 v158, v163, v163
	v_add_f32_e32 v3, v3, v158
	v_mul_f32_e32 v158, v161, v161
	v_fmac_f32_e32 v158, v164, v164
	v_add_f32_e32 v3, v3, v158
	v_cvt_pk_bf16_f32 v158, v108, v109
	v_cvt_pk_bf16_f32 v159, v110, v111
	v_cvt_pk_bf16_f32 v160, v112, v113
	v_cvt_pk_bf16_f32 v161, v114, v115
	global_store_dwordx4 v[138:139], v[158:161], off offset:256
	v_and_b32_e32 v139, 0xffff0000, v158
	v_lshlrev_b32_e32 v138, 16, v158
	v_lshlrev_b32_e32 v158, 16, v159
	v_and_b32_e32 v159, 0xffff0000, v159
	v_mul_f32_e32 v139, v139, v139
	v_fmac_f32_e32 v139, v138, v138
	v_mul_f32_e32 v138, v159, v159
	v_lshlrev_b32_e32 v162, 16, v160
	v_and_b32_e32 v160, 0xffff0000, v160
	v_fmac_f32_e32 v138, v158, v158
	v_add_f32_e32 v138, v139, v138
	v_mul_f32_e32 v139, v160, v160
	v_lshlrev_b32_e32 v163, 16, v161
	v_and_b32_e32 v161, 0xffff0000, v161
	v_fmac_f32_e32 v139, v162, v162
	v_add_f32_e32 v138, v138, v139
	v_mul_f32_e32 v139, v161, v161
	v_fmac_f32_e32 v139, v163, v163
	v_add_f32_e32 v138, v138, v139
	v_add_f32_e32 v3, v3, v138
	v_mov_b32_e32 v138, v3
	s_nop 1
	v_permlane16_swap_b32_e32 v3, v138
	s_waitcnt lgkmcnt(0)
	v_add_f32_e32 v3, v3, v138
	v_mov_b32_e32 v138, v3
	s_nop 1
	v_permlane32_swap_b32_e32 v3, v138
	s_and_saveexec_b64 s[12:13], s[6:7]
	s_cbranch_execz .LBB0_331
	s_waitcnt lgkmcnt(0)
	v_add_f32_e32 v3, v3, v138
	v_mul_f32_e32 v3, 0x4f800000, v3
	v_trunc_f32_e32 v3, v3
	v_mul_f32_e32 v138, 0x2f800000, v3
	v_floor_f32_e32 v139, v138
	v_fmac_f32_e32 v3, 0xcf800000, v139
	v_cvt_u32_f32_e32 v138, v3
	v_cvt_u32_f32_e32 v139, v139
	global_atomic_add_x2 v[136:137], v[138:139], off offset:1280
.LBB0_331:
	s_or_b64 exec, exec, s[12:13]
	v_add_u32_e32 v3, 0xb0, v2
	v_mad_i64_i32 v[134:135], s[12:13], v3, s33, v[134:135]
	v_cvt_pk_bf16_f32 v158, v116, v117
	v_cvt_pk_bf16_f32 v159, v118, v119
	v_cvt_pk_bf16_f32 v160, v120, v121
	v_cvt_pk_bf16_f32 v161, v122, v123
	global_store_dwordx4 v[134:135], v[158:161], off
	s_waitcnt lgkmcnt(0)
	v_and_b32_e32 v138, 0xffff0000, v158
	v_lshlrev_b32_e32 v3, 16, v158
	v_and_b32_e32 v158, 0xffff0000, v159
	v_mul_f32_e32 v138, v138, v138
	v_lshlrev_b32_e32 v139, 16, v159
	v_fmac_f32_e32 v138, v3, v3
	v_mul_f32_e32 v3, v158, v158
	v_lshlrev_b32_e32 v159, 16, v160
	v_and_b32_e32 v160, 0xffff0000, v160
	v_fmac_f32_e32 v3, v139, v139
	v_add_f32_e32 v3, v138, v3
	v_mul_f32_e32 v138, v160, v160
	v_lshlrev_b32_e32 v162, 16, v161
	v_and_b32_e32 v161, 0xffff0000, v161
	v_fmac_f32_e32 v138, v159, v159
	v_add_f32_e32 v3, v3, v138
	v_mul_f32_e32 v138, v161, v161
	v_cvt_pk_bf16_f32 v158, v124, v125
	v_cvt_pk_bf16_f32 v159, v126, v127
	v_cvt_pk_bf16_f32 v160, v128, v129
	v_cvt_pk_bf16_f32 v161, v130, v131
	global_store_dwordx4 v[134:135], v[158:161], off offset:256
	v_and_b32_e32 v135, 0xffff0000, v158
	v_fmac_f32_e32 v138, v162, v162
	v_lshlrev_b32_e32 v134, 16, v158
	v_and_b32_e32 v139, 0xffff0000, v159
	v_mul_f32_e32 v135, v135, v135
	v_add_f32_e32 v3, v3, v138
	v_lshlrev_b32_e32 v138, 16, v159
	v_fmac_f32_e32 v135, v134, v134
	v_mul_f32_e32 v134, v139, v139
	v_and_b32_e32 v159, 0xffff0000, v160
	v_fmac_f32_e32 v134, v138, v138
	v_lshlrev_b32_e32 v158, 16, v160
	v_add_f32_e32 v134, v135, v134
	v_mul_f32_e32 v135, v159, v159
	v_lshlrev_b32_e32 v160, 16, v161
	v_and_b32_e32 v161, 0xffff0000, v161
	v_fmac_f32_e32 v135, v158, v158
	v_add_f32_e32 v134, v134, v135
	v_mul_f32_e32 v135, v161, v161
	v_fmac_f32_e32 v135, v160, v160
	v_add_f32_e32 v134, v134, v135
	v_add_f32_e32 v3, v3, v134
	v_mov_b32_e32 v0, v3
	s_nop 1
	v_permlane16_swap_b32_e32 v3, v0
	s_waitcnt lgkmcnt(0)
	v_add_f32_e32 v0, v3, v0
	v_mov_b32_e32 v3, v0
	s_nop 1
	v_permlane32_swap_b32_e32 v0, v3
	s_and_saveexec_b64 s[12:13], s[6:7]
	s_cbranch_execz .LBB0_333
	s_waitcnt lgkmcnt(0)
	v_add_f32_e32 v0, v0, v3
	v_mul_f32_e32 v0, 0x4f800000, v0
	v_trunc_f32_e32 v0, v0
	v_mul_f32_e32 v3, 0x2f800000, v0
	v_floor_f32_e32 v3, v3
	v_fmac_f32_e32 v0, 0xcf800000, v3
	v_cvt_u32_f32_e32 v134, v0
	v_cvt_u32_f32_e32 v135, v3
	global_atomic_add_x2 v[136:137], v[134:135], off offset:1408
